# GEMM K-loops: the per-segment s_setprio 1/0 toggles removed (192 instructions)
# speedup vs baseline: 1.0140x; 1.0005x over previous
; #define PG8_STAGE(bufoff, gbase, voff) do { _Pragma("unroll") for (int _i = 0; _i < 2; ++_i) \
;         __builtin_amdgcn_global_load_lds((const unsigned*)((const char*)(gbase) + (voff)[_i]), (PG8_LAS unsigned*)(lds + (bufoff) + ldsw + _i * 8192), 16, 0, 0); } while (0)
; #define PG8_LDA(dst, b, h) do { _Pragma("unroll") for (int m = 0; m < 4; ++m) _Pragma("unroll") for (int k = 0; k < 2; ++k) dst[m][k] = *(const PG8_LAS bf16x8*)(lds + PG8_SA(b, h) + aoff + m * 2048 + k * 1024); } while (0)
; #define PG8_LDB(dst, b, h) do { _Pragma("unroll") for (int n = 0; n < 2; ++n) _Pragma("unroll") for (int k = 0; k < 2; ++k) dst[n][k] = *(const PG8_LAS bf16x8*)(lds + PG8_SB(b, h) + boff + n * 2048 + k * 1024); } while (0)
; #define PG8_MMA(ai, bj, At, Bt) do { __builtin_amdgcn_s_setprio(1); _Pragma("unroll") for (int m = 0; m < 4; ++m) _Pragma("unroll") for (int n = 0; n < 2; ++n) _Pragma("unroll") for (int k = 0; k < 2; ++k) \
;         acc[ai][bj][m][n] = __builtin_amdgcn_mfma_f32_16x16x32_bf16(Bt[n][k], At[m][k], acc[ai][bj][m][n], 0, 0, 0); __builtin_amdgcn_s_setprio(0); } while (0)
; #define PG8_WAIT_V(n) asm volatile("s_waitcnt vmcnt(" #n ")" ::: "memory")
; #define PG8_WAIT_L(n) asm volatile("s_waitcnt lgkmcnt(" #n ")" ::: "memory")
; template <class Epi, class Sched, bool ALIGN_EPI = false, bool SP2 = false>
; __device__ __forceinline__ void gemm_phase(PG8_LAS unsigned char* lds, const Gemm g, const Sched& S, const Epi& E, const int tid) {
;     ...
;             const bool last = (t == nt - 2);
;             const char* a1 = cA + (size_t)(t + 1) * kstep;
;             const char* a2 = last ? nA : cA + (size_t)(t + 2) * kstep; const char* b2 = last ? nB : cB + (size_t)(t + 2) * kstep;
;             const char* a3 = a2 + kstep; const char* b3 = b2 + kstep;
;             if (last && has_next) S.a_ready(nxt);
;             if constexpr (SP2) {
;             PG8_LDB(B0, 0, 0); PG8_LDB(B1, 0, 1); PG8_SCHED; PG8_LDA(At, 0, 0); PG8_STAGE(PG8_SA(1, 1), a1 + hstepA, voffA);
;             PG8_WAIT_V(8); PG8_WAIT_L(0); PG8_BAR; PG8_MMA(0, 0, At, B0); PG8_MMA(0, 1, At, B1); PG8_BAR; PG8_SCHED;
;             PG8_LDA(At, 0, 1); PG8_STAGE(PG8_SB(0, 0), b2, voffB); PG8_STAGE(PG8_SB(0, 1), b2 + hstep, voffB); PG8_STAGE(PG8_SA(0, 0), a2, voffA);
;             PG8_WAIT_V(8); PG8_WAIT_L(0); PG8_BAR; PG8_MMA(1, 0, At, B0); PG8_MMA(1, 1, At, B1); PG8_BAR; PG8_SCHED;
.LBB0_279:
	ds_read_b128 v[144:147], v154
	ds_read_b128 v[148:151], v154 offset:1024
	ds_read_b128 v[160:163], v154 offset:2048
	ds_read_b128 v[164:167], v154 offset:3072
	ds_read_b128 v[168:171], v155
	ds_read_b128 v[172:175], v155 offset:1024
	ds_read_b128 v[176:179], v155 offset:2048
	ds_read_b128 v[180:183], v155 offset:3072
	s_add_u32 s26, s24, 0xfffc0080
	s_addc_u32 s27, s25, -1
	s_cmp_eq_u32 s58, 12
	s_cselect_b32 s29, s17, s27
	s_cselect_b32 s28, s54, s26
	s_cselect_b32 s27, s15, s57
	s_cselect_b32 s26, s55, s56
	v_lshl_add_u64 v[196:197], s[24:25], 0, v[136:137]
	s_add_i32 m0, s39, 0xc000
	ds_read_b128 v[184:187], v156
	ds_read_b128 v[188:191], v156 offset:1024
	ds_read_b128 v[192:195], v156 offset:2048
	ds_read_b128 v[200:203], v156 offset:3072
	ds_read_b128 v[204:207], v156 offset:4096
	ds_read_b128 v[208:211], v156 offset:5120
	ds_read_b128 v[212:215], v156 offset:6144
	ds_read_b128 v[216:219], v156 offset:7168
	global_load_lds_dwordx4 v[196:197], off
	v_lshl_add_u64 v[196:197], s[24:25], 0, v[138:139]
	s_add_i32 m0, s39, 0xe000
	s_nop 0
	global_load_lds_dwordx4 v[196:197], off
	s_waitcnt vmcnt(8)
	s_waitcnt lgkmcnt(0)
	s_barrier
	s_waitcnt lgkmcnt(0)
	v_mfma_f32_16x16x32_bf16 v[124:127], v[144:147], v[184:187], v[124:127]
	v_mfma_f32_16x16x32_bf16 v[120:123], v[160:163], v[184:187], v[120:123]
	v_mfma_f32_16x16x32_bf16 v[108:111], v[144:147], v[192:195], v[108:111]
	v_mfma_f32_16x16x32_bf16 v[104:107], v[160:163], v[192:195], v[104:107]
	v_mfma_f32_16x16x32_bf16 v[92:95], v[144:147], v[204:207], v[92:95]
	v_mfma_f32_16x16x32_bf16 v[88:91], v[160:163], v[204:207], v[88:91]
	v_mfma_f32_16x16x32_bf16 v[76:79], v[144:147], v[212:215], v[76:79]
	v_mfma_f32_16x16x32_bf16 v[72:75], v[160:163], v[212:215], v[72:75]
	v_mfma_f32_16x16x32_bf16 v[124:127], v[148:151], v[188:191], v[124:127]
	v_mfma_f32_16x16x32_bf16 v[120:123], v[164:167], v[188:191], v[120:123]
	v_mfma_f32_16x16x32_bf16 v[108:111], v[148:151], v[200:203], v[108:111]
	v_mfma_f32_16x16x32_bf16 v[104:107], v[164:167], v[200:203], v[104:107]
	v_mfma_f32_16x16x32_bf16 v[92:95], v[148:151], v[208:211], v[92:95]
	v_mfma_f32_16x16x32_bf16 v[88:91], v[164:167], v[208:211], v[88:91]
	v_mfma_f32_16x16x32_bf16 v[76:79], v[148:151], v[216:219], v[76:79]
	v_mfma_f32_16x16x32_bf16 v[72:75], v[164:167], v[216:219], v[72:75]
	v_mfma_f32_16x16x32_bf16 v[116:119], v[168:171], v[184:187], v[116:119]
	v_mfma_f32_16x16x32_bf16 v[112:115], v[176:179], v[184:187], v[112:115]
	v_mfma_f32_16x16x32_bf16 v[100:103], v[168:171], v[192:195], v[100:103]
	v_mfma_f32_16x16x32_bf16 v[96:99], v[176:179], v[192:195], v[96:99]
	v_mfma_f32_16x16x32_bf16 v[84:87], v[168:171], v[204:207], v[84:87]
	v_mfma_f32_16x16x32_bf16 v[80:83], v[176:179], v[204:207], v[80:83]
	v_mfma_f32_16x16x32_bf16 v[68:71], v[168:171], v[212:215], v[68:71]
	v_mfma_f32_16x16x32_bf16 v[64:67], v[176:179], v[212:215], v[64:67]
	v_mfma_f32_16x16x32_bf16 v[116:119], v[172:175], v[188:191], v[116:119]
	v_mfma_f32_16x16x32_bf16 v[112:115], v[180:183], v[188:191], v[112:115]
	v_mfma_f32_16x16x32_bf16 v[100:103], v[172:175], v[200:203], v[100:103]
	v_mfma_f32_16x16x32_bf16 v[96:99], v[180:183], v[200:203], v[96:99]
	v_mfma_f32_16x16x32_bf16 v[84:87], v[172:175], v[208:211], v[84:87]
	v_mfma_f32_16x16x32_bf16 v[80:83], v[180:183], v[208:211], v[80:83]
	v_mfma_f32_16x16x32_bf16 v[68:71], v[172:175], v[216:219], v[68:71]
	v_mfma_f32_16x16x32_bf16 v[64:67], v[180:183], v[216:219], v[64:67]
	s_barrier
	s_mov_b32 m0, s23
	v_lshl_add_u64 v[196:197], s[26:27], 0, v[132:133]
	s_add_u32 s60, s26, 0x40000
	ds_read_b128 v[184:187], v156 offset:16384
	ds_read_b128 v[188:191], v156 offset:17408
	ds_read_b128 v[192:195], v156 offset:18432
	ds_read_b128 v[200:203], v156 offset:19456
	ds_read_b128 v[204:207], v156 offset:20480
	ds_read_b128 v[208:211], v156 offset:21504
	ds_read_b128 v[212:215], v156 offset:22528
	ds_read_b128 v[216:219], v156 offset:23552
	global_load_lds_dwordx4 v[196:197], off
	v_lshl_add_u64 v[220:221], s[26:27], 0, v[128:129]
	s_mov_b32 m0, s36
	s_addc_u32 s61, s27, 0
	global_load_lds_dwordx4 v[220:221], off
	v_lshl_add_u64 v[222:223], s[60:61], 0, v[132:133]
	s_mov_b32 m0, s37
	v_lshl_add_u64 v[224:225], s[28:29], 0, v[130:131]
	global_load_lds_dwordx4 v[222:223], off
	v_lshl_add_u64 v[222:223], s[60:61], 0, v[128:129]
	s_mov_b32 m0, s38
	s_nop 0
	global_load_lds_dwordx4 v[222:223], off
	v_lshl_add_u64 v[222:223], s[28:29], 0, v[134:135]
	s_mov_b32 m0, s39
	s_nop 0
	global_load_lds_dwordx4 v[222:223], off
	s_mov_b32 m0, s40
	s_nop 0
	global_load_lds_dwordx4 v[224:225], off
	s_waitcnt vmcnt(8)
	s_waitcnt lgkmcnt(0)
	s_barrier
; #define PG8_STAGE(bufoff, gbase, voff) do { _Pragma("unroll") for (int _i = 0; _i < 2; ++_i) \
;         __builtin_amdgcn_global_load_lds((const unsigned*)((const char*)(gbase) + (voff)[_i]), (PG8_LAS unsigned*)(lds + (bufoff) + ldsw + _i * 8192), 16, 0, 0); } while (0)
; #define PG8_LDA(dst, b, h) do { _Pragma("unroll") for (int m = 0; m < 4; ++m) _Pragma("unroll") for (int k = 0; k < 2; ++k) dst[m][k] = *(const PG8_LAS bf16x8*)(lds + PG8_SA(b, h) + aoff + m * 2048 + k * 1024); } while (0)
; #define PG8_LDB(dst, b, h) do { _Pragma("unroll") for (int n = 0; n < 2; ++n) _Pragma("unroll") for (int k = 0; k < 2; ++k) dst[n][k] = *(const PG8_LAS bf16x8*)(lds + PG8_SB(b, h) + boff + n * 2048 + k * 1024); } while (0)
; #define PG8_MMA(ai, bj, At, Bt) do { __builtin_amdgcn_s_setprio(1); _Pragma("unroll") for (int m = 0; m < 4; ++m) _Pragma("unroll") for (int n = 0; n < 2; ++n) _Pragma("unroll") for (int k = 0; k < 2; ++k) \
;         acc[ai][bj][m][n] = __builtin_amdgcn_mfma_f32_16x16x32_bf16(Bt[n][k], At[m][k], acc[ai][bj][m][n], 0, 0, 0); __builtin_amdgcn_s_setprio(0); } while (0)
; #define PG8_WAIT_V(n) asm volatile("s_waitcnt vmcnt(" #n ")" ::: "memory")
; #define PG8_WAIT_L(n) asm volatile("s_waitcnt lgkmcnt(" #n ")" ::: "memory")
; #define PG8_BAR __builtin_amdgcn_s_barrier()
; #define PG8_SCHED __builtin_amdgcn_sched_barrier(0)
; template <class Epi, class Sched, bool ALIGN_EPI = false, bool SP2 = false>
; __device__ __forceinline__ void gemm_phase(PG8_LAS unsigned char* lds, const Gemm g, const Sched& S, const Epi& E, const int tid) {
;     ...
;             PG8_WAIT_V(8); PG8_WAIT_L(0); PG8_BAR; PG8_MMA(1, 0, At, B0); PG8_MMA(1, 1, At, B1); PG8_BAR; PG8_SCHED;
;             PG8_LDB(B0, 1, 0); PG8_LDB(B1, 1, 1); PG8_SCHED; PG8_LDA(At, 1, 0); PG8_STAGE(PG8_SA(0, 1), a2 + hstepA, voffA);
;             PG8_WAIT_V(8); PG8_WAIT_L(0); PG8_BAR; PG8_MMA(0, 0, At, B0); PG8_MMA(0, 1, At, B1); PG8_BAR; PG8_SCHED;
	s_waitcnt lgkmcnt(0)
	v_mfma_f32_16x16x32_bf16 v[60:63], v[144:147], v[184:187], v[60:63]
	v_mfma_f32_16x16x32_bf16 v[56:59], v[160:163], v[184:187], v[56:59]
	v_mfma_f32_16x16x32_bf16 v[44:47], v[144:147], v[192:195], v[44:47]
	v_mfma_f32_16x16x32_bf16 v[40:43], v[160:163], v[192:195], v[40:43]
	v_mfma_f32_16x16x32_bf16 v[28:31], v[144:147], v[204:207], v[28:31]
	v_mfma_f32_16x16x32_bf16 v[24:27], v[160:163], v[204:207], v[24:27]
	v_mfma_f32_16x16x32_bf16 v[12:15], v[144:147], v[212:215], v[12:15]
	v_mfma_f32_16x16x32_bf16 v[8:11], v[160:163], v[212:215], v[8:11]
	v_mfma_f32_16x16x32_bf16 v[60:63], v[148:151], v[188:191], v[60:63]
	v_mfma_f32_16x16x32_bf16 v[56:59], v[164:167], v[188:191], v[56:59]
	v_mfma_f32_16x16x32_bf16 v[44:47], v[148:151], v[200:203], v[44:47]
	v_mfma_f32_16x16x32_bf16 v[40:43], v[164:167], v[200:203], v[40:43]
	v_mfma_f32_16x16x32_bf16 v[28:31], v[148:151], v[208:211], v[28:31]
	v_mfma_f32_16x16x32_bf16 v[24:27], v[164:167], v[208:211], v[24:27]
	v_mfma_f32_16x16x32_bf16 v[12:15], v[148:151], v[216:219], v[12:15]
	v_mfma_f32_16x16x32_bf16 v[8:11], v[164:167], v[216:219], v[8:11]
	v_mfma_f32_16x16x32_bf16 v[52:55], v[168:171], v[184:187], v[52:55]
	v_mfma_f32_16x16x32_bf16 v[48:51], v[176:179], v[184:187], v[48:51]
	v_mfma_f32_16x16x32_bf16 v[36:39], v[168:171], v[192:195], v[36:39]
	v_mfma_f32_16x16x32_bf16 v[32:35], v[176:179], v[192:195], v[32:35]
	v_mfma_f32_16x16x32_bf16 v[20:23], v[168:171], v[204:207], v[20:23]
	v_mfma_f32_16x16x32_bf16 v[16:19], v[176:179], v[204:207], v[16:19]
	v_mfma_f32_16x16x32_bf16 v[4:7], v[168:171], v[212:215], v[4:7]
	v_mfma_f32_16x16x32_bf16 v[0:3], v[176:179], v[212:215], v[0:3]
	v_mfma_f32_16x16x32_bf16 v[52:55], v[172:175], v[188:191], v[52:55]
	v_mfma_f32_16x16x32_bf16 v[48:51], v[180:183], v[188:191], v[48:51]
	v_mfma_f32_16x16x32_bf16 v[36:39], v[172:175], v[200:203], v[36:39]
	v_mfma_f32_16x16x32_bf16 v[32:35], v[180:183], v[200:203], v[32:35]
	v_mfma_f32_16x16x32_bf16 v[20:23], v[172:175], v[208:211], v[20:23]
	v_mfma_f32_16x16x32_bf16 v[16:19], v[180:183], v[208:211], v[16:19]
	v_mfma_f32_16x16x32_bf16 v[4:7], v[172:175], v[216:219], v[4:7]
	v_mfma_f32_16x16x32_bf16 v[0:3], v[180:183], v[216:219], v[0:3]
	s_barrier
	ds_read_b128 v[144:147], v157
	ds_read_b128 v[148:151], v157 offset:1024
	ds_read_b128 v[160:163], v157 offset:2048
	ds_read_b128 v[164:167], v157 offset:3072
	ds_read_b128 v[168:171], v158
	ds_read_b128 v[172:175], v158 offset:1024
	ds_read_b128 v[176:179], v158 offset:2048
	ds_read_b128 v[180:183], v158 offset:3072
	s_add_u32 s28, s28, 0x40000
	s_addc_u32 s29, s29, 0
	s_mov_b32 m0, s41
	v_lshl_add_u64 v[226:227], s[28:29], 0, v[134:135]
	ds_read_b128 v[184:187], v156 offset:32768
	ds_read_b128 v[188:191], v156 offset:33792
	ds_read_b128 v[192:195], v156 offset:34816
	ds_read_b128 v[200:203], v156 offset:35840
	ds_read_b128 v[204:207], v156 offset:36864
	ds_read_b128 v[208:211], v156 offset:37888
	ds_read_b128 v[212:215], v156 offset:38912
	ds_read_b128 v[216:219], v156 offset:39936
	global_load_lds_dwordx4 v[226:227], off
	v_lshl_add_u64 v[226:227], s[28:29], 0, v[130:131]
	s_mov_b32 m0, s42
	s_nop 0
	global_load_lds_dwordx4 v[226:227], off
	s_waitcnt vmcnt(8)
	s_waitcnt lgkmcnt(0)
	s_barrier
	s_waitcnt lgkmcnt(0)
	v_mfma_f32_16x16x32_bf16 v[124:127], v[144:147], v[184:187], v[124:127]
	v_mfma_f32_16x16x32_bf16 v[120:123], v[160:163], v[184:187], v[120:123]
	v_mfma_f32_16x16x32_bf16 v[108:111], v[144:147], v[192:195], v[108:111]
	v_mfma_f32_16x16x32_bf16 v[104:107], v[160:163], v[192:195], v[104:107]
	v_mfma_f32_16x16x32_bf16 v[92:95], v[144:147], v[204:207], v[92:95]
	v_mfma_f32_16x16x32_bf16 v[88:91], v[160:163], v[204:207], v[88:91]
	v_mfma_f32_16x16x32_bf16 v[76:79], v[144:147], v[212:215], v[76:79]
	v_mfma_f32_16x16x32_bf16 v[72:75], v[160:163], v[212:215], v[72:75]
	v_mfma_f32_16x16x32_bf16 v[124:127], v[148:151], v[188:191], v[124:127]
	v_mfma_f32_16x16x32_bf16 v[120:123], v[164:167], v[188:191], v[120:123]
	v_mfma_f32_16x16x32_bf16 v[108:111], v[148:151], v[200:203], v[108:111]
	v_mfma_f32_16x16x32_bf16 v[104:107], v[164:167], v[200:203], v[104:107]
	v_mfma_f32_16x16x32_bf16 v[92:95], v[148:151], v[208:211], v[92:95]
	v_mfma_f32_16x16x32_bf16 v[88:91], v[164:167], v[208:211], v[88:91]
	v_mfma_f32_16x16x32_bf16 v[76:79], v[148:151], v[216:219], v[76:79]
	v_mfma_f32_16x16x32_bf16 v[72:75], v[164:167], v[216:219], v[72:75]
	v_mfma_f32_16x16x32_bf16 v[116:119], v[168:171], v[184:187], v[116:119]
	v_mfma_f32_16x16x32_bf16 v[112:115], v[176:179], v[184:187], v[112:115]
	v_mfma_f32_16x16x32_bf16 v[100:103], v[168:171], v[192:195], v[100:103]
	v_mfma_f32_16x16x32_bf16 v[96:99], v[176:179], v[192:195], v[96:99]
	v_mfma_f32_16x16x32_bf16 v[84:87], v[168:171], v[204:207], v[84:87]
	v_mfma_f32_16x16x32_bf16 v[80:83], v[176:179], v[204:207], v[80:83]
	v_mfma_f32_16x16x32_bf16 v[68:71], v[168:171], v[212:215], v[68:71]
	v_mfma_f32_16x16x32_bf16 v[64:67], v[176:179], v[212:215], v[64:67]
	v_mfma_f32_16x16x32_bf16 v[116:119], v[172:175], v[188:191], v[116:119]
	v_mfma_f32_16x16x32_bf16 v[112:115], v[180:183], v[188:191], v[112:115]
	v_mfma_f32_16x16x32_bf16 v[100:103], v[172:175], v[200:203], v[100:103]
	v_mfma_f32_16x16x32_bf16 v[96:99], v[180:183], v[200:203], v[96:99]
	v_mfma_f32_16x16x32_bf16 v[84:87], v[172:175], v[208:211], v[84:87]
	v_mfma_f32_16x16x32_bf16 v[80:83], v[180:183], v[208:211], v[80:83]
	v_mfma_f32_16x16x32_bf16 v[68:71], v[172:175], v[216:219], v[68:71]
	v_mfma_f32_16x16x32_bf16 v[64:67], v[180:183], v[216:219], v[64:67]
	s_barrier
; #define PG8_STAGE(bufoff, gbase, voff) do { _Pragma("unroll") for (int _i = 0; _i < 2; ++_i) \
;         __builtin_amdgcn_global_load_lds((const unsigned*)((const char*)(gbase) + (voff)[_i]), (PG8_LAS unsigned*)(lds + (bufoff) + ldsw + _i * 8192), 16, 0, 0); } while (0)
; #define PG8_LDA(dst, b, h) do { _Pragma("unroll") for (int m = 0; m < 4; ++m) _Pragma("unroll") for (int k = 0; k < 2; ++k) dst[m][k] = *(const PG8_LAS bf16x8*)(lds + PG8_SA(b, h) + aoff + m * 2048 + k * 1024); } while (0)
; #define PG8_MMA(ai, bj, At, Bt) do { __builtin_amdgcn_s_setprio(1); _Pragma("unroll") for (int m = 0; m < 4; ++m) _Pragma("unroll") for (int n = 0; n < 2; ++n) _Pragma("unroll") for (int k = 0; k < 2; ++k) \
;         acc[ai][bj][m][n] = __builtin_amdgcn_mfma_f32_16x16x32_bf16(Bt[n][k], At[m][k], acc[ai][bj][m][n], 0, 0, 0); __builtin_amdgcn_s_setprio(0); } while (0)
; #define PG8_WAIT_V(n) asm volatile("s_waitcnt vmcnt(" #n ")" ::: "memory")
; #define PG8_WAIT_L(n) asm volatile("s_waitcnt lgkmcnt(" #n ")" ::: "memory")
; #define PG8_BAR __builtin_amdgcn_s_barrier()
; #define PG8_SCHED __builtin_amdgcn_sched_barrier(0)
; __device__ __forceinline__ float ss_scale(const u64* ss, int row) { return __builtin_amdgcn_rsqf((float)ss[row] * (1.f / 4294967296.f / 1024.f) + EPS); }
; template <class Epi, class Sched, bool ALIGN_EPI = false, bool SP2 = false>
; __device__ __forceinline__ void gemm_phase(PG8_LAS unsigned char* lds, const Gemm g, const Sched& S, const Epi& E, const int tid) {
;     ...
;             PG8_LDA(At, 1, 1); PG8_STAGE(PG8_SB(1, 0), b3, voffB); PG8_STAGE(PG8_SB(1, 1), b3 + hstep, voffB); PG8_STAGE(PG8_SA(1, 0), a3, voffA);
;             PG8_WAIT_V(8); PG8_WAIT_L(0); PG8_BAR; PG8_MMA(1, 0, At, B0); PG8_MMA(1, 1, At, B1); PG8_BAR; PG8_SCHED;
;     __device__ __forceinline__ void operator()(const f32x4 (&acc)[2][2][4][2], const pg8::Unit& u, int wr, int wc, int fr, int fq) const {
;         const int row0 = u.pm * 256 + wr * 64 + fr, col0 = u.pn * 128 + wc * 32 + 8 * fq;
; #pragma unroll
;         for (int ai = 0; ai < 2; ++ai)
; #pragma unroll
;             for (int m = 0; m < 4; ++m) {
;                 const int row = row0 + ai * 128 + m * 16;
;                 float s = ss_scale(ss, row);
	s_mov_b32 m0, s45
	v_lshl_add_u64 v[196:197], v[196:197], 0, s[10:11]
	s_add_u32 s26, s26, 0x40080
	ds_read_b128 v[184:187], v156 offset:49152
	ds_read_b128 v[188:191], v156 offset:50176
	ds_read_b128 v[192:195], v156 offset:51200
	ds_read_b128 v[200:203], v156 offset:52224
	ds_read_b128 v[204:207], v156 offset:53248
	ds_read_b128 v[208:211], v156 offset:54272
	ds_read_b128 v[212:215], v156 offset:55296
	ds_read_b128 v[216:219], v156 offset:56320
	global_load_lds_dwordx4 v[196:197], off
	v_lshl_add_u64 v[196:197], v[220:221], 0, s[10:11]
	s_mov_b32 m0, s46
	s_addc_u32 s27, s27, 0
	global_load_lds_dwordx4 v[196:197], off
	v_lshl_add_u64 v[196:197], s[26:27], 0, v[132:133]
	s_mov_b32 m0, s49
	s_nop 0
	global_load_lds_dwordx4 v[196:197], off
	v_lshl_add_u64 v[196:197], s[26:27], 0, v[128:129]
	s_mov_b32 m0, s50
	s_nop 0
	global_load_lds_dwordx4 v[196:197], off
	v_lshl_add_u64 v[196:197], v[222:223], 0, s[10:11]
	s_mov_b32 m0, s47
	s_nop 0
	global_load_lds_dwordx4 v[196:197], off
	v_lshl_add_u64 v[196:197], v[224:225], 0, s[10:11]
	s_mov_b32 m0, s48
	s_nop 0
	global_load_lds_dwordx4 v[196:197], off
	s_waitcnt vmcnt(8)
	s_waitcnt lgkmcnt(0)
	s_barrier
	s_waitcnt lgkmcnt(0)
	v_mfma_f32_16x16x32_bf16 v[60:63], v[144:147], v[184:187], v[60:63]
	v_mfma_f32_16x16x32_bf16 v[56:59], v[160:163], v[184:187], v[56:59]
	v_mfma_f32_16x16x32_bf16 v[44:47], v[144:147], v[192:195], v[44:47]
	v_mfma_f32_16x16x32_bf16 v[40:43], v[160:163], v[192:195], v[40:43]
	v_mfma_f32_16x16x32_bf16 v[28:31], v[144:147], v[204:207], v[28:31]
	v_mfma_f32_16x16x32_bf16 v[24:27], v[160:163], v[204:207], v[24:27]
	v_mfma_f32_16x16x32_bf16 v[12:15], v[144:147], v[212:215], v[12:15]
	v_mfma_f32_16x16x32_bf16 v[8:11], v[160:163], v[212:215], v[8:11]
	v_mfma_f32_16x16x32_bf16 v[60:63], v[148:151], v[188:191], v[60:63]
	v_mfma_f32_16x16x32_bf16 v[56:59], v[164:167], v[188:191], v[56:59]
	v_mfma_f32_16x16x32_bf16 v[44:47], v[148:151], v[200:203], v[44:47]
	v_mfma_f32_16x16x32_bf16 v[40:43], v[164:167], v[200:203], v[40:43]
	v_mfma_f32_16x16x32_bf16 v[28:31], v[148:151], v[208:211], v[28:31]
	v_mfma_f32_16x16x32_bf16 v[24:27], v[164:167], v[208:211], v[24:27]
	v_mfma_f32_16x16x32_bf16 v[12:15], v[148:151], v[216:219], v[12:15]
	v_mfma_f32_16x16x32_bf16 v[8:11], v[164:167], v[216:219], v[8:11]
	v_mfma_f32_16x16x32_bf16 v[52:55], v[168:171], v[184:187], v[52:55]
	v_mfma_f32_16x16x32_bf16 v[48:51], v[176:179], v[184:187], v[48:51]
	v_mfma_f32_16x16x32_bf16 v[36:39], v[168:171], v[192:195], v[36:39]
	v_mfma_f32_16x16x32_bf16 v[32:35], v[176:179], v[192:195], v[32:35]
	v_mfma_f32_16x16x32_bf16 v[20:23], v[168:171], v[204:207], v[20:23]
	v_mfma_f32_16x16x32_bf16 v[16:19], v[176:179], v[204:207], v[16:19]
	v_mfma_f32_16x16x32_bf16 v[4:7], v[168:171], v[212:215], v[4:7]
	v_mfma_f32_16x16x32_bf16 v[0:3], v[176:179], v[212:215], v[0:3]
	v_mfma_f32_16x16x32_bf16 v[52:55], v[172:175], v[188:191], v[52:55]
	v_mfma_f32_16x16x32_bf16 v[48:51], v[180:183], v[188:191], v[48:51]
	v_mfma_f32_16x16x32_bf16 v[36:39], v[172:175], v[200:203], v[36:39]
	v_mfma_f32_16x16x32_bf16 v[32:35], v[180:183], v[200:203], v[32:35]
	v_mfma_f32_16x16x32_bf16 v[20:23], v[172:175], v[208:211], v[20:23]
	v_mfma_f32_16x16x32_bf16 v[16:19], v[180:183], v[208:211], v[16:19]
	v_mfma_f32_16x16x32_bf16 v[4:7], v[172:175], v[216:219], v[4:7]
	v_mfma_f32_16x16x32_bf16 v[0:3], v[180:183], v[216:219], v[0:3]
	s_barrier
	s_add_i32 s58, s58, 2
	s_add_u32 s24, s24, 0x100
	s_addc_u32 s25, s25, 0
	s_add_u32 s56, s56, 0x100
	s_addc_u32 s57, s57, 0
	s_cmp_gt_u32 s58, 13
	s_cbranch_scc0 .LBB0_279
	v_lshl_add_u32 v144, s22, 8, v152
	v_mov_b32_e32 v145, 0
	v_lshl_add_u64 v[150:151], v[144:145], 3, s[6:7]
	global_load_dwordx2 v[176:177], v[150:151], off
	global_load_dwordx2 v[178:179], v[150:151], off offset:128
	global_load_dwordx2 v[180:181], v[150:151], off offset:256
	global_load_dwordx2 v[182:183], v[150:151], off offset:384
	global_load_dwordx2 v[184:185], v[150:151], off offset:1024
	global_load_dwordx2 v[186:187], v[150:151], off offset:1152
	global_load_dwordx2 v[188:189], v[150:151], off offset:1280
	global_load_dwordx2 v[190:191], v[150:151], off offset:1408
	v_lshl_or_b32 v148, s53, 7, v153
	v_mul_u32_u24_e32 v146, s52, v144
	v_lshl_add_u32 v146, v148, 1, v146
	v_mov_b32_e32 v147, 0
	v_lshl_add_u64 v[146:147], v[146:147], 0, s[8:9]
	v_mov_b32_e32 v164, 1.0
	v_mov_b32_e32 v165, 1.0
	s_mov_b32 s101, 0
	s_and_b64 vcc, exec, s[12:13]
	s_cbranch_vccz .LBB0_282
	s_barrier

; #define PG8_STAGE(bufoff, gbase, voff) do { _Pragma("unroll") for (int _i = 0; _i < 2; ++_i) \
;         __builtin_amdgcn_global_load_lds((const unsigned*)((const char*)(gbase) + (voff)[_i]), (PG8_LAS unsigned*)(lds + (bufoff) + ldsw + _i * 8192), 16, 0, 0); } while (0)
; #define PG8_LDA(dst, b, h) do { _Pragma("unroll") for (int m = 0; m < 4; ++m) _Pragma("unroll") for (int k = 0; k < 2; ++k) dst[m][k] = *(const PG8_LAS bf16x8*)(lds + PG8_SA(b, h) + aoff + m * 2048 + k * 1024); } while (0)
; #define PG8_LDB(dst, b, h) do { _Pragma("unroll") for (int n = 0; n < 2; ++n) _Pragma("unroll") for (int k = 0; k < 2; ++k) dst[n][k] = *(const PG8_LAS bf16x8*)(lds + PG8_SB(b, h) + boff + n * 2048 + k * 1024); } while (0)
; #define PG8_MMA(ai, bj, At, Bt) do { __builtin_amdgcn_s_setprio(1); _Pragma("unroll") for (int m = 0; m < 4; ++m) _Pragma("unroll") for (int n = 0; n < 2; ++n) _Pragma("unroll") for (int k = 0; k < 2; ++k) \
;         acc[ai][bj][m][n] = __builtin_amdgcn_mfma_f32_16x16x32_bf16(Bt[n][k], At[m][k], acc[ai][bj][m][n], 0, 0, 0); __builtin_amdgcn_s_setprio(0); } while (0)
; #define PG8_WAIT_V(n) asm volatile("s_waitcnt vmcnt(" #n ")" ::: "memory")
; #define PG8_WAIT_L(n) asm volatile("s_waitcnt lgkmcnt(" #n ")" ::: "memory")
; template <class Epi, class Sched, bool ALIGN_EPI = false, bool SP2 = false>
; __device__ __forceinline__ void gemm_phase(PG8_LAS unsigned char* lds, const Gemm g, const Sched& S, const Epi& E, const int tid) {
;     ...
;             const bool last = (t == nt - 2);
;             const char* a1 = cA + (size_t)(t + 1) * kstep;
;             const char* a2 = last ? nA : cA + (size_t)(t + 2) * kstep; const char* b2 = last ? nB : cB + (size_t)(t + 2) * kstep;
;             const char* a3 = a2 + kstep; const char* b3 = b2 + kstep;
;             if (last && has_next) S.a_ready(nxt);
;             if constexpr (SP2) {
;             PG8_LDB(B0, 0, 0); PG8_LDB(B1, 0, 1); PG8_SCHED; PG8_LDA(At, 0, 0); PG8_STAGE(PG8_SA(1, 1), a1 + hstepA, voffA);
;             PG8_WAIT_V(8); PG8_WAIT_L(0); PG8_BAR; PG8_MMA(0, 0, At, B0); PG8_MMA(0, 1, At, B1); PG8_BAR; PG8_SCHED;
;             PG8_LDA(At, 0, 1); PG8_STAGE(PG8_SB(0, 0), b2, voffB); PG8_STAGE(PG8_SB(0, 1), b2 + hstep, voffB); PG8_STAGE(PG8_SA(0, 0), a2, voffA);
;             PG8_WAIT_V(8); PG8_WAIT_L(0); PG8_BAR; PG8_MMA(1, 0, At, B0); PG8_MMA(1, 1, At, B1); PG8_BAR; PG8_SCHED;
.LBB0_353:
	ds_read_b128 v[144:147], v150
	ds_read_b128 v[156:159], v150 offset:1024
	ds_read_b128 v[160:163], v150 offset:2048
	ds_read_b128 v[164:167], v150 offset:3072
	ds_read_b128 v[168:171], v151
	ds_read_b128 v[172:175], v151 offset:1024
	ds_read_b128 v[176:179], v151 offset:2048
	ds_read_b128 v[180:183], v151 offset:3072
	s_add_u32 s24, s22, 0x100
	s_addc_u32 s25, s23, 0
	s_cmp_eq_u32 s59, 40
	s_cselect_b32 s29, s7, s25
	s_cselect_b32 s28, s6, s24
	s_cselect_b32 s27, s21, s58
	s_cselect_b32 s26, s20, s57
	v_lshl_add_u64 v[196:197], s[22:23], 0, v[136:137]
	s_add_i32 m0, s38, 0xc000
	ds_read_b128 v[184:187], v152
	ds_read_b128 v[188:191], v152 offset:1024
	ds_read_b128 v[192:195], v152 offset:2048
	ds_read_b128 v[200:203], v152 offset:3072
	ds_read_b128 v[204:207], v152 offset:4096
	ds_read_b128 v[208:211], v152 offset:5120
	ds_read_b128 v[212:215], v152 offset:6144
	ds_read_b128 v[216:219], v152 offset:7168
	global_load_lds_dwordx4 v[196:197], off
	v_lshl_add_u64 v[196:197], s[22:23], 0, v[138:139]
	s_add_i32 m0, s38, 0xe000
	s_nop 0
	global_load_lds_dwordx4 v[196:197], off
	s_waitcnt vmcnt(8)
	s_waitcnt lgkmcnt(0)
	s_barrier
	s_waitcnt lgkmcnt(0)
	v_mfma_f32_16x16x32_bf16 v[124:127], v[144:147], v[184:187], v[124:127]
	v_mfma_f32_16x16x32_bf16 v[120:123], v[160:163], v[184:187], v[120:123]
	v_mfma_f32_16x16x32_bf16 v[108:111], v[144:147], v[192:195], v[108:111]
	v_mfma_f32_16x16x32_bf16 v[104:107], v[160:163], v[192:195], v[104:107]
	v_mfma_f32_16x16x32_bf16 v[92:95], v[144:147], v[204:207], v[92:95]
	v_mfma_f32_16x16x32_bf16 v[88:91], v[160:163], v[204:207], v[88:91]
	v_mfma_f32_16x16x32_bf16 v[76:79], v[144:147], v[212:215], v[76:79]
	v_mfma_f32_16x16x32_bf16 v[72:75], v[160:163], v[212:215], v[72:75]
	v_mfma_f32_16x16x32_bf16 v[124:127], v[156:159], v[188:191], v[124:127]
	v_mfma_f32_16x16x32_bf16 v[120:123], v[164:167], v[188:191], v[120:123]
	v_mfma_f32_16x16x32_bf16 v[108:111], v[156:159], v[200:203], v[108:111]
	v_mfma_f32_16x16x32_bf16 v[104:107], v[164:167], v[200:203], v[104:107]
	v_mfma_f32_16x16x32_bf16 v[92:95], v[156:159], v[208:211], v[92:95]
	v_mfma_f32_16x16x32_bf16 v[88:91], v[164:167], v[208:211], v[88:91]
	v_mfma_f32_16x16x32_bf16 v[76:79], v[156:159], v[216:219], v[76:79]
	v_mfma_f32_16x16x32_bf16 v[72:75], v[164:167], v[216:219], v[72:75]
	v_mfma_f32_16x16x32_bf16 v[116:119], v[168:171], v[184:187], v[116:119]
	v_mfma_f32_16x16x32_bf16 v[112:115], v[176:179], v[184:187], v[112:115]
	v_mfma_f32_16x16x32_bf16 v[100:103], v[168:171], v[192:195], v[100:103]
	v_mfma_f32_16x16x32_bf16 v[96:99], v[176:179], v[192:195], v[96:99]
	v_mfma_f32_16x16x32_bf16 v[84:87], v[168:171], v[204:207], v[84:87]
	v_mfma_f32_16x16x32_bf16 v[80:83], v[176:179], v[204:207], v[80:83]
	v_mfma_f32_16x16x32_bf16 v[68:71], v[168:171], v[212:215], v[68:71]
	v_mfma_f32_16x16x32_bf16 v[64:67], v[176:179], v[212:215], v[64:67]
	v_mfma_f32_16x16x32_bf16 v[116:119], v[172:175], v[188:191], v[116:119]
	v_mfma_f32_16x16x32_bf16 v[112:115], v[180:183], v[188:191], v[112:115]
	v_mfma_f32_16x16x32_bf16 v[100:103], v[172:175], v[200:203], v[100:103]
	v_mfma_f32_16x16x32_bf16 v[96:99], v[180:183], v[200:203], v[96:99]
	v_mfma_f32_16x16x32_bf16 v[84:87], v[172:175], v[208:211], v[84:87]
	v_mfma_f32_16x16x32_bf16 v[80:83], v[180:183], v[208:211], v[80:83]
	v_mfma_f32_16x16x32_bf16 v[68:71], v[172:175], v[216:219], v[68:71]
	v_mfma_f32_16x16x32_bf16 v[64:67], v[180:183], v[216:219], v[64:67]
	s_barrier
	s_mov_b32 m0, s34
	v_lshl_add_u64 v[196:197], s[26:27], 0, v[130:131]
	s_add_u32 s22, s26, 0xb0000
	ds_read_b128 v[184:187], v152 offset:16384
	ds_read_b128 v[188:191], v152 offset:17408
	ds_read_b128 v[192:195], v152 offset:18432
	ds_read_b128 v[200:203], v152 offset:19456
	ds_read_b128 v[204:207], v152 offset:20480
	ds_read_b128 v[208:211], v152 offset:21504
	ds_read_b128 v[212:215], v152 offset:22528
	ds_read_b128 v[216:219], v152 offset:23552
	global_load_lds_dwordx4 v[196:197], off
	v_lshl_add_u64 v[220:221], s[26:27], 0, v[134:135]
	s_mov_b32 m0, s35
	s_addc_u32 s23, s27, 0
	global_load_lds_dwordx4 v[220:221], off
	v_lshl_add_u64 v[222:223], s[22:23], 0, v[130:131]
	s_mov_b32 m0, s36
	v_lshl_add_u64 v[224:225], s[28:29], 0, v[132:133]
	global_load_lds_dwordx4 v[222:223], off
	v_lshl_add_u64 v[222:223], s[22:23], 0, v[134:135]
	s_mov_b32 m0, s37
	s_nop 0
	global_load_lds_dwordx4 v[222:223], off
	v_lshl_add_u64 v[222:223], s[28:29], 0, v[128:129]
	s_mov_b32 m0, s38
	s_nop 0
	global_load_lds_dwordx4 v[222:223], off
	s_mov_b32 m0, s39
	s_nop 0
	global_load_lds_dwordx4 v[224:225], off
	s_waitcnt vmcnt(8)
	s_waitcnt lgkmcnt(0)
	s_barrier
; #define PG8_STAGE(bufoff, gbase, voff) do { _Pragma("unroll") for (int _i = 0; _i < 2; ++_i) \
;         __builtin_amdgcn_global_load_lds((const unsigned*)((const char*)(gbase) + (voff)[_i]), (PG8_LAS unsigned*)(lds + (bufoff) + ldsw + _i * 8192), 16, 0, 0); } while (0)
; #define PG8_LDA(dst, b, h) do { _Pragma("unroll") for (int m = 0; m < 4; ++m) _Pragma("unroll") for (int k = 0; k < 2; ++k) dst[m][k] = *(const PG8_LAS bf16x8*)(lds + PG8_SA(b, h) + aoff + m * 2048 + k * 1024); } while (0)
; #define PG8_LDB(dst, b, h) do { _Pragma("unroll") for (int n = 0; n < 2; ++n) _Pragma("unroll") for (int k = 0; k < 2; ++k) dst[n][k] = *(const PG8_LAS bf16x8*)(lds + PG8_SB(b, h) + boff + n * 2048 + k * 1024); } while (0)
; #define PG8_MMA(ai, bj, At, Bt) do { __builtin_amdgcn_s_setprio(1); _Pragma("unroll") for (int m = 0; m < 4; ++m) _Pragma("unroll") for (int n = 0; n < 2; ++n) _Pragma("unroll") for (int k = 0; k < 2; ++k) \
;         acc[ai][bj][m][n] = __builtin_amdgcn_mfma_f32_16x16x32_bf16(Bt[n][k], At[m][k], acc[ai][bj][m][n], 0, 0, 0); __builtin_amdgcn_s_setprio(0); } while (0)
; #define PG8_WAIT_V(n) asm volatile("s_waitcnt vmcnt(" #n ")" ::: "memory")
; #define PG8_WAIT_L(n) asm volatile("s_waitcnt lgkmcnt(" #n ")" ::: "memory")
; #define PG8_BAR __builtin_amdgcn_s_barrier()
; #define PG8_SCHED __builtin_amdgcn_sched_barrier(0)
; template <class Epi, class Sched, bool ALIGN_EPI = false, bool SP2 = false>
; __device__ __forceinline__ void gemm_phase(PG8_LAS unsigned char* lds, const Gemm g, const Sched& S, const Epi& E, const int tid) {
;     ...
;             PG8_WAIT_V(8); PG8_WAIT_L(0); PG8_BAR; PG8_MMA(1, 0, At, B0); PG8_MMA(1, 1, At, B1); PG8_BAR; PG8_SCHED;
;             PG8_LDB(B0, 1, 0); PG8_LDB(B1, 1, 1); PG8_SCHED; PG8_LDA(At, 1, 0); PG8_STAGE(PG8_SA(0, 1), a2 + hstepA, voffA);
;             PG8_WAIT_V(8); PG8_WAIT_L(0); PG8_BAR; PG8_MMA(0, 0, At, B0); PG8_MMA(0, 1, At, B1); PG8_BAR; PG8_SCHED;
	s_waitcnt lgkmcnt(0)
	v_mfma_f32_16x16x32_bf16 v[60:63], v[144:147], v[184:187], v[60:63]
	v_mfma_f32_16x16x32_bf16 v[56:59], v[160:163], v[184:187], v[56:59]
	v_mfma_f32_16x16x32_bf16 v[44:47], v[144:147], v[192:195], v[44:47]
	v_mfma_f32_16x16x32_bf16 v[40:43], v[160:163], v[192:195], v[40:43]
	v_mfma_f32_16x16x32_bf16 v[28:31], v[144:147], v[204:207], v[28:31]
	v_mfma_f32_16x16x32_bf16 v[24:27], v[160:163], v[204:207], v[24:27]
	v_mfma_f32_16x16x32_bf16 v[12:15], v[144:147], v[212:215], v[12:15]
	v_mfma_f32_16x16x32_bf16 v[8:11], v[160:163], v[212:215], v[8:11]
	v_mfma_f32_16x16x32_bf16 v[60:63], v[156:159], v[188:191], v[60:63]
	v_mfma_f32_16x16x32_bf16 v[56:59], v[164:167], v[188:191], v[56:59]
	v_mfma_f32_16x16x32_bf16 v[44:47], v[156:159], v[200:203], v[44:47]
	v_mfma_f32_16x16x32_bf16 v[40:43], v[164:167], v[200:203], v[40:43]
	v_mfma_f32_16x16x32_bf16 v[28:31], v[156:159], v[208:211], v[28:31]
	v_mfma_f32_16x16x32_bf16 v[24:27], v[164:167], v[208:211], v[24:27]
	v_mfma_f32_16x16x32_bf16 v[12:15], v[156:159], v[216:219], v[12:15]
	v_mfma_f32_16x16x32_bf16 v[8:11], v[164:167], v[216:219], v[8:11]
	v_mfma_f32_16x16x32_bf16 v[52:55], v[168:171], v[184:187], v[52:55]
	v_mfma_f32_16x16x32_bf16 v[48:51], v[176:179], v[184:187], v[48:51]
	v_mfma_f32_16x16x32_bf16 v[36:39], v[168:171], v[192:195], v[36:39]
	v_mfma_f32_16x16x32_bf16 v[32:35], v[176:179], v[192:195], v[32:35]
	v_mfma_f32_16x16x32_bf16 v[20:23], v[168:171], v[204:207], v[20:23]
	v_mfma_f32_16x16x32_bf16 v[16:19], v[176:179], v[204:207], v[16:19]
	v_mfma_f32_16x16x32_bf16 v[4:7], v[168:171], v[212:215], v[4:7]
	v_mfma_f32_16x16x32_bf16 v[0:3], v[176:179], v[212:215], v[0:3]
	v_mfma_f32_16x16x32_bf16 v[52:55], v[172:175], v[188:191], v[52:55]
	v_mfma_f32_16x16x32_bf16 v[48:51], v[180:183], v[188:191], v[48:51]
	v_mfma_f32_16x16x32_bf16 v[36:39], v[172:175], v[200:203], v[36:39]
	v_mfma_f32_16x16x32_bf16 v[32:35], v[180:183], v[200:203], v[32:35]
	v_mfma_f32_16x16x32_bf16 v[20:23], v[172:175], v[208:211], v[20:23]
	v_mfma_f32_16x16x32_bf16 v[16:19], v[180:183], v[208:211], v[16:19]
	v_mfma_f32_16x16x32_bf16 v[4:7], v[172:175], v[216:219], v[4:7]
	v_mfma_f32_16x16x32_bf16 v[0:3], v[180:183], v[216:219], v[0:3]
	s_barrier
	ds_read_b128 v[144:147], v153
	ds_read_b128 v[156:159], v153 offset:1024
	ds_read_b128 v[160:163], v153 offset:2048
	ds_read_b128 v[164:167], v153 offset:3072
	ds_read_b128 v[168:171], v154
	ds_read_b128 v[172:175], v154 offset:1024
	ds_read_b128 v[176:179], v154 offset:2048
	ds_read_b128 v[180:183], v154 offset:3072
	s_add_u32 s22, s28, 0xb0000
	s_addc_u32 s23, s29, 0
	s_mov_b32 m0, s40
	v_lshl_add_u64 v[226:227], s[22:23], 0, v[128:129]
	ds_read_b128 v[184:187], v152 offset:32768
	ds_read_b128 v[188:191], v152 offset:33792
	ds_read_b128 v[192:195], v152 offset:34816
	ds_read_b128 v[200:203], v152 offset:35840
	ds_read_b128 v[204:207], v152 offset:36864
	ds_read_b128 v[208:211], v152 offset:37888
	ds_read_b128 v[212:215], v152 offset:38912
	ds_read_b128 v[216:219], v152 offset:39936
	global_load_lds_dwordx4 v[226:227], off
	v_lshl_add_u64 v[226:227], s[22:23], 0, v[132:133]
	s_mov_b32 m0, s41
	s_nop 0
	global_load_lds_dwordx4 v[226:227], off
	s_waitcnt vmcnt(8)
	s_waitcnt lgkmcnt(0)
	s_barrier
	s_waitcnt lgkmcnt(0)
	v_mfma_f32_16x16x32_bf16 v[124:127], v[144:147], v[184:187], v[124:127]
	v_mfma_f32_16x16x32_bf16 v[120:123], v[160:163], v[184:187], v[120:123]
	v_mfma_f32_16x16x32_bf16 v[108:111], v[144:147], v[192:195], v[108:111]
	v_mfma_f32_16x16x32_bf16 v[104:107], v[160:163], v[192:195], v[104:107]
	v_mfma_f32_16x16x32_bf16 v[92:95], v[144:147], v[204:207], v[92:95]
	v_mfma_f32_16x16x32_bf16 v[88:91], v[160:163], v[204:207], v[88:91]
	v_mfma_f32_16x16x32_bf16 v[76:79], v[144:147], v[212:215], v[76:79]
	v_mfma_f32_16x16x32_bf16 v[72:75], v[160:163], v[212:215], v[72:75]
	v_mfma_f32_16x16x32_bf16 v[124:127], v[156:159], v[188:191], v[124:127]
	v_mfma_f32_16x16x32_bf16 v[120:123], v[164:167], v[188:191], v[120:123]
	v_mfma_f32_16x16x32_bf16 v[108:111], v[156:159], v[200:203], v[108:111]
	v_mfma_f32_16x16x32_bf16 v[104:107], v[164:167], v[200:203], v[104:107]
	v_mfma_f32_16x16x32_bf16 v[92:95], v[156:159], v[208:211], v[92:95]
	v_mfma_f32_16x16x32_bf16 v[88:91], v[164:167], v[208:211], v[88:91]
	v_mfma_f32_16x16x32_bf16 v[76:79], v[156:159], v[216:219], v[76:79]
	v_mfma_f32_16x16x32_bf16 v[72:75], v[164:167], v[216:219], v[72:75]
	v_mfma_f32_16x16x32_bf16 v[116:119], v[168:171], v[184:187], v[116:119]
	v_mfma_f32_16x16x32_bf16 v[112:115], v[176:179], v[184:187], v[112:115]
	v_mfma_f32_16x16x32_bf16 v[100:103], v[168:171], v[192:195], v[100:103]
	v_mfma_f32_16x16x32_bf16 v[96:99], v[176:179], v[192:195], v[96:99]
	v_mfma_f32_16x16x32_bf16 v[84:87], v[168:171], v[204:207], v[84:87]
	v_mfma_f32_16x16x32_bf16 v[80:83], v[176:179], v[204:207], v[80:83]
	v_mfma_f32_16x16x32_bf16 v[68:71], v[168:171], v[212:215], v[68:71]
	v_mfma_f32_16x16x32_bf16 v[64:67], v[176:179], v[212:215], v[64:67]
	v_mfma_f32_16x16x32_bf16 v[116:119], v[172:175], v[188:191], v[116:119]
	v_mfma_f32_16x16x32_bf16 v[112:115], v[180:183], v[188:191], v[112:115]
	v_mfma_f32_16x16x32_bf16 v[100:103], v[172:175], v[200:203], v[100:103]
	v_mfma_f32_16x16x32_bf16 v[96:99], v[180:183], v[200:203], v[96:99]
	v_mfma_f32_16x16x32_bf16 v[84:87], v[172:175], v[208:211], v[84:87]
	v_mfma_f32_16x16x32_bf16 v[80:83], v[180:183], v[208:211], v[80:83]
	v_mfma_f32_16x16x32_bf16 v[68:71], v[172:175], v[216:219], v[68:71]
	v_mfma_f32_16x16x32_bf16 v[64:67], v[180:183], v[216:219], v[64:67]
	s_barrier
; #define PG8_STAGE(bufoff, gbase, voff) do { _Pragma("unroll") for (int _i = 0; _i < 2; ++_i) \
;         __builtin_amdgcn_global_load_lds((const unsigned*)((const char*)(gbase) + (voff)[_i]), (PG8_LAS unsigned*)(lds + (bufoff) + ldsw + _i * 8192), 16, 0, 0); } while (0)
; #define PG8_LDA(dst, b, h) do { _Pragma("unroll") for (int m = 0; m < 4; ++m) _Pragma("unroll") for (int k = 0; k < 2; ++k) dst[m][k] = *(const PG8_LAS bf16x8*)(lds + PG8_SA(b, h) + aoff + m * 2048 + k * 1024); } while (0)
; #define PG8_MMA(ai, bj, At, Bt) do { __builtin_amdgcn_s_setprio(1); _Pragma("unroll") for (int m = 0; m < 4; ++m) _Pragma("unroll") for (int n = 0; n < 2; ++n) _Pragma("unroll") for (int k = 0; k < 2; ++k) \
;         acc[ai][bj][m][n] = __builtin_amdgcn_mfma_f32_16x16x32_bf16(Bt[n][k], At[m][k], acc[ai][bj][m][n], 0, 0, 0); __builtin_amdgcn_s_setprio(0); } while (0)
; #define PG8_WAIT_V(n) asm volatile("s_waitcnt vmcnt(" #n ")" ::: "memory")
; #define PG8_WAIT_L(n) asm volatile("s_waitcnt lgkmcnt(" #n ")" ::: "memory")
; #define PG8_BAR __builtin_amdgcn_s_barrier()
; #define PG8_SCHED __builtin_amdgcn_sched_barrier(0)
; template <class Epi, class Sched, bool ALIGN_EPI = false, bool SP2 = false>
; __device__ __forceinline__ void gemm_phase(PG8_LAS unsigned char* lds, const Gemm g, const Sched& S, const Epi& E, const int tid) {
;     ...
;             PG8_LDA(At, 1, 1); PG8_STAGE(PG8_SB(1, 0), b3, voffB); PG8_STAGE(PG8_SB(1, 1), b3 + hstep, voffB); PG8_STAGE(PG8_SA(1, 0), a3, voffA);
;             PG8_WAIT_V(8); PG8_WAIT_L(0); PG8_BAR; PG8_MMA(1, 0, At, B0); PG8_MMA(1, 1, At, B1); PG8_BAR; PG8_SCHED;
	s_mov_b32 m0, s44
	v_lshl_add_u64 v[196:197], v[196:197], 0, s[14:15]
	s_add_u32 s22, s26, 0xb0080
	ds_read_b128 v[184:187], v152 offset:49152
	ds_read_b128 v[188:191], v152 offset:50176
	ds_read_b128 v[192:195], v152 offset:51200
	ds_read_b128 v[200:203], v152 offset:52224
	ds_read_b128 v[204:207], v152 offset:53248
	ds_read_b128 v[208:211], v152 offset:54272
	ds_read_b128 v[212:215], v152 offset:55296
	ds_read_b128 v[216:219], v152 offset:56320
	global_load_lds_dwordx4 v[196:197], off
	v_lshl_add_u64 v[196:197], v[220:221], 0, s[14:15]
	s_mov_b32 m0, s45
	s_addc_u32 s23, s27, 0
	global_load_lds_dwordx4 v[196:197], off
	v_lshl_add_u64 v[196:197], s[22:23], 0, v[130:131]
	s_mov_b32 m0, s48
	s_nop 0
	global_load_lds_dwordx4 v[196:197], off
	v_lshl_add_u64 v[196:197], s[22:23], 0, v[134:135]
	s_mov_b32 m0, s49
	s_nop 0
	global_load_lds_dwordx4 v[196:197], off
	v_lshl_add_u64 v[196:197], v[222:223], 0, s[14:15]
	s_mov_b32 m0, s46
	s_nop 0
	global_load_lds_dwordx4 v[196:197], off
	v_lshl_add_u64 v[196:197], v[224:225], 0, s[14:15]
	s_mov_b32 m0, s47
	s_nop 0
	global_load_lds_dwordx4 v[196:197], off
	s_waitcnt vmcnt(8)
	s_waitcnt lgkmcnt(0)
	s_barrier
	s_waitcnt lgkmcnt(0)
	v_mfma_f32_16x16x32_bf16 v[60:63], v[144:147], v[184:187], v[60:63]
	v_mfma_f32_16x16x32_bf16 v[56:59], v[160:163], v[184:187], v[56:59]
	v_mfma_f32_16x16x32_bf16 v[44:47], v[144:147], v[192:195], v[44:47]
	v_mfma_f32_16x16x32_bf16 v[40:43], v[160:163], v[192:195], v[40:43]
	v_mfma_f32_16x16x32_bf16 v[28:31], v[144:147], v[204:207], v[28:31]
	v_mfma_f32_16x16x32_bf16 v[24:27], v[160:163], v[204:207], v[24:27]
	v_mfma_f32_16x16x32_bf16 v[12:15], v[144:147], v[212:215], v[12:15]
	v_mfma_f32_16x16x32_bf16 v[8:11], v[160:163], v[212:215], v[8:11]
	v_mfma_f32_16x16x32_bf16 v[60:63], v[156:159], v[188:191], v[60:63]
	v_mfma_f32_16x16x32_bf16 v[56:59], v[164:167], v[188:191], v[56:59]
	v_mfma_f32_16x16x32_bf16 v[44:47], v[156:159], v[200:203], v[44:47]
	v_mfma_f32_16x16x32_bf16 v[40:43], v[164:167], v[200:203], v[40:43]
	v_mfma_f32_16x16x32_bf16 v[28:31], v[156:159], v[208:211], v[28:31]
	v_mfma_f32_16x16x32_bf16 v[24:27], v[164:167], v[208:211], v[24:27]
	v_mfma_f32_16x16x32_bf16 v[12:15], v[156:159], v[216:219], v[12:15]
	v_mfma_f32_16x16x32_bf16 v[8:11], v[164:167], v[216:219], v[8:11]
	v_mfma_f32_16x16x32_bf16 v[52:55], v[168:171], v[184:187], v[52:55]
	v_mfma_f32_16x16x32_bf16 v[48:51], v[176:179], v[184:187], v[48:51]
	v_mfma_f32_16x16x32_bf16 v[36:39], v[168:171], v[192:195], v[36:39]
	v_mfma_f32_16x16x32_bf16 v[32:35], v[176:179], v[192:195], v[32:35]
	v_mfma_f32_16x16x32_bf16 v[20:23], v[168:171], v[204:207], v[20:23]
	v_mfma_f32_16x16x32_bf16 v[16:19], v[176:179], v[204:207], v[16:19]
	v_mfma_f32_16x16x32_bf16 v[4:7], v[168:171], v[212:215], v[4:7]
	v_mfma_f32_16x16x32_bf16 v[0:3], v[176:179], v[212:215], v[0:3]
	v_mfma_f32_16x16x32_bf16 v[52:55], v[172:175], v[188:191], v[52:55]
	v_mfma_f32_16x16x32_bf16 v[48:51], v[180:183], v[188:191], v[48:51]
	v_mfma_f32_16x16x32_bf16 v[36:39], v[172:175], v[200:203], v[36:39]
	v_mfma_f32_16x16x32_bf16 v[32:35], v[180:183], v[200:203], v[32:35]
	v_mfma_f32_16x16x32_bf16 v[20:23], v[172:175], v[208:211], v[20:23]
	v_mfma_f32_16x16x32_bf16 v[16:19], v[180:183], v[208:211], v[16:19]
	v_mfma_f32_16x16x32_bf16 v[4:7], v[172:175], v[216:219], v[4:7]
	v_mfma_f32_16x16x32_bf16 v[0:3], v[180:183], v[216:219], v[0:3]
	s_barrier
	s_add_i32 s59, s59, 2
	s_add_u32 s57, s57, 0x100
	s_addc_u32 s58, s58, 0
	s_cmp_gt_u32 s59, 41
	s_mov_b64 s[22:23], s[24:25]
	s_cbranch_scc0 .LBB0_353
	s_and_b64 vcc, exec, s[16:17]
	s_cbranch_vccnz .LBB0_357
	s_andn2_b64 vcc, exec, s[18:19]
	s_cbranch_vccz .LBB0_358

; #define PG8_STAGE(bufoff, gbase, voff) do { _Pragma("unroll") for (int _i = 0; _i < 2; ++_i) \
;         __builtin_amdgcn_global_load_lds((const unsigned*)((const char*)(gbase) + (voff)[_i]), (PG8_LAS unsigned*)(lds + (bufoff) + ldsw + _i * 8192), 16, 0, 0); } while (0)
; #define PG8_LDA(dst, b, h) do { _Pragma("unroll") for (int m = 0; m < 4; ++m) _Pragma("unroll") for (int k = 0; k < 2; ++k) dst[m][k] = *(const PG8_LAS bf16x8*)(lds + PG8_SA(b, h) + aoff + m * 2048 + k * 1024); } while (0)
; #define PG8_LDB(dst, b, h) do { _Pragma("unroll") for (int n = 0; n < 2; ++n) _Pragma("unroll") for (int k = 0; k < 2; ++k) dst[n][k] = *(const PG8_LAS bf16x8*)(lds + PG8_SB(b, h) + boff + n * 2048 + k * 1024); } while (0)
; #define PG8_MMA(ai, bj, At, Bt) do { __builtin_amdgcn_s_setprio(1); _Pragma("unroll") for (int m = 0; m < 4; ++m) _Pragma("unroll") for (int n = 0; n < 2; ++n) _Pragma("unroll") for (int k = 0; k < 2; ++k) \
;         acc[ai][bj][m][n] = __builtin_amdgcn_mfma_f32_16x16x32_bf16(Bt[n][k], At[m][k], acc[ai][bj][m][n], 0, 0, 0); __builtin_amdgcn_s_setprio(0); } while (0)
; #define PG8_WAIT_V(n) asm volatile("s_waitcnt vmcnt(" #n ")" ::: "memory")
; #define PG8_WAIT_L(n) asm volatile("s_waitcnt lgkmcnt(" #n ")" ::: "memory")
; template <class Epi, class Sched, bool ALIGN_EPI = false, bool SP2 = false>
; __device__ __forceinline__ void gemm_phase(PG8_LAS unsigned char* lds, const Gemm g, const Sched& S, const Epi& E, const int tid) {
;     ...
;             const bool last = (t == nt - 2);
;             const char* a1 = cA + (size_t)(t + 1) * kstep;
;             const char* a2 = last ? nA : cA + (size_t)(t + 2) * kstep; const char* b2 = last ? nB : cB + (size_t)(t + 2) * kstep;
;             const char* a3 = a2 + kstep; const char* b3 = b2 + kstep;
;             if (last && has_next) S.a_ready(nxt);
;             if constexpr (SP2) {
;             PG8_LDB(B0, 0, 0); PG8_LDB(B1, 0, 1); PG8_SCHED; PG8_LDA(At, 0, 0); PG8_STAGE(PG8_SA(1, 1), a1 + hstepA, voffA);
;             PG8_WAIT_V(8); PG8_WAIT_L(0); PG8_BAR; PG8_MMA(0, 0, At, B0); PG8_MMA(0, 1, At, B1); PG8_BAR; PG8_SCHED;
;             PG8_LDA(At, 0, 1); PG8_STAGE(PG8_SB(0, 0), b2, voffB); PG8_STAGE(PG8_SB(0, 1), b2 + hstep, voffB); PG8_STAGE(PG8_SA(0, 0), a2, voffA);
;             PG8_WAIT_V(8); PG8_WAIT_L(0); PG8_BAR; PG8_MMA(1, 0, At, B0); PG8_MMA(1, 1, At, B1); PG8_BAR; PG8_SCHED;
.LBB0_437:
	ds_read_b128 v[152:155], v174
	ds_read_b128 v[156:159], v174 offset:1024
	ds_read_b128 v[160:163], v174 offset:2048
	ds_read_b128 v[164:167], v174 offset:3072
	ds_read_b128 v[168:171], v175
	ds_read_b128 v[182:185], v175 offset:1024
	ds_read_b128 v[186:189], v175 offset:2048
	ds_read_b128 v[190:193], v175 offset:3072
	s_add_u32 s34, s30, 0xfffc0080
	s_addc_u32 s35, s31, -1
	s_cmp_eq_u32 s39, 12
	s_cselect_b32 s37, s0, s35
	s_cselect_b32 s36, s21, s34
	s_cselect_b32 s35, s23, s38
	s_cselect_b32 s34, s25, s33
	v_lshl_add_u64 v[172:173], s[30:31], 0, v[142:143]
	s_add_i32 m0, s57, 0xc000
	ds_read_b128 v[194:197], v176
	ds_read_b128 v[200:203], v176 offset:1024
	ds_read_b128 v[204:207], v176 offset:2048
	ds_read_b128 v[208:211], v176 offset:3072
	ds_read_b128 v[212:215], v176 offset:4096
	ds_read_b128 v[216:219], v176 offset:5120
	ds_read_b128 v[220:223], v176 offset:6144
	ds_read_b128 v[224:227], v176 offset:7168
	global_load_lds_dwordx4 v[172:173], off
	v_lshl_add_u64 v[172:173], s[30:31], 0, v[144:145]
	s_add_i32 m0, s57, 0xe000
	s_nop 0
	global_load_lds_dwordx4 v[172:173], off
	s_waitcnt vmcnt(8)
	s_waitcnt lgkmcnt(0)
	s_barrier
	s_waitcnt lgkmcnt(0)
	v_mfma_f32_16x16x32_bf16 v[124:127], v[152:155], v[194:197], v[124:127]
	v_mfma_f32_16x16x32_bf16 v[120:123], v[160:163], v[194:197], v[120:123]
	v_mfma_f32_16x16x32_bf16 v[108:111], v[152:155], v[204:207], v[108:111]
	v_mfma_f32_16x16x32_bf16 v[104:107], v[160:163], v[204:207], v[104:107]
	v_mfma_f32_16x16x32_bf16 v[92:95], v[152:155], v[212:215], v[92:95]
	v_mfma_f32_16x16x32_bf16 v[88:91], v[160:163], v[212:215], v[88:91]
	v_mfma_f32_16x16x32_bf16 v[76:79], v[152:155], v[220:223], v[76:79]
	v_mfma_f32_16x16x32_bf16 v[72:75], v[160:163], v[220:223], v[72:75]
	v_mfma_f32_16x16x32_bf16 v[124:127], v[156:159], v[200:203], v[124:127]
	v_mfma_f32_16x16x32_bf16 v[120:123], v[164:167], v[200:203], v[120:123]
	v_mfma_f32_16x16x32_bf16 v[108:111], v[156:159], v[208:211], v[108:111]
	v_mfma_f32_16x16x32_bf16 v[104:107], v[164:167], v[208:211], v[104:107]
	v_mfma_f32_16x16x32_bf16 v[92:95], v[156:159], v[216:219], v[92:95]
	v_mfma_f32_16x16x32_bf16 v[88:91], v[164:167], v[216:219], v[88:91]
	v_mfma_f32_16x16x32_bf16 v[76:79], v[156:159], v[224:227], v[76:79]
	v_mfma_f32_16x16x32_bf16 v[72:75], v[164:167], v[224:227], v[72:75]
	v_mfma_f32_16x16x32_bf16 v[116:119], v[168:171], v[194:197], v[116:119]
	v_mfma_f32_16x16x32_bf16 v[112:115], v[186:189], v[194:197], v[112:115]
	v_mfma_f32_16x16x32_bf16 v[100:103], v[168:171], v[204:207], v[100:103]
	v_mfma_f32_16x16x32_bf16 v[96:99], v[186:189], v[204:207], v[96:99]
	v_mfma_f32_16x16x32_bf16 v[84:87], v[168:171], v[212:215], v[84:87]
	v_mfma_f32_16x16x32_bf16 v[80:83], v[186:189], v[212:215], v[80:83]
	v_mfma_f32_16x16x32_bf16 v[68:71], v[168:171], v[220:223], v[68:71]
	v_mfma_f32_16x16x32_bf16 v[64:67], v[186:189], v[220:223], v[64:67]
	v_mfma_f32_16x16x32_bf16 v[116:119], v[182:185], v[200:203], v[116:119]
	v_mfma_f32_16x16x32_bf16 v[112:115], v[190:193], v[200:203], v[112:115]
	v_mfma_f32_16x16x32_bf16 v[100:103], v[182:185], v[208:211], v[100:103]
	v_mfma_f32_16x16x32_bf16 v[96:99], v[190:193], v[208:211], v[96:99]
	v_mfma_f32_16x16x32_bf16 v[84:87], v[182:185], v[216:219], v[84:87]
	v_mfma_f32_16x16x32_bf16 v[80:83], v[190:193], v[216:219], v[80:83]
	v_mfma_f32_16x16x32_bf16 v[68:71], v[182:185], v[224:227], v[68:71]
	v_mfma_f32_16x16x32_bf16 v[64:67], v[190:193], v[224:227], v[64:67]
	s_barrier
	s_mov_b32 m0, s53
	v_lshl_add_u64 v[172:173], s[34:35], 0, v[132:133]
	s_add_u32 s44, s34, 0x40000
	ds_read_b128 v[194:197], v176 offset:16384
	ds_read_b128 v[200:203], v176 offset:17408
	ds_read_b128 v[204:207], v176 offset:18432
	ds_read_b128 v[208:211], v176 offset:19456
	ds_read_b128 v[212:215], v176 offset:20480
	ds_read_b128 v[216:219], v176 offset:21504
	ds_read_b128 v[220:223], v176 offset:22528
	ds_read_b128 v[224:227], v176 offset:23552
	global_load_lds_dwordx4 v[172:173], off
	v_lshl_add_u64 v[228:229], s[34:35], 0, v[128:129]
	s_mov_b32 m0, s54
	s_addc_u32 s45, s35, 0
	global_load_lds_dwordx4 v[228:229], off
	v_lshl_add_u64 v[230:231], s[44:45], 0, v[132:133]
	s_mov_b32 m0, s55
	v_lshl_add_u64 v[232:233], s[36:37], 0, v[130:131]
	global_load_lds_dwordx4 v[230:231], off
	v_lshl_add_u64 v[230:231], s[44:45], 0, v[128:129]
	s_mov_b32 m0, s56
	s_nop 0
	global_load_lds_dwordx4 v[230:231], off
	v_lshl_add_u64 v[230:231], s[36:37], 0, v[134:135]
	s_mov_b32 m0, s57
	s_nop 0
	global_load_lds_dwordx4 v[230:231], off
	s_mov_b32 m0, s58
	s_nop 0
	global_load_lds_dwordx4 v[232:233], off
	s_waitcnt vmcnt(8)
	s_waitcnt lgkmcnt(0)
	s_barrier
; #define PG8_STAGE(bufoff, gbase, voff) do { _Pragma("unroll") for (int _i = 0; _i < 2; ++_i) \
;         __builtin_amdgcn_global_load_lds((const unsigned*)((const char*)(gbase) + (voff)[_i]), (PG8_LAS unsigned*)(lds + (bufoff) + ldsw + _i * 8192), 16, 0, 0); } while (0)
; #define PG8_LDA(dst, b, h) do { _Pragma("unroll") for (int m = 0; m < 4; ++m) _Pragma("unroll") for (int k = 0; k < 2; ++k) dst[m][k] = *(const PG8_LAS bf16x8*)(lds + PG8_SA(b, h) + aoff + m * 2048 + k * 1024); } while (0)
; #define PG8_LDB(dst, b, h) do { _Pragma("unroll") for (int n = 0; n < 2; ++n) _Pragma("unroll") for (int k = 0; k < 2; ++k) dst[n][k] = *(const PG8_LAS bf16x8*)(lds + PG8_SB(b, h) + boff + n * 2048 + k * 1024); } while (0)
; #define PG8_MMA(ai, bj, At, Bt) do { __builtin_amdgcn_s_setprio(1); _Pragma("unroll") for (int m = 0; m < 4; ++m) _Pragma("unroll") for (int n = 0; n < 2; ++n) _Pragma("unroll") for (int k = 0; k < 2; ++k) \
;         acc[ai][bj][m][n] = __builtin_amdgcn_mfma_f32_16x16x32_bf16(Bt[n][k], At[m][k], acc[ai][bj][m][n], 0, 0, 0); __builtin_amdgcn_s_setprio(0); } while (0)
; #define PG8_WAIT_V(n) asm volatile("s_waitcnt vmcnt(" #n ")" ::: "memory")
; #define PG8_WAIT_L(n) asm volatile("s_waitcnt lgkmcnt(" #n ")" ::: "memory")
; #define PG8_BAR __builtin_amdgcn_s_barrier()
; #define PG8_SCHED __builtin_amdgcn_sched_barrier(0)
; template <class Epi, class Sched, bool ALIGN_EPI = false, bool SP2 = false>
; __device__ __forceinline__ void gemm_phase(PG8_LAS unsigned char* lds, const Gemm g, const Sched& S, const Epi& E, const int tid) {
;     ...
;             PG8_WAIT_V(8); PG8_WAIT_L(0); PG8_BAR; PG8_MMA(1, 0, At, B0); PG8_MMA(1, 1, At, B1); PG8_BAR; PG8_SCHED;
;             PG8_LDB(B0, 1, 0); PG8_LDB(B1, 1, 1); PG8_SCHED; PG8_LDA(At, 1, 0); PG8_STAGE(PG8_SA(0, 1), a2 + hstepA, voffA);
;             PG8_WAIT_V(8); PG8_WAIT_L(0); PG8_BAR; PG8_MMA(0, 0, At, B0); PG8_MMA(0, 1, At, B1); PG8_BAR; PG8_SCHED;
	s_waitcnt lgkmcnt(0)
	v_mfma_f32_16x16x32_bf16 v[60:63], v[152:155], v[194:197], v[60:63]
	v_mfma_f32_16x16x32_bf16 v[56:59], v[160:163], v[194:197], v[56:59]
	v_mfma_f32_16x16x32_bf16 v[44:47], v[152:155], v[204:207], v[44:47]
	v_mfma_f32_16x16x32_bf16 v[40:43], v[160:163], v[204:207], v[40:43]
	v_mfma_f32_16x16x32_bf16 v[28:31], v[152:155], v[212:215], v[28:31]
	v_mfma_f32_16x16x32_bf16 v[24:27], v[160:163], v[212:215], v[24:27]
	v_mfma_f32_16x16x32_bf16 v[12:15], v[152:155], v[220:223], v[12:15]
	v_mfma_f32_16x16x32_bf16 v[8:11], v[160:163], v[220:223], v[8:11]
	v_mfma_f32_16x16x32_bf16 v[60:63], v[156:159], v[200:203], v[60:63]
	v_mfma_f32_16x16x32_bf16 v[56:59], v[164:167], v[200:203], v[56:59]
	v_mfma_f32_16x16x32_bf16 v[44:47], v[156:159], v[208:211], v[44:47]
	v_mfma_f32_16x16x32_bf16 v[40:43], v[164:167], v[208:211], v[40:43]
	v_mfma_f32_16x16x32_bf16 v[28:31], v[156:159], v[216:219], v[28:31]
	v_mfma_f32_16x16x32_bf16 v[24:27], v[164:167], v[216:219], v[24:27]
	v_mfma_f32_16x16x32_bf16 v[12:15], v[156:159], v[224:227], v[12:15]
	v_mfma_f32_16x16x32_bf16 v[8:11], v[164:167], v[224:227], v[8:11]
	v_mfma_f32_16x16x32_bf16 v[52:55], v[168:171], v[194:197], v[52:55]
	v_mfma_f32_16x16x32_bf16 v[48:51], v[186:189], v[194:197], v[48:51]
	v_mfma_f32_16x16x32_bf16 v[36:39], v[168:171], v[204:207], v[36:39]
	v_mfma_f32_16x16x32_bf16 v[32:35], v[186:189], v[204:207], v[32:35]
	v_mfma_f32_16x16x32_bf16 v[20:23], v[168:171], v[212:215], v[20:23]
	v_mfma_f32_16x16x32_bf16 v[16:19], v[186:189], v[212:215], v[16:19]
	v_mfma_f32_16x16x32_bf16 v[4:7], v[168:171], v[220:223], v[4:7]
	v_mfma_f32_16x16x32_bf16 v[0:3], v[186:189], v[220:223], v[0:3]
	v_mfma_f32_16x16x32_bf16 v[52:55], v[182:185], v[200:203], v[52:55]
	v_mfma_f32_16x16x32_bf16 v[48:51], v[190:193], v[200:203], v[48:51]
	v_mfma_f32_16x16x32_bf16 v[36:39], v[182:185], v[208:211], v[36:39]
	v_mfma_f32_16x16x32_bf16 v[32:35], v[190:193], v[208:211], v[32:35]
	v_mfma_f32_16x16x32_bf16 v[20:23], v[182:185], v[216:219], v[20:23]
	v_mfma_f32_16x16x32_bf16 v[16:19], v[190:193], v[216:219], v[16:19]
	v_mfma_f32_16x16x32_bf16 v[4:7], v[182:185], v[224:227], v[4:7]
	v_mfma_f32_16x16x32_bf16 v[0:3], v[190:193], v[224:227], v[0:3]
	s_barrier
	ds_read_b128 v[152:155], v177
	ds_read_b128 v[156:159], v177 offset:1024
	ds_read_b128 v[160:163], v177 offset:2048
	ds_read_b128 v[164:167], v177 offset:3072
	ds_read_b128 v[168:171], v178
	ds_read_b128 v[182:185], v178 offset:1024
	ds_read_b128 v[186:189], v178 offset:2048
	ds_read_b128 v[190:193], v178 offset:3072
	s_add_u32 s36, s36, 0x40000
	s_addc_u32 s37, s37, 0
	s_mov_b32 m0, s59
	v_lshl_add_u64 v[234:235], s[36:37], 0, v[134:135]
	ds_read_b128 v[194:197], v176 offset:32768
	ds_read_b128 v[200:203], v176 offset:33792
	ds_read_b128 v[204:207], v176 offset:34816
	ds_read_b128 v[208:211], v176 offset:35840
	ds_read_b128 v[212:215], v176 offset:36864
	ds_read_b128 v[216:219], v176 offset:37888
	ds_read_b128 v[220:223], v176 offset:38912
	ds_read_b128 v[224:227], v176 offset:39936
	global_load_lds_dwordx4 v[234:235], off
	v_lshl_add_u64 v[234:235], s[36:37], 0, v[130:131]
	s_mov_b32 m0, s60
	s_nop 0
	global_load_lds_dwordx4 v[234:235], off
	s_waitcnt vmcnt(8)
	s_waitcnt lgkmcnt(0)
	s_barrier
	s_waitcnt lgkmcnt(0)
	v_mfma_f32_16x16x32_bf16 v[124:127], v[152:155], v[194:197], v[124:127]
	v_mfma_f32_16x16x32_bf16 v[120:123], v[160:163], v[194:197], v[120:123]
	v_mfma_f32_16x16x32_bf16 v[108:111], v[152:155], v[204:207], v[108:111]
	v_mfma_f32_16x16x32_bf16 v[104:107], v[160:163], v[204:207], v[104:107]
	v_mfma_f32_16x16x32_bf16 v[92:95], v[152:155], v[212:215], v[92:95]
	v_mfma_f32_16x16x32_bf16 v[88:91], v[160:163], v[212:215], v[88:91]
	v_mfma_f32_16x16x32_bf16 v[76:79], v[152:155], v[220:223], v[76:79]
	v_mfma_f32_16x16x32_bf16 v[72:75], v[160:163], v[220:223], v[72:75]
	v_mfma_f32_16x16x32_bf16 v[124:127], v[156:159], v[200:203], v[124:127]
	v_mfma_f32_16x16x32_bf16 v[120:123], v[164:167], v[200:203], v[120:123]
	v_mfma_f32_16x16x32_bf16 v[108:111], v[156:159], v[208:211], v[108:111]
	v_mfma_f32_16x16x32_bf16 v[104:107], v[164:167], v[208:211], v[104:107]
	v_mfma_f32_16x16x32_bf16 v[92:95], v[156:159], v[216:219], v[92:95]
	v_mfma_f32_16x16x32_bf16 v[88:91], v[164:167], v[216:219], v[88:91]
	v_mfma_f32_16x16x32_bf16 v[76:79], v[156:159], v[224:227], v[76:79]
	v_mfma_f32_16x16x32_bf16 v[72:75], v[164:167], v[224:227], v[72:75]
	v_mfma_f32_16x16x32_bf16 v[116:119], v[168:171], v[194:197], v[116:119]
	v_mfma_f32_16x16x32_bf16 v[112:115], v[186:189], v[194:197], v[112:115]
	v_mfma_f32_16x16x32_bf16 v[100:103], v[168:171], v[204:207], v[100:103]
	v_mfma_f32_16x16x32_bf16 v[96:99], v[186:189], v[204:207], v[96:99]
	v_mfma_f32_16x16x32_bf16 v[84:87], v[168:171], v[212:215], v[84:87]
	v_mfma_f32_16x16x32_bf16 v[80:83], v[186:189], v[212:215], v[80:83]
	v_mfma_f32_16x16x32_bf16 v[68:71], v[168:171], v[220:223], v[68:71]
	v_mfma_f32_16x16x32_bf16 v[64:67], v[186:189], v[220:223], v[64:67]
	v_mfma_f32_16x16x32_bf16 v[116:119], v[182:185], v[200:203], v[116:119]
	v_mfma_f32_16x16x32_bf16 v[112:115], v[190:193], v[200:203], v[112:115]
	v_mfma_f32_16x16x32_bf16 v[100:103], v[182:185], v[208:211], v[100:103]
	v_mfma_f32_16x16x32_bf16 v[96:99], v[190:193], v[208:211], v[96:99]
	v_mfma_f32_16x16x32_bf16 v[84:87], v[182:185], v[216:219], v[84:87]
	v_mfma_f32_16x16x32_bf16 v[80:83], v[190:193], v[216:219], v[80:83]
	v_mfma_f32_16x16x32_bf16 v[68:71], v[182:185], v[224:227], v[68:71]
	v_mfma_f32_16x16x32_bf16 v[64:67], v[190:193], v[224:227], v[64:67]
	s_barrier
; #define PG8_STAGE(bufoff, gbase, voff) do { _Pragma("unroll") for (int _i = 0; _i < 2; ++_i) \
;         __builtin_amdgcn_global_load_lds((const unsigned*)((const char*)(gbase) + (voff)[_i]), (PG8_LAS unsigned*)(lds + (bufoff) + ldsw + _i * 8192), 16, 0, 0); } while (0)
; #define PG8_LDA(dst, b, h) do { _Pragma("unroll") for (int m = 0; m < 4; ++m) _Pragma("unroll") for (int k = 0; k < 2; ++k) dst[m][k] = *(const PG8_LAS bf16x8*)(lds + PG8_SA(b, h) + aoff + m * 2048 + k * 1024); } while (0)
; #define PG8_MMA(ai, bj, At, Bt) do { __builtin_amdgcn_s_setprio(1); _Pragma("unroll") for (int m = 0; m < 4; ++m) _Pragma("unroll") for (int n = 0; n < 2; ++n) _Pragma("unroll") for (int k = 0; k < 2; ++k) \
;         acc[ai][bj][m][n] = __builtin_amdgcn_mfma_f32_16x16x32_bf16(Bt[n][k], At[m][k], acc[ai][bj][m][n], 0, 0, 0); __builtin_amdgcn_s_setprio(0); } while (0)
; #define PG8_WAIT_V(n) asm volatile("s_waitcnt vmcnt(" #n ")" ::: "memory")
; #define PG8_WAIT_L(n) asm volatile("s_waitcnt lgkmcnt(" #n ")" ::: "memory")
; #define PG8_BAR __builtin_amdgcn_s_barrier()
; #define PG8_SCHED __builtin_amdgcn_sched_barrier(0)
; template <class Epi, class Sched, bool ALIGN_EPI = false, bool SP2 = false>
; __device__ __forceinline__ void gemm_phase(PG8_LAS unsigned char* lds, const Gemm g, const Sched& S, const Epi& E, const int tid) {
;     ...
;             PG8_LDA(At, 1, 1); PG8_STAGE(PG8_SB(1, 0), b3, voffB); PG8_STAGE(PG8_SB(1, 1), b3 + hstep, voffB); PG8_STAGE(PG8_SA(1, 0), a3, voffA);
;             PG8_WAIT_V(8); PG8_WAIT_L(0); PG8_BAR; PG8_MMA(1, 0, At, B0); PG8_MMA(1, 1, At, B1); PG8_BAR; PG8_SCHED;
	s_mov_b32 m0, s62
	v_lshl_add_u64 v[172:173], v[172:173], 0, s[16:17]
	s_add_u32 s34, s34, 0x40080
	ds_read_b128 v[194:197], v176 offset:49152
	ds_read_b128 v[200:203], v176 offset:50176
	ds_read_b128 v[204:207], v176 offset:51200
	ds_read_b128 v[208:211], v176 offset:52224
	ds_read_b128 v[212:215], v176 offset:53248
	ds_read_b128 v[216:219], v176 offset:54272
	ds_read_b128 v[220:223], v176 offset:55296
	ds_read_b128 v[224:227], v176 offset:56320
	global_load_lds_dwordx4 v[172:173], off
	v_lshl_add_u64 v[172:173], v[228:229], 0, s[16:17]
	s_mov_b32 m0, s63
	s_addc_u32 s35, s35, 0
	global_load_lds_dwordx4 v[172:173], off
	v_lshl_add_u64 v[172:173], s[34:35], 0, v[132:133]
	s_mov_b32 m0, s68
	s_nop 0
	global_load_lds_dwordx4 v[172:173], off
	v_lshl_add_u64 v[172:173], s[34:35], 0, v[128:129]
	s_mov_b32 m0, s69
	s_nop 0
	global_load_lds_dwordx4 v[172:173], off
	v_lshl_add_u64 v[172:173], v[230:231], 0, s[16:17]
	s_mov_b32 m0, s64
	s_nop 0
	global_load_lds_dwordx4 v[172:173], off
	v_lshl_add_u64 v[172:173], v[232:233], 0, s[16:17]
	s_mov_b32 m0, s65
	s_nop 0
	global_load_lds_dwordx4 v[172:173], off
	s_waitcnt vmcnt(8)
	s_waitcnt lgkmcnt(0)
	s_barrier
	s_waitcnt lgkmcnt(0)
	v_mfma_f32_16x16x32_bf16 v[60:63], v[152:155], v[194:197], v[60:63]
	v_mfma_f32_16x16x32_bf16 v[56:59], v[160:163], v[194:197], v[56:59]
	v_mfma_f32_16x16x32_bf16 v[44:47], v[152:155], v[204:207], v[44:47]
	v_mfma_f32_16x16x32_bf16 v[40:43], v[160:163], v[204:207], v[40:43]
	v_mfma_f32_16x16x32_bf16 v[28:31], v[152:155], v[212:215], v[28:31]
	v_mfma_f32_16x16x32_bf16 v[24:27], v[160:163], v[212:215], v[24:27]
	v_mfma_f32_16x16x32_bf16 v[12:15], v[152:155], v[220:223], v[12:15]
	v_mfma_f32_16x16x32_bf16 v[8:11], v[160:163], v[220:223], v[8:11]
	v_mfma_f32_16x16x32_bf16 v[60:63], v[156:159], v[200:203], v[60:63]
	v_mfma_f32_16x16x32_bf16 v[56:59], v[164:167], v[200:203], v[56:59]
	v_mfma_f32_16x16x32_bf16 v[44:47], v[156:159], v[208:211], v[44:47]
	v_mfma_f32_16x16x32_bf16 v[40:43], v[164:167], v[208:211], v[40:43]
	v_mfma_f32_16x16x32_bf16 v[28:31], v[156:159], v[216:219], v[28:31]
	v_mfma_f32_16x16x32_bf16 v[24:27], v[164:167], v[216:219], v[24:27]
	v_mfma_f32_16x16x32_bf16 v[12:15], v[156:159], v[224:227], v[12:15]
	v_mfma_f32_16x16x32_bf16 v[8:11], v[164:167], v[224:227], v[8:11]
	v_mfma_f32_16x16x32_bf16 v[52:55], v[168:171], v[194:197], v[52:55]
	v_mfma_f32_16x16x32_bf16 v[48:51], v[186:189], v[194:197], v[48:51]
	v_mfma_f32_16x16x32_bf16 v[36:39], v[168:171], v[204:207], v[36:39]
	v_mfma_f32_16x16x32_bf16 v[32:35], v[186:189], v[204:207], v[32:35]
	v_mfma_f32_16x16x32_bf16 v[20:23], v[168:171], v[212:215], v[20:23]
	v_mfma_f32_16x16x32_bf16 v[16:19], v[186:189], v[212:215], v[16:19]
	v_mfma_f32_16x16x32_bf16 v[4:7], v[168:171], v[220:223], v[4:7]
	v_mfma_f32_16x16x32_bf16 v[0:3], v[186:189], v[220:223], v[0:3]
	v_mfma_f32_16x16x32_bf16 v[52:55], v[182:185], v[200:203], v[52:55]
	v_mfma_f32_16x16x32_bf16 v[48:51], v[190:193], v[200:203], v[48:51]
	v_mfma_f32_16x16x32_bf16 v[36:39], v[182:185], v[208:211], v[36:39]
	v_mfma_f32_16x16x32_bf16 v[32:35], v[190:193], v[208:211], v[32:35]
	v_mfma_f32_16x16x32_bf16 v[20:23], v[182:185], v[216:219], v[20:23]
	v_mfma_f32_16x16x32_bf16 v[16:19], v[190:193], v[216:219], v[16:19]
	v_mfma_f32_16x16x32_bf16 v[4:7], v[182:185], v[224:227], v[4:7]
	v_mfma_f32_16x16x32_bf16 v[0:3], v[190:193], v[224:227], v[0:3]
	s_barrier
	s_add_i32 s39, s39, 2
	s_add_u32 s30, s30, 0x100
	s_addc_u32 s31, s31, 0
	s_add_u32 s33, s33, 0x100
	s_addc_u32 s38, s38, 0
	s_cmp_gt_u32 s39, 13
	s_cbranch_scc0 .LBB0_437
	s_and_b64 vcc, exec, s[18:19]
	s_cbranch_vccz .LBB0_440
	s_barrier

; #define PG8_STAGE(bufoff, gbase, voff) do { _Pragma("unroll") for (int _i = 0; _i < 2; ++_i) \
;         __builtin_amdgcn_global_load_lds((const unsigned*)((const char*)(gbase) + (voff)[_i]), (PG8_LAS unsigned*)(lds + (bufoff) + ldsw + _i * 8192), 16, 0, 0); } while (0)
; #define PG8_LDA(dst, b, h) do { _Pragma("unroll") for (int m = 0; m < 4; ++m) _Pragma("unroll") for (int k = 0; k < 2; ++k) dst[m][k] = *(const PG8_LAS bf16x8*)(lds + PG8_SA(b, h) + aoff + m * 2048 + k * 1024); } while (0)
; #define PG8_LDB(dst, b, h) do { _Pragma("unroll") for (int n = 0; n < 2; ++n) _Pragma("unroll") for (int k = 0; k < 2; ++k) dst[n][k] = *(const PG8_LAS bf16x8*)(lds + PG8_SB(b, h) + boff + n * 2048 + k * 1024); } while (0)
; #define PG8_MMA(ai, bj, At, Bt) do { __builtin_amdgcn_s_setprio(1); _Pragma("unroll") for (int m = 0; m < 4; ++m) _Pragma("unroll") for (int n = 0; n < 2; ++n) _Pragma("unroll") for (int k = 0; k < 2; ++k) \
;         acc[ai][bj][m][n] = __builtin_amdgcn_mfma_f32_16x16x32_bf16(Bt[n][k], At[m][k], acc[ai][bj][m][n], 0, 0, 0); __builtin_amdgcn_s_setprio(0); } while (0)
; #define PG8_WAIT_V(n) asm volatile("s_waitcnt vmcnt(" #n ")" ::: "memory")
; #define PG8_WAIT_L(n) asm volatile("s_waitcnt lgkmcnt(" #n ")" ::: "memory")
; template <class Epi, class Sched, bool ALIGN_EPI = false, bool SP2 = false>
; __device__ __forceinline__ void gemm_phase(PG8_LAS unsigned char* lds, const Gemm g, const Sched& S, const Epi& E, const int tid) {
;     ...
;             const bool last = (t == nt - 2);
;             const char* a1 = cA + (size_t)(t + 1) * kstep;
;             const char* a2 = last ? nA : cA + (size_t)(t + 2) * kstep; const char* b2 = last ? nB : cB + (size_t)(t + 2) * kstep;
;             const char* a3 = a2 + kstep; const char* b3 = b2 + kstep;
;             if (last && has_next) S.a_ready(nxt);
;             if constexpr (SP2) {
;             PG8_LDB(B0, 0, 0); PG8_LDB(B1, 0, 1); PG8_SCHED; PG8_LDA(At, 0, 0); PG8_STAGE(PG8_SA(1, 1), a1 + hstepA, voffA);
;             PG8_WAIT_V(8); PG8_WAIT_L(0); PG8_BAR; PG8_MMA(0, 0, At, B0); PG8_MMA(0, 1, At, B1); PG8_BAR; PG8_SCHED;
;             PG8_LDA(At, 0, 1); PG8_STAGE(PG8_SB(0, 0), b2, voffB); PG8_STAGE(PG8_SB(0, 1), b2 + hstep, voffB); PG8_STAGE(PG8_SA(0, 0), a2, voffA);
;             PG8_WAIT_V(8); PG8_WAIT_L(0); PG8_BAR; PG8_MMA(1, 0, At, B0); PG8_MMA(1, 1, At, B1); PG8_BAR; PG8_SCHED;
.LBB0_765:
	ds_read_b128 v[144:147], v150
	ds_read_b128 v[156:159], v150 offset:1024
	ds_read_b128 v[160:163], v150 offset:2048
	ds_read_b128 v[164:167], v150 offset:3072
	ds_read_b128 v[168:171], v151
	ds_read_b128 v[172:175], v151 offset:1024
	ds_read_b128 v[176:179], v151 offset:2048
	ds_read_b128 v[180:183], v151 offset:3072
	s_add_u32 s6, s28, 0x100
	s_addc_u32 s7, s29, 0
	s_cmp_eq_u32 s61, 12
	s_cselect_b32 s35, s23, s7
	s_cselect_b32 s34, s22, s6
	s_cselect_b32 s31, s21, s60
	s_cselect_b32 s30, s58, s59
	v_lshl_add_u64 v[196:197], s[28:29], 0, v[136:137]
	s_add_i32 m0, s41, 0xc000
	ds_read_b128 v[184:187], v152
	ds_read_b128 v[188:191], v152 offset:1024
	ds_read_b128 v[192:195], v152 offset:2048
	ds_read_b128 v[200:203], v152 offset:3072
	ds_read_b128 v[204:207], v152 offset:4096
	ds_read_b128 v[208:211], v152 offset:5120
	ds_read_b128 v[212:215], v152 offset:6144
	ds_read_b128 v[216:219], v152 offset:7168
	global_load_lds_dwordx4 v[196:197], off
	v_lshl_add_u64 v[196:197], s[28:29], 0, v[138:139]
	s_add_i32 m0, s41, 0xe000
	s_nop 0
	global_load_lds_dwordx4 v[196:197], off
	s_waitcnt vmcnt(8)
	s_waitcnt lgkmcnt(0)
	s_barrier
	s_waitcnt lgkmcnt(0)
	v_mfma_f32_16x16x32_bf16 v[124:127], v[144:147], v[184:187], v[124:127]
	v_mfma_f32_16x16x32_bf16 v[120:123], v[160:163], v[184:187], v[120:123]
	v_mfma_f32_16x16x32_bf16 v[108:111], v[144:147], v[192:195], v[108:111]
	v_mfma_f32_16x16x32_bf16 v[104:107], v[160:163], v[192:195], v[104:107]
	v_mfma_f32_16x16x32_bf16 v[92:95], v[144:147], v[204:207], v[92:95]
	v_mfma_f32_16x16x32_bf16 v[88:91], v[160:163], v[204:207], v[88:91]
	v_mfma_f32_16x16x32_bf16 v[76:79], v[144:147], v[212:215], v[76:79]
	v_mfma_f32_16x16x32_bf16 v[72:75], v[160:163], v[212:215], v[72:75]
	v_mfma_f32_16x16x32_bf16 v[124:127], v[156:159], v[188:191], v[124:127]
	v_mfma_f32_16x16x32_bf16 v[120:123], v[164:167], v[188:191], v[120:123]
	v_mfma_f32_16x16x32_bf16 v[108:111], v[156:159], v[200:203], v[108:111]
	v_mfma_f32_16x16x32_bf16 v[104:107], v[164:167], v[200:203], v[104:107]
	v_mfma_f32_16x16x32_bf16 v[92:95], v[156:159], v[208:211], v[92:95]
	v_mfma_f32_16x16x32_bf16 v[88:91], v[164:167], v[208:211], v[88:91]
	v_mfma_f32_16x16x32_bf16 v[76:79], v[156:159], v[216:219], v[76:79]
	v_mfma_f32_16x16x32_bf16 v[72:75], v[164:167], v[216:219], v[72:75]
	v_mfma_f32_16x16x32_bf16 v[116:119], v[168:171], v[184:187], v[116:119]
	v_mfma_f32_16x16x32_bf16 v[112:115], v[176:179], v[184:187], v[112:115]
	v_mfma_f32_16x16x32_bf16 v[100:103], v[168:171], v[192:195], v[100:103]
	v_mfma_f32_16x16x32_bf16 v[96:99], v[176:179], v[192:195], v[96:99]
	v_mfma_f32_16x16x32_bf16 v[84:87], v[168:171], v[204:207], v[84:87]
	v_mfma_f32_16x16x32_bf16 v[80:83], v[176:179], v[204:207], v[80:83]
	v_mfma_f32_16x16x32_bf16 v[68:71], v[168:171], v[212:215], v[68:71]
	v_mfma_f32_16x16x32_bf16 v[64:67], v[176:179], v[212:215], v[64:67]
	v_mfma_f32_16x16x32_bf16 v[116:119], v[172:175], v[188:191], v[116:119]
	v_mfma_f32_16x16x32_bf16 v[112:115], v[180:183], v[188:191], v[112:115]
	v_mfma_f32_16x16x32_bf16 v[100:103], v[172:175], v[200:203], v[100:103]
	v_mfma_f32_16x16x32_bf16 v[96:99], v[180:183], v[200:203], v[96:99]
	v_mfma_f32_16x16x32_bf16 v[84:87], v[172:175], v[208:211], v[84:87]
	v_mfma_f32_16x16x32_bf16 v[80:83], v[180:183], v[208:211], v[80:83]
	v_mfma_f32_16x16x32_bf16 v[68:71], v[172:175], v[216:219], v[68:71]
	v_mfma_f32_16x16x32_bf16 v[64:67], v[180:183], v[216:219], v[64:67]
	s_barrier
	s_mov_b32 m0, s27
	v_lshl_add_u64 v[196:197], s[30:31], 0, v[130:131]
	s_add_u32 s28, s30, 0x40000
	ds_read_b128 v[184:187], v152 offset:16384
	ds_read_b128 v[188:191], v152 offset:17408
	ds_read_b128 v[192:195], v152 offset:18432
	ds_read_b128 v[200:203], v152 offset:19456
	ds_read_b128 v[204:207], v152 offset:20480
	ds_read_b128 v[208:211], v152 offset:21504
	ds_read_b128 v[212:215], v152 offset:22528
	ds_read_b128 v[216:219], v152 offset:23552
	global_load_lds_dwordx4 v[196:197], off
	v_lshl_add_u64 v[220:221], s[30:31], 0, v[134:135]
	s_mov_b32 m0, s38
	s_addc_u32 s29, s31, 0
	global_load_lds_dwordx4 v[220:221], off
	v_lshl_add_u64 v[222:223], s[28:29], 0, v[130:131]
	s_mov_b32 m0, s39
	v_lshl_add_u64 v[224:225], s[34:35], 0, v[132:133]
	global_load_lds_dwordx4 v[222:223], off
	v_lshl_add_u64 v[222:223], s[28:29], 0, v[134:135]
	s_mov_b32 m0, s40
	s_nop 0
	global_load_lds_dwordx4 v[222:223], off
	v_lshl_add_u64 v[222:223], s[34:35], 0, v[128:129]
	s_mov_b32 m0, s41
	s_nop 0
	global_load_lds_dwordx4 v[222:223], off
	s_mov_b32 m0, s42
	s_nop 0
	global_load_lds_dwordx4 v[224:225], off
	s_waitcnt vmcnt(8)
	s_waitcnt lgkmcnt(0)
	s_barrier
; #define PG8_STAGE(bufoff, gbase, voff) do { _Pragma("unroll") for (int _i = 0; _i < 2; ++_i) \
;         __builtin_amdgcn_global_load_lds((const unsigned*)((const char*)(gbase) + (voff)[_i]), (PG8_LAS unsigned*)(lds + (bufoff) + ldsw + _i * 8192), 16, 0, 0); } while (0)
; #define PG8_LDA(dst, b, h) do { _Pragma("unroll") for (int m = 0; m < 4; ++m) _Pragma("unroll") for (int k = 0; k < 2; ++k) dst[m][k] = *(const PG8_LAS bf16x8*)(lds + PG8_SA(b, h) + aoff + m * 2048 + k * 1024); } while (0)
; #define PG8_LDB(dst, b, h) do { _Pragma("unroll") for (int n = 0; n < 2; ++n) _Pragma("unroll") for (int k = 0; k < 2; ++k) dst[n][k] = *(const PG8_LAS bf16x8*)(lds + PG8_SB(b, h) + boff + n * 2048 + k * 1024); } while (0)
; #define PG8_MMA(ai, bj, At, Bt) do { __builtin_amdgcn_s_setprio(1); _Pragma("unroll") for (int m = 0; m < 4; ++m) _Pragma("unroll") for (int n = 0; n < 2; ++n) _Pragma("unroll") for (int k = 0; k < 2; ++k) \
;         acc[ai][bj][m][n] = __builtin_amdgcn_mfma_f32_16x16x32_bf16(Bt[n][k], At[m][k], acc[ai][bj][m][n], 0, 0, 0); __builtin_amdgcn_s_setprio(0); } while (0)
; #define PG8_WAIT_V(n) asm volatile("s_waitcnt vmcnt(" #n ")" ::: "memory")
; #define PG8_WAIT_L(n) asm volatile("s_waitcnt lgkmcnt(" #n ")" ::: "memory")
; #define PG8_BAR __builtin_amdgcn_s_barrier()
; #define PG8_SCHED __builtin_amdgcn_sched_barrier(0)
; template <class Epi, class Sched, bool ALIGN_EPI = false, bool SP2 = false>
; __device__ __forceinline__ void gemm_phase(PG8_LAS unsigned char* lds, const Gemm g, const Sched& S, const Epi& E, const int tid) {
;     ...
;             PG8_WAIT_V(8); PG8_WAIT_L(0); PG8_BAR; PG8_MMA(1, 0, At, B0); PG8_MMA(1, 1, At, B1); PG8_BAR; PG8_SCHED;
;             PG8_LDB(B0, 1, 0); PG8_LDB(B1, 1, 1); PG8_SCHED; PG8_LDA(At, 1, 0); PG8_STAGE(PG8_SA(0, 1), a2 + hstepA, voffA);
;             PG8_WAIT_V(8); PG8_WAIT_L(0); PG8_BAR; PG8_MMA(0, 0, At, B0); PG8_MMA(0, 1, At, B1); PG8_BAR; PG8_SCHED;
	s_waitcnt lgkmcnt(0)
	v_mfma_f32_16x16x32_bf16 v[60:63], v[144:147], v[184:187], v[60:63]
	v_mfma_f32_16x16x32_bf16 v[56:59], v[160:163], v[184:187], v[56:59]
	v_mfma_f32_16x16x32_bf16 v[44:47], v[144:147], v[192:195], v[44:47]
	v_mfma_f32_16x16x32_bf16 v[40:43], v[160:163], v[192:195], v[40:43]
	v_mfma_f32_16x16x32_bf16 v[28:31], v[144:147], v[204:207], v[28:31]
	v_mfma_f32_16x16x32_bf16 v[24:27], v[160:163], v[204:207], v[24:27]
	v_mfma_f32_16x16x32_bf16 v[12:15], v[144:147], v[212:215], v[12:15]
	v_mfma_f32_16x16x32_bf16 v[8:11], v[160:163], v[212:215], v[8:11]
	v_mfma_f32_16x16x32_bf16 v[60:63], v[156:159], v[188:191], v[60:63]
	v_mfma_f32_16x16x32_bf16 v[56:59], v[164:167], v[188:191], v[56:59]
	v_mfma_f32_16x16x32_bf16 v[44:47], v[156:159], v[200:203], v[44:47]
	v_mfma_f32_16x16x32_bf16 v[40:43], v[164:167], v[200:203], v[40:43]
	v_mfma_f32_16x16x32_bf16 v[28:31], v[156:159], v[208:211], v[28:31]
	v_mfma_f32_16x16x32_bf16 v[24:27], v[164:167], v[208:211], v[24:27]
	v_mfma_f32_16x16x32_bf16 v[12:15], v[156:159], v[216:219], v[12:15]
	v_mfma_f32_16x16x32_bf16 v[8:11], v[164:167], v[216:219], v[8:11]
	v_mfma_f32_16x16x32_bf16 v[52:55], v[168:171], v[184:187], v[52:55]
	v_mfma_f32_16x16x32_bf16 v[48:51], v[176:179], v[184:187], v[48:51]
	v_mfma_f32_16x16x32_bf16 v[36:39], v[168:171], v[192:195], v[36:39]
	v_mfma_f32_16x16x32_bf16 v[32:35], v[176:179], v[192:195], v[32:35]
	v_mfma_f32_16x16x32_bf16 v[20:23], v[168:171], v[204:207], v[20:23]
	v_mfma_f32_16x16x32_bf16 v[16:19], v[176:179], v[204:207], v[16:19]
	v_mfma_f32_16x16x32_bf16 v[4:7], v[168:171], v[212:215], v[4:7]
	v_mfma_f32_16x16x32_bf16 v[0:3], v[176:179], v[212:215], v[0:3]
	v_mfma_f32_16x16x32_bf16 v[52:55], v[172:175], v[188:191], v[52:55]
	v_mfma_f32_16x16x32_bf16 v[48:51], v[180:183], v[188:191], v[48:51]
	v_mfma_f32_16x16x32_bf16 v[36:39], v[172:175], v[200:203], v[36:39]
	v_mfma_f32_16x16x32_bf16 v[32:35], v[180:183], v[200:203], v[32:35]
	v_mfma_f32_16x16x32_bf16 v[20:23], v[172:175], v[208:211], v[20:23]
	v_mfma_f32_16x16x32_bf16 v[16:19], v[180:183], v[208:211], v[16:19]
	v_mfma_f32_16x16x32_bf16 v[4:7], v[172:175], v[216:219], v[4:7]
	v_mfma_f32_16x16x32_bf16 v[0:3], v[180:183], v[216:219], v[0:3]
	s_barrier
	ds_read_b128 v[144:147], v153
	ds_read_b128 v[156:159], v153 offset:1024
	ds_read_b128 v[160:163], v153 offset:2048
	ds_read_b128 v[164:167], v153 offset:3072
	ds_read_b128 v[168:171], v154
	ds_read_b128 v[172:175], v154 offset:1024
	ds_read_b128 v[176:179], v154 offset:2048
	ds_read_b128 v[180:183], v154 offset:3072
	s_add_u32 s28, s34, 0xe0000
	s_addc_u32 s29, s35, 0
	s_mov_b32 m0, s43
	v_lshl_add_u64 v[226:227], s[28:29], 0, v[128:129]
	ds_read_b128 v[184:187], v152 offset:32768
	ds_read_b128 v[188:191], v152 offset:33792
	ds_read_b128 v[192:195], v152 offset:34816
	ds_read_b128 v[200:203], v152 offset:35840
	ds_read_b128 v[204:207], v152 offset:36864
	ds_read_b128 v[208:211], v152 offset:37888
	ds_read_b128 v[212:215], v152 offset:38912
	ds_read_b128 v[216:219], v152 offset:39936
	global_load_lds_dwordx4 v[226:227], off
	v_lshl_add_u64 v[226:227], s[28:29], 0, v[132:133]
	s_mov_b32 m0, s44
	s_nop 0
	global_load_lds_dwordx4 v[226:227], off
	s_waitcnt vmcnt(8)
	s_waitcnt lgkmcnt(0)
	s_barrier
	s_waitcnt lgkmcnt(0)
	v_mfma_f32_16x16x32_bf16 v[124:127], v[144:147], v[184:187], v[124:127]
	v_mfma_f32_16x16x32_bf16 v[120:123], v[160:163], v[184:187], v[120:123]
	v_mfma_f32_16x16x32_bf16 v[108:111], v[144:147], v[192:195], v[108:111]
	v_mfma_f32_16x16x32_bf16 v[104:107], v[160:163], v[192:195], v[104:107]
	v_mfma_f32_16x16x32_bf16 v[92:95], v[144:147], v[204:207], v[92:95]
	v_mfma_f32_16x16x32_bf16 v[88:91], v[160:163], v[204:207], v[88:91]
	v_mfma_f32_16x16x32_bf16 v[76:79], v[144:147], v[212:215], v[76:79]
	v_mfma_f32_16x16x32_bf16 v[72:75], v[160:163], v[212:215], v[72:75]
	v_mfma_f32_16x16x32_bf16 v[124:127], v[156:159], v[188:191], v[124:127]
	v_mfma_f32_16x16x32_bf16 v[120:123], v[164:167], v[188:191], v[120:123]
	v_mfma_f32_16x16x32_bf16 v[108:111], v[156:159], v[200:203], v[108:111]
	v_mfma_f32_16x16x32_bf16 v[104:107], v[164:167], v[200:203], v[104:107]
	v_mfma_f32_16x16x32_bf16 v[92:95], v[156:159], v[208:211], v[92:95]
	v_mfma_f32_16x16x32_bf16 v[88:91], v[164:167], v[208:211], v[88:91]
	v_mfma_f32_16x16x32_bf16 v[76:79], v[156:159], v[216:219], v[76:79]
	v_mfma_f32_16x16x32_bf16 v[72:75], v[164:167], v[216:219], v[72:75]
	v_mfma_f32_16x16x32_bf16 v[116:119], v[168:171], v[184:187], v[116:119]
	v_mfma_f32_16x16x32_bf16 v[112:115], v[176:179], v[184:187], v[112:115]
	v_mfma_f32_16x16x32_bf16 v[100:103], v[168:171], v[192:195], v[100:103]
	v_mfma_f32_16x16x32_bf16 v[96:99], v[176:179], v[192:195], v[96:99]
	v_mfma_f32_16x16x32_bf16 v[84:87], v[168:171], v[204:207], v[84:87]
	v_mfma_f32_16x16x32_bf16 v[80:83], v[176:179], v[204:207], v[80:83]
	v_mfma_f32_16x16x32_bf16 v[68:71], v[168:171], v[212:215], v[68:71]
	v_mfma_f32_16x16x32_bf16 v[64:67], v[176:179], v[212:215], v[64:67]
	v_mfma_f32_16x16x32_bf16 v[116:119], v[172:175], v[188:191], v[116:119]
	v_mfma_f32_16x16x32_bf16 v[112:115], v[180:183], v[188:191], v[112:115]
	v_mfma_f32_16x16x32_bf16 v[100:103], v[172:175], v[200:203], v[100:103]
	v_mfma_f32_16x16x32_bf16 v[96:99], v[180:183], v[200:203], v[96:99]
	v_mfma_f32_16x16x32_bf16 v[84:87], v[172:175], v[208:211], v[84:87]
	v_mfma_f32_16x16x32_bf16 v[80:83], v[180:183], v[208:211], v[80:83]
	v_mfma_f32_16x16x32_bf16 v[68:71], v[172:175], v[216:219], v[68:71]
	v_mfma_f32_16x16x32_bf16 v[64:67], v[180:183], v[216:219], v[64:67]
	s_barrier
; #define PG8_STAGE(bufoff, gbase, voff) do { _Pragma("unroll") for (int _i = 0; _i < 2; ++_i) \
;         __builtin_amdgcn_global_load_lds((const unsigned*)((const char*)(gbase) + (voff)[_i]), (PG8_LAS unsigned*)(lds + (bufoff) + ldsw + _i * 8192), 16, 0, 0); } while (0)
; #define PG8_LDA(dst, b, h) do { _Pragma("unroll") for (int m = 0; m < 4; ++m) _Pragma("unroll") for (int k = 0; k < 2; ++k) dst[m][k] = *(const PG8_LAS bf16x8*)(lds + PG8_SA(b, h) + aoff + m * 2048 + k * 1024); } while (0)
; #define PG8_MMA(ai, bj, At, Bt) do { __builtin_amdgcn_s_setprio(1); _Pragma("unroll") for (int m = 0; m < 4; ++m) _Pragma("unroll") for (int n = 0; n < 2; ++n) _Pragma("unroll") for (int k = 0; k < 2; ++k) \
;         acc[ai][bj][m][n] = __builtin_amdgcn_mfma_f32_16x16x32_bf16(Bt[n][k], At[m][k], acc[ai][bj][m][n], 0, 0, 0); __builtin_amdgcn_s_setprio(0); } while (0)
; #define PG8_WAIT_V(n) asm volatile("s_waitcnt vmcnt(" #n ")" ::: "memory")
; #define PG8_WAIT_L(n) asm volatile("s_waitcnt lgkmcnt(" #n ")" ::: "memory")
; #define PG8_BAR __builtin_amdgcn_s_barrier()
; #define PG8_SCHED __builtin_amdgcn_sched_barrier(0)
; template <class Epi, class Sched, bool ALIGN_EPI = false, bool SP2 = false>
; __device__ __forceinline__ void gemm_phase(PG8_LAS unsigned char* lds, const Gemm g, const Sched& S, const Epi& E, const int tid) {
;     ...
;             PG8_LDA(At, 1, 1); PG8_STAGE(PG8_SB(1, 0), b3, voffB); PG8_STAGE(PG8_SB(1, 1), b3 + hstep, voffB); PG8_STAGE(PG8_SA(1, 0), a3, voffA);
;             PG8_WAIT_V(8); PG8_WAIT_L(0); PG8_BAR; PG8_MMA(1, 0, At, B0); PG8_MMA(1, 1, At, B1); PG8_BAR; PG8_SCHED;
	s_mov_b32 m0, s47
	v_lshl_add_u64 v[196:197], v[196:197], 0, s[14:15]
	s_add_u32 s28, s30, 0x40080
	ds_read_b128 v[184:187], v152 offset:49152
	ds_read_b128 v[188:191], v152 offset:50176
	ds_read_b128 v[192:195], v152 offset:51200
	ds_read_b128 v[200:203], v152 offset:52224
	ds_read_b128 v[204:207], v152 offset:53248
	ds_read_b128 v[208:211], v152 offset:54272
	ds_read_b128 v[212:215], v152 offset:55296
	ds_read_b128 v[216:219], v152 offset:56320
	global_load_lds_dwordx4 v[196:197], off
	v_lshl_add_u64 v[196:197], v[220:221], 0, s[14:15]
	s_mov_b32 m0, s48
	s_addc_u32 s29, s31, 0
	global_load_lds_dwordx4 v[196:197], off
	v_lshl_add_u64 v[196:197], s[28:29], 0, v[130:131]
	s_mov_b32 m0, s51
	s_nop 0
	global_load_lds_dwordx4 v[196:197], off
	v_lshl_add_u64 v[196:197], s[28:29], 0, v[134:135]
	s_mov_b32 m0, s52
	s_nop 0
	global_load_lds_dwordx4 v[196:197], off
	v_lshl_add_u64 v[196:197], v[222:223], 0, s[14:15]
	s_mov_b32 m0, s49
	s_nop 0
	global_load_lds_dwordx4 v[196:197], off
	v_lshl_add_u64 v[196:197], v[224:225], 0, s[14:15]
	s_mov_b32 m0, s50
	s_nop 0
	global_load_lds_dwordx4 v[196:197], off
	s_waitcnt vmcnt(8)
	s_waitcnt lgkmcnt(0)
	s_barrier
	s_waitcnt lgkmcnt(0)
	v_mfma_f32_16x16x32_bf16 v[60:63], v[144:147], v[184:187], v[60:63]
	v_mfma_f32_16x16x32_bf16 v[56:59], v[160:163], v[184:187], v[56:59]
	v_mfma_f32_16x16x32_bf16 v[44:47], v[144:147], v[192:195], v[44:47]
	v_mfma_f32_16x16x32_bf16 v[40:43], v[160:163], v[192:195], v[40:43]
	v_mfma_f32_16x16x32_bf16 v[28:31], v[144:147], v[204:207], v[28:31]
	v_mfma_f32_16x16x32_bf16 v[24:27], v[160:163], v[204:207], v[24:27]
	v_mfma_f32_16x16x32_bf16 v[12:15], v[144:147], v[212:215], v[12:15]
	v_mfma_f32_16x16x32_bf16 v[8:11], v[160:163], v[212:215], v[8:11]
	v_mfma_f32_16x16x32_bf16 v[60:63], v[156:159], v[188:191], v[60:63]
	v_mfma_f32_16x16x32_bf16 v[56:59], v[164:167], v[188:191], v[56:59]
	v_mfma_f32_16x16x32_bf16 v[44:47], v[156:159], v[200:203], v[44:47]
	v_mfma_f32_16x16x32_bf16 v[40:43], v[164:167], v[200:203], v[40:43]
	v_mfma_f32_16x16x32_bf16 v[28:31], v[156:159], v[208:211], v[28:31]
	v_mfma_f32_16x16x32_bf16 v[24:27], v[164:167], v[208:211], v[24:27]
	v_mfma_f32_16x16x32_bf16 v[12:15], v[156:159], v[216:219], v[12:15]
	v_mfma_f32_16x16x32_bf16 v[8:11], v[164:167], v[216:219], v[8:11]
	v_mfma_f32_16x16x32_bf16 v[52:55], v[168:171], v[184:187], v[52:55]
	v_mfma_f32_16x16x32_bf16 v[48:51], v[176:179], v[184:187], v[48:51]
	v_mfma_f32_16x16x32_bf16 v[36:39], v[168:171], v[192:195], v[36:39]
	v_mfma_f32_16x16x32_bf16 v[32:35], v[176:179], v[192:195], v[32:35]
	v_mfma_f32_16x16x32_bf16 v[20:23], v[168:171], v[204:207], v[20:23]
	v_mfma_f32_16x16x32_bf16 v[16:19], v[176:179], v[204:207], v[16:19]
	v_mfma_f32_16x16x32_bf16 v[4:7], v[168:171], v[212:215], v[4:7]
	v_mfma_f32_16x16x32_bf16 v[0:3], v[176:179], v[212:215], v[0:3]
	v_mfma_f32_16x16x32_bf16 v[52:55], v[172:175], v[188:191], v[52:55]
	v_mfma_f32_16x16x32_bf16 v[48:51], v[180:183], v[188:191], v[48:51]
	v_mfma_f32_16x16x32_bf16 v[36:39], v[172:175], v[200:203], v[36:39]
	v_mfma_f32_16x16x32_bf16 v[32:35], v[180:183], v[200:203], v[32:35]
	v_mfma_f32_16x16x32_bf16 v[20:23], v[172:175], v[208:211], v[20:23]
	v_mfma_f32_16x16x32_bf16 v[16:19], v[180:183], v[208:211], v[16:19]
	v_mfma_f32_16x16x32_bf16 v[4:7], v[172:175], v[216:219], v[4:7]
	v_mfma_f32_16x16x32_bf16 v[0:3], v[180:183], v[216:219], v[0:3]
	s_barrier
	s_add_i32 s61, s61, 2
	s_add_u32 s59, s59, 0x100
	s_addc_u32 s60, s60, 0
	s_cmp_gt_u32 s61, 13
	s_mov_b64 s[28:29], s[6:7]
	s_cbranch_scc0 .LBB0_765
	s_and_b64 vcc, exec, s[16:17]
	s_cbranch_vccnz .LBB0_769
	s_andn2_b64 vcc, exec, s[18:19]
	s_cbranch_vccz .LBB0_770

; #define PG8_STAGE(bufoff, gbase, voff) do { _Pragma("unroll") for (int _i = 0; _i < 2; ++_i) \
;         __builtin_amdgcn_global_load_lds((const unsigned*)((const char*)(gbase) + (voff)[_i]), (PG8_LAS unsigned*)(lds + (bufoff) + ldsw + _i * 8192), 16, 0, 0); } while (0)
; #define PG8_LDA(dst, b, h) do { _Pragma("unroll") for (int m = 0; m < 4; ++m) _Pragma("unroll") for (int k = 0; k < 2; ++k) dst[m][k] = *(const PG8_LAS bf16x8*)(lds + PG8_SA(b, h) + aoff + m * 2048 + k * 1024); } while (0)
; #define PG8_LDB(dst, b, h) do { _Pragma("unroll") for (int n = 0; n < 2; ++n) _Pragma("unroll") for (int k = 0; k < 2; ++k) dst[n][k] = *(const PG8_LAS bf16x8*)(lds + PG8_SB(b, h) + boff + n * 2048 + k * 1024); } while (0)
; #define PG8_MMA(ai, bj, At, Bt) do { __builtin_amdgcn_s_setprio(1); _Pragma("unroll") for (int m = 0; m < 4; ++m) _Pragma("unroll") for (int n = 0; n < 2; ++n) _Pragma("unroll") for (int k = 0; k < 2; ++k) \
;         acc[ai][bj][m][n] = __builtin_amdgcn_mfma_f32_16x16x32_bf16(Bt[n][k], At[m][k], acc[ai][bj][m][n], 0, 0, 0); __builtin_amdgcn_s_setprio(0); } while (0)
; #define PG8_WAIT_V(n) asm volatile("s_waitcnt vmcnt(" #n ")" ::: "memory")
; #define PG8_WAIT_L(n) asm volatile("s_waitcnt lgkmcnt(" #n ")" ::: "memory")
; template <class Epi, class Sched, bool ALIGN_EPI = false, bool SP2 = false>
; __device__ __forceinline__ void gemm_phase(PG8_LAS unsigned char* lds, const Gemm g, const Sched& S, const Epi& E, const int tid) {
;     ...
;             const bool last = (t == nt - 2);
;             const char* a1 = cA + (size_t)(t + 1) * kstep;
;             const char* a2 = last ? nA : cA + (size_t)(t + 2) * kstep; const char* b2 = last ? nB : cB + (size_t)(t + 2) * kstep;
;             const char* a3 = a2 + kstep; const char* b3 = b2 + kstep;
;             if (last && has_next) S.a_ready(nxt);
;             if constexpr (SP2) {
;             PG8_LDB(B0, 0, 0); PG8_LDB(B1, 0, 1); PG8_SCHED; PG8_LDA(At, 0, 0); PG8_STAGE(PG8_SA(1, 1), a1 + hstepA, voffA);
;             PG8_WAIT_V(8); PG8_WAIT_L(0); PG8_BAR; PG8_MMA(0, 0, At, B0); PG8_MMA(0, 1, At, B1); PG8_BAR; PG8_SCHED;
;             PG8_LDA(At, 0, 1); PG8_STAGE(PG8_SB(0, 0), b2, voffB); PG8_STAGE(PG8_SB(0, 1), b2 + hstep, voffB); PG8_STAGE(PG8_SA(0, 0), a2, voffA);
;             PG8_WAIT_V(8); PG8_WAIT_L(0); PG8_BAR; PG8_MMA(1, 0, At, B0); PG8_MMA(1, 1, At, B1); PG8_BAR; PG8_SCHED;
.LBB0_849:
	ds_read_b128 v[144:147], v154
	ds_read_b128 v[148:151], v154 offset:1024
	ds_read_b128 v[160:163], v154 offset:2048
	ds_read_b128 v[164:167], v154 offset:3072
	ds_read_b128 v[168:171], v155
	ds_read_b128 v[172:175], v155 offset:1024
	ds_read_b128 v[176:179], v155 offset:2048
	ds_read_b128 v[180:183], v155 offset:3072
	s_add_u32 s26, s24, 0xfffc0080
	s_addc_u32 s27, s25, -1
	s_cmp_eq_u32 s58, 12
	s_cselect_b32 s29, s17, s27
	s_cselect_b32 s28, s54, s26
	s_cselect_b32 s27, s15, s57
	s_cselect_b32 s26, s55, s56
	v_lshl_add_u64 v[196:197], s[24:25], 0, v[136:137]
	s_add_i32 m0, s39, 0xc000
	ds_read_b128 v[184:187], v156
	ds_read_b128 v[188:191], v156 offset:1024
	ds_read_b128 v[192:195], v156 offset:2048
	ds_read_b128 v[200:203], v156 offset:3072
	ds_read_b128 v[204:207], v156 offset:4096
	ds_read_b128 v[208:211], v156 offset:5120
	ds_read_b128 v[212:215], v156 offset:6144
	ds_read_b128 v[216:219], v156 offset:7168
	global_load_lds_dwordx4 v[196:197], off
	v_lshl_add_u64 v[196:197], s[24:25], 0, v[138:139]
	s_add_i32 m0, s39, 0xe000
	s_nop 0
	global_load_lds_dwordx4 v[196:197], off
	s_waitcnt vmcnt(8)
	s_waitcnt lgkmcnt(0)
	s_barrier
	s_waitcnt lgkmcnt(0)
	v_mfma_f32_16x16x32_bf16 v[124:127], v[144:147], v[184:187], v[124:127]
	v_mfma_f32_16x16x32_bf16 v[120:123], v[160:163], v[184:187], v[120:123]
	v_mfma_f32_16x16x32_bf16 v[108:111], v[144:147], v[192:195], v[108:111]
	v_mfma_f32_16x16x32_bf16 v[104:107], v[160:163], v[192:195], v[104:107]
	v_mfma_f32_16x16x32_bf16 v[92:95], v[144:147], v[204:207], v[92:95]
	v_mfma_f32_16x16x32_bf16 v[88:91], v[160:163], v[204:207], v[88:91]
	v_mfma_f32_16x16x32_bf16 v[76:79], v[144:147], v[212:215], v[76:79]
	v_mfma_f32_16x16x32_bf16 v[72:75], v[160:163], v[212:215], v[72:75]
	v_mfma_f32_16x16x32_bf16 v[124:127], v[148:151], v[188:191], v[124:127]
	v_mfma_f32_16x16x32_bf16 v[120:123], v[164:167], v[188:191], v[120:123]
	v_mfma_f32_16x16x32_bf16 v[108:111], v[148:151], v[200:203], v[108:111]
	v_mfma_f32_16x16x32_bf16 v[104:107], v[164:167], v[200:203], v[104:107]
	v_mfma_f32_16x16x32_bf16 v[92:95], v[148:151], v[208:211], v[92:95]
	v_mfma_f32_16x16x32_bf16 v[88:91], v[164:167], v[208:211], v[88:91]
	v_mfma_f32_16x16x32_bf16 v[76:79], v[148:151], v[216:219], v[76:79]
	v_mfma_f32_16x16x32_bf16 v[72:75], v[164:167], v[216:219], v[72:75]
	v_mfma_f32_16x16x32_bf16 v[116:119], v[168:171], v[184:187], v[116:119]
	v_mfma_f32_16x16x32_bf16 v[112:115], v[176:179], v[184:187], v[112:115]
	v_mfma_f32_16x16x32_bf16 v[100:103], v[168:171], v[192:195], v[100:103]
	v_mfma_f32_16x16x32_bf16 v[96:99], v[176:179], v[192:195], v[96:99]
	v_mfma_f32_16x16x32_bf16 v[84:87], v[168:171], v[204:207], v[84:87]
	v_mfma_f32_16x16x32_bf16 v[80:83], v[176:179], v[204:207], v[80:83]
	v_mfma_f32_16x16x32_bf16 v[68:71], v[168:171], v[212:215], v[68:71]
	v_mfma_f32_16x16x32_bf16 v[64:67], v[176:179], v[212:215], v[64:67]
	v_mfma_f32_16x16x32_bf16 v[116:119], v[172:175], v[188:191], v[116:119]
	v_mfma_f32_16x16x32_bf16 v[112:115], v[180:183], v[188:191], v[112:115]
	v_mfma_f32_16x16x32_bf16 v[100:103], v[172:175], v[200:203], v[100:103]
	v_mfma_f32_16x16x32_bf16 v[96:99], v[180:183], v[200:203], v[96:99]
	v_mfma_f32_16x16x32_bf16 v[84:87], v[172:175], v[208:211], v[84:87]
	v_mfma_f32_16x16x32_bf16 v[80:83], v[180:183], v[208:211], v[80:83]
	v_mfma_f32_16x16x32_bf16 v[68:71], v[172:175], v[216:219], v[68:71]
	v_mfma_f32_16x16x32_bf16 v[64:67], v[180:183], v[216:219], v[64:67]
	s_barrier
	s_mov_b32 m0, s23
	v_lshl_add_u64 v[196:197], s[26:27], 0, v[132:133]
	s_add_u32 s60, s26, 0x40000
	ds_read_b128 v[184:187], v156 offset:16384
	ds_read_b128 v[188:191], v156 offset:17408
	ds_read_b128 v[192:195], v156 offset:18432
	ds_read_b128 v[200:203], v156 offset:19456
	ds_read_b128 v[204:207], v156 offset:20480
	ds_read_b128 v[208:211], v156 offset:21504
	ds_read_b128 v[212:215], v156 offset:22528
	ds_read_b128 v[216:219], v156 offset:23552
	global_load_lds_dwordx4 v[196:197], off
	v_lshl_add_u64 v[220:221], s[26:27], 0, v[128:129]
	s_mov_b32 m0, s36
	s_addc_u32 s61, s27, 0
	global_load_lds_dwordx4 v[220:221], off
	v_lshl_add_u64 v[222:223], s[60:61], 0, v[132:133]
	s_mov_b32 m0, s37
	v_lshl_add_u64 v[224:225], s[28:29], 0, v[130:131]
	global_load_lds_dwordx4 v[222:223], off
	v_lshl_add_u64 v[222:223], s[60:61], 0, v[128:129]
	s_mov_b32 m0, s38
	s_nop 0
	global_load_lds_dwordx4 v[222:223], off
	v_lshl_add_u64 v[222:223], s[28:29], 0, v[134:135]
	s_mov_b32 m0, s39
	s_nop 0
	global_load_lds_dwordx4 v[222:223], off
	s_mov_b32 m0, s40
	s_nop 0
	global_load_lds_dwordx4 v[224:225], off
	s_waitcnt vmcnt(8)
	s_waitcnt lgkmcnt(0)
	s_barrier
; #define PG8_STAGE(bufoff, gbase, voff) do { _Pragma("unroll") for (int _i = 0; _i < 2; ++_i) \
;         __builtin_amdgcn_global_load_lds((const unsigned*)((const char*)(gbase) + (voff)[_i]), (PG8_LAS unsigned*)(lds + (bufoff) + ldsw + _i * 8192), 16, 0, 0); } while (0)
; #define PG8_LDA(dst, b, h) do { _Pragma("unroll") for (int m = 0; m < 4; ++m) _Pragma("unroll") for (int k = 0; k < 2; ++k) dst[m][k] = *(const PG8_LAS bf16x8*)(lds + PG8_SA(b, h) + aoff + m * 2048 + k * 1024); } while (0)
; #define PG8_LDB(dst, b, h) do { _Pragma("unroll") for (int n = 0; n < 2; ++n) _Pragma("unroll") for (int k = 0; k < 2; ++k) dst[n][k] = *(const PG8_LAS bf16x8*)(lds + PG8_SB(b, h) + boff + n * 2048 + k * 1024); } while (0)
; #define PG8_MMA(ai, bj, At, Bt) do { __builtin_amdgcn_s_setprio(1); _Pragma("unroll") for (int m = 0; m < 4; ++m) _Pragma("unroll") for (int n = 0; n < 2; ++n) _Pragma("unroll") for (int k = 0; k < 2; ++k) \
;         acc[ai][bj][m][n] = __builtin_amdgcn_mfma_f32_16x16x32_bf16(Bt[n][k], At[m][k], acc[ai][bj][m][n], 0, 0, 0); __builtin_amdgcn_s_setprio(0); } while (0)
; #define PG8_WAIT_V(n) asm volatile("s_waitcnt vmcnt(" #n ")" ::: "memory")
; #define PG8_WAIT_L(n) asm volatile("s_waitcnt lgkmcnt(" #n ")" ::: "memory")
; #define PG8_BAR __builtin_amdgcn_s_barrier()
; #define PG8_SCHED __builtin_amdgcn_sched_barrier(0)
; template <class Epi, class Sched, bool ALIGN_EPI = false, bool SP2 = false>
; __device__ __forceinline__ void gemm_phase(PG8_LAS unsigned char* lds, const Gemm g, const Sched& S, const Epi& E, const int tid) {
;     ...
;             PG8_WAIT_V(8); PG8_WAIT_L(0); PG8_BAR; PG8_MMA(1, 0, At, B0); PG8_MMA(1, 1, At, B1); PG8_BAR; PG8_SCHED;
;             PG8_LDB(B0, 1, 0); PG8_LDB(B1, 1, 1); PG8_SCHED; PG8_LDA(At, 1, 0); PG8_STAGE(PG8_SA(0, 1), a2 + hstepA, voffA);
;             PG8_WAIT_V(8); PG8_WAIT_L(0); PG8_BAR; PG8_MMA(0, 0, At, B0); PG8_MMA(0, 1, At, B1); PG8_BAR; PG8_SCHED;
	s_waitcnt lgkmcnt(0)
	v_mfma_f32_16x16x32_bf16 v[60:63], v[144:147], v[184:187], v[60:63]
	v_mfma_f32_16x16x32_bf16 v[56:59], v[160:163], v[184:187], v[56:59]
	v_mfma_f32_16x16x32_bf16 v[44:47], v[144:147], v[192:195], v[44:47]
	v_mfma_f32_16x16x32_bf16 v[40:43], v[160:163], v[192:195], v[40:43]
	v_mfma_f32_16x16x32_bf16 v[28:31], v[144:147], v[204:207], v[28:31]
	v_mfma_f32_16x16x32_bf16 v[24:27], v[160:163], v[204:207], v[24:27]
	v_mfma_f32_16x16x32_bf16 v[12:15], v[144:147], v[212:215], v[12:15]
	v_mfma_f32_16x16x32_bf16 v[8:11], v[160:163], v[212:215], v[8:11]
	v_mfma_f32_16x16x32_bf16 v[60:63], v[148:151], v[188:191], v[60:63]
	v_mfma_f32_16x16x32_bf16 v[56:59], v[164:167], v[188:191], v[56:59]
	v_mfma_f32_16x16x32_bf16 v[44:47], v[148:151], v[200:203], v[44:47]
	v_mfma_f32_16x16x32_bf16 v[40:43], v[164:167], v[200:203], v[40:43]
	v_mfma_f32_16x16x32_bf16 v[28:31], v[148:151], v[208:211], v[28:31]
	v_mfma_f32_16x16x32_bf16 v[24:27], v[164:167], v[208:211], v[24:27]
	v_mfma_f32_16x16x32_bf16 v[12:15], v[148:151], v[216:219], v[12:15]
	v_mfma_f32_16x16x32_bf16 v[8:11], v[164:167], v[216:219], v[8:11]
	v_mfma_f32_16x16x32_bf16 v[52:55], v[168:171], v[184:187], v[52:55]
	v_mfma_f32_16x16x32_bf16 v[48:51], v[176:179], v[184:187], v[48:51]
	v_mfma_f32_16x16x32_bf16 v[36:39], v[168:171], v[192:195], v[36:39]
	v_mfma_f32_16x16x32_bf16 v[32:35], v[176:179], v[192:195], v[32:35]
	v_mfma_f32_16x16x32_bf16 v[20:23], v[168:171], v[204:207], v[20:23]
	v_mfma_f32_16x16x32_bf16 v[16:19], v[176:179], v[204:207], v[16:19]
	v_mfma_f32_16x16x32_bf16 v[4:7], v[168:171], v[212:215], v[4:7]
	v_mfma_f32_16x16x32_bf16 v[0:3], v[176:179], v[212:215], v[0:3]
	v_mfma_f32_16x16x32_bf16 v[52:55], v[172:175], v[188:191], v[52:55]
	v_mfma_f32_16x16x32_bf16 v[48:51], v[180:183], v[188:191], v[48:51]
	v_mfma_f32_16x16x32_bf16 v[36:39], v[172:175], v[200:203], v[36:39]
	v_mfma_f32_16x16x32_bf16 v[32:35], v[180:183], v[200:203], v[32:35]
	v_mfma_f32_16x16x32_bf16 v[20:23], v[172:175], v[208:211], v[20:23]
	v_mfma_f32_16x16x32_bf16 v[16:19], v[180:183], v[208:211], v[16:19]
	v_mfma_f32_16x16x32_bf16 v[4:7], v[172:175], v[216:219], v[4:7]
	v_mfma_f32_16x16x32_bf16 v[0:3], v[180:183], v[216:219], v[0:3]
	s_barrier
	ds_read_b128 v[144:147], v157
	ds_read_b128 v[148:151], v157 offset:1024
	ds_read_b128 v[160:163], v157 offset:2048
	ds_read_b128 v[164:167], v157 offset:3072
	ds_read_b128 v[168:171], v158
	ds_read_b128 v[172:175], v158 offset:1024
	ds_read_b128 v[176:179], v158 offset:2048
	ds_read_b128 v[180:183], v158 offset:3072
	s_add_u32 s28, s28, 0x40000
	s_addc_u32 s29, s29, 0
	s_mov_b32 m0, s41
	v_lshl_add_u64 v[226:227], s[28:29], 0, v[134:135]
	ds_read_b128 v[184:187], v156 offset:32768
	ds_read_b128 v[188:191], v156 offset:33792
	ds_read_b128 v[192:195], v156 offset:34816
	ds_read_b128 v[200:203], v156 offset:35840
	ds_read_b128 v[204:207], v156 offset:36864
	ds_read_b128 v[208:211], v156 offset:37888
	ds_read_b128 v[212:215], v156 offset:38912
	ds_read_b128 v[216:219], v156 offset:39936
	global_load_lds_dwordx4 v[226:227], off
	v_lshl_add_u64 v[226:227], s[28:29], 0, v[130:131]
	s_mov_b32 m0, s42
	s_nop 0
	global_load_lds_dwordx4 v[226:227], off
	s_waitcnt vmcnt(8)
	s_waitcnt lgkmcnt(0)
	s_barrier
	s_waitcnt lgkmcnt(0)
	v_mfma_f32_16x16x32_bf16 v[124:127], v[144:147], v[184:187], v[124:127]
	v_mfma_f32_16x16x32_bf16 v[120:123], v[160:163], v[184:187], v[120:123]
	v_mfma_f32_16x16x32_bf16 v[108:111], v[144:147], v[192:195], v[108:111]
	v_mfma_f32_16x16x32_bf16 v[104:107], v[160:163], v[192:195], v[104:107]
	v_mfma_f32_16x16x32_bf16 v[92:95], v[144:147], v[204:207], v[92:95]
	v_mfma_f32_16x16x32_bf16 v[88:91], v[160:163], v[204:207], v[88:91]
	v_mfma_f32_16x16x32_bf16 v[76:79], v[144:147], v[212:215], v[76:79]
	v_mfma_f32_16x16x32_bf16 v[72:75], v[160:163], v[212:215], v[72:75]
	v_mfma_f32_16x16x32_bf16 v[124:127], v[148:151], v[188:191], v[124:127]
	v_mfma_f32_16x16x32_bf16 v[120:123], v[164:167], v[188:191], v[120:123]
	v_mfma_f32_16x16x32_bf16 v[108:111], v[148:151], v[200:203], v[108:111]
	v_mfma_f32_16x16x32_bf16 v[104:107], v[164:167], v[200:203], v[104:107]
	v_mfma_f32_16x16x32_bf16 v[92:95], v[148:151], v[208:211], v[92:95]
	v_mfma_f32_16x16x32_bf16 v[88:91], v[164:167], v[208:211], v[88:91]
	v_mfma_f32_16x16x32_bf16 v[76:79], v[148:151], v[216:219], v[76:79]
	v_mfma_f32_16x16x32_bf16 v[72:75], v[164:167], v[216:219], v[72:75]
	v_mfma_f32_16x16x32_bf16 v[116:119], v[168:171], v[184:187], v[116:119]
	v_mfma_f32_16x16x32_bf16 v[112:115], v[176:179], v[184:187], v[112:115]
	v_mfma_f32_16x16x32_bf16 v[100:103], v[168:171], v[192:195], v[100:103]
	v_mfma_f32_16x16x32_bf16 v[96:99], v[176:179], v[192:195], v[96:99]
	v_mfma_f32_16x16x32_bf16 v[84:87], v[168:171], v[204:207], v[84:87]
	v_mfma_f32_16x16x32_bf16 v[80:83], v[176:179], v[204:207], v[80:83]
	v_mfma_f32_16x16x32_bf16 v[68:71], v[168:171], v[212:215], v[68:71]
	v_mfma_f32_16x16x32_bf16 v[64:67], v[176:179], v[212:215], v[64:67]
	v_mfma_f32_16x16x32_bf16 v[116:119], v[172:175], v[188:191], v[116:119]
	v_mfma_f32_16x16x32_bf16 v[112:115], v[180:183], v[188:191], v[112:115]
	v_mfma_f32_16x16x32_bf16 v[100:103], v[172:175], v[200:203], v[100:103]
	v_mfma_f32_16x16x32_bf16 v[96:99], v[180:183], v[200:203], v[96:99]
	v_mfma_f32_16x16x32_bf16 v[84:87], v[172:175], v[208:211], v[84:87]
	v_mfma_f32_16x16x32_bf16 v[80:83], v[180:183], v[208:211], v[80:83]
	v_mfma_f32_16x16x32_bf16 v[68:71], v[172:175], v[216:219], v[68:71]
	v_mfma_f32_16x16x32_bf16 v[64:67], v[180:183], v[216:219], v[64:67]
	s_barrier
; #define PG8_STAGE(bufoff, gbase, voff) do { _Pragma("unroll") for (int _i = 0; _i < 2; ++_i) \
;         __builtin_amdgcn_global_load_lds((const unsigned*)((const char*)(gbase) + (voff)[_i]), (PG8_LAS unsigned*)(lds + (bufoff) + ldsw + _i * 8192), 16, 0, 0); } while (0)
; #define PG8_LDA(dst, b, h) do { _Pragma("unroll") for (int m = 0; m < 4; ++m) _Pragma("unroll") for (int k = 0; k < 2; ++k) dst[m][k] = *(const PG8_LAS bf16x8*)(lds + PG8_SA(b, h) + aoff + m * 2048 + k * 1024); } while (0)
; #define PG8_MMA(ai, bj, At, Bt) do { __builtin_amdgcn_s_setprio(1); _Pragma("unroll") for (int m = 0; m < 4; ++m) _Pragma("unroll") for (int n = 0; n < 2; ++n) _Pragma("unroll") for (int k = 0; k < 2; ++k) \
;         acc[ai][bj][m][n] = __builtin_amdgcn_mfma_f32_16x16x32_bf16(Bt[n][k], At[m][k], acc[ai][bj][m][n], 0, 0, 0); __builtin_amdgcn_s_setprio(0); } while (0)
; #define PG8_WAIT_V(n) asm volatile("s_waitcnt vmcnt(" #n ")" ::: "memory")
; #define PG8_WAIT_L(n) asm volatile("s_waitcnt lgkmcnt(" #n ")" ::: "memory")
; #define PG8_BAR __builtin_amdgcn_s_barrier()
; #define PG8_SCHED __builtin_amdgcn_sched_barrier(0)
; __device__ __forceinline__ float ss_scale(const u64* ss, int row) { return __builtin_amdgcn_rsqf((float)ss[row] * (1.f / 4294967296.f / 1024.f) + EPS); }
; template <class Epi, class Sched, bool ALIGN_EPI = false, bool SP2 = false>
; __device__ __forceinline__ void gemm_phase(PG8_LAS unsigned char* lds, const Gemm g, const Sched& S, const Epi& E, const int tid) {
;     ...
;             PG8_LDA(At, 1, 1); PG8_STAGE(PG8_SB(1, 0), b3, voffB); PG8_STAGE(PG8_SB(1, 1), b3 + hstep, voffB); PG8_STAGE(PG8_SA(1, 0), a3, voffA);
;             PG8_WAIT_V(8); PG8_WAIT_L(0); PG8_BAR; PG8_MMA(1, 0, At, B0); PG8_MMA(1, 1, At, B1); PG8_BAR; PG8_SCHED;
;     __device__ __forceinline__ void operator()(const f32x4 (&acc)[2][2][4][2], const pg8::Unit& u, int wr, int wc, int fr, int fq) const {
;         const int row0 = u.pm * 256 + wr * 64 + fr, col0 = u.pn * 128 + wc * 32 + 8 * fq;
; #pragma unroll
;         for (int ai = 0; ai < 2; ++ai)
; #pragma unroll
;             for (int m = 0; m < 4; ++m) {
;                 const int row = row0 + ai * 128 + m * 16;
;                 float s = ss_scale(ss, row);
	s_mov_b32 m0, s45
	v_lshl_add_u64 v[196:197], v[196:197], 0, s[10:11]
	s_add_u32 s26, s26, 0x40080
	ds_read_b128 v[184:187], v156 offset:49152
	ds_read_b128 v[188:191], v156 offset:50176
	ds_read_b128 v[192:195], v156 offset:51200
	ds_read_b128 v[200:203], v156 offset:52224
	ds_read_b128 v[204:207], v156 offset:53248
	ds_read_b128 v[208:211], v156 offset:54272
	ds_read_b128 v[212:215], v156 offset:55296
	ds_read_b128 v[216:219], v156 offset:56320
	global_load_lds_dwordx4 v[196:197], off
	v_lshl_add_u64 v[196:197], v[220:221], 0, s[10:11]
	s_mov_b32 m0, s46
	s_addc_u32 s27, s27, 0
	global_load_lds_dwordx4 v[196:197], off
	v_lshl_add_u64 v[196:197], s[26:27], 0, v[132:133]
	s_mov_b32 m0, s49
	s_nop 0
	global_load_lds_dwordx4 v[196:197], off
	v_lshl_add_u64 v[196:197], s[26:27], 0, v[128:129]
	s_mov_b32 m0, s50
	s_nop 0
	global_load_lds_dwordx4 v[196:197], off
	v_lshl_add_u64 v[196:197], v[222:223], 0, s[10:11]
	s_mov_b32 m0, s47
	s_nop 0
	global_load_lds_dwordx4 v[196:197], off
	v_lshl_add_u64 v[196:197], v[224:225], 0, s[10:11]
	s_mov_b32 m0, s48
	s_nop 0
	global_load_lds_dwordx4 v[196:197], off
	s_waitcnt vmcnt(8)
	s_waitcnt lgkmcnt(0)
	s_barrier
	s_waitcnt lgkmcnt(0)
	v_mfma_f32_16x16x32_bf16 v[60:63], v[144:147], v[184:187], v[60:63]
	v_mfma_f32_16x16x32_bf16 v[56:59], v[160:163], v[184:187], v[56:59]
	v_mfma_f32_16x16x32_bf16 v[44:47], v[144:147], v[192:195], v[44:47]
	v_mfma_f32_16x16x32_bf16 v[40:43], v[160:163], v[192:195], v[40:43]
	v_mfma_f32_16x16x32_bf16 v[28:31], v[144:147], v[204:207], v[28:31]
	v_mfma_f32_16x16x32_bf16 v[24:27], v[160:163], v[204:207], v[24:27]
	v_mfma_f32_16x16x32_bf16 v[12:15], v[144:147], v[212:215], v[12:15]
	v_mfma_f32_16x16x32_bf16 v[8:11], v[160:163], v[212:215], v[8:11]
	v_mfma_f32_16x16x32_bf16 v[60:63], v[148:151], v[188:191], v[60:63]
	v_mfma_f32_16x16x32_bf16 v[56:59], v[164:167], v[188:191], v[56:59]
	v_mfma_f32_16x16x32_bf16 v[44:47], v[148:151], v[200:203], v[44:47]
	v_mfma_f32_16x16x32_bf16 v[40:43], v[164:167], v[200:203], v[40:43]
	v_mfma_f32_16x16x32_bf16 v[28:31], v[148:151], v[208:211], v[28:31]
	v_mfma_f32_16x16x32_bf16 v[24:27], v[164:167], v[208:211], v[24:27]
	v_mfma_f32_16x16x32_bf16 v[12:15], v[148:151], v[216:219], v[12:15]
	v_mfma_f32_16x16x32_bf16 v[8:11], v[164:167], v[216:219], v[8:11]
	v_mfma_f32_16x16x32_bf16 v[52:55], v[168:171], v[184:187], v[52:55]
	v_mfma_f32_16x16x32_bf16 v[48:51], v[176:179], v[184:187], v[48:51]
	v_mfma_f32_16x16x32_bf16 v[36:39], v[168:171], v[192:195], v[36:39]
	v_mfma_f32_16x16x32_bf16 v[32:35], v[176:179], v[192:195], v[32:35]
	v_mfma_f32_16x16x32_bf16 v[20:23], v[168:171], v[204:207], v[20:23]
	v_mfma_f32_16x16x32_bf16 v[16:19], v[176:179], v[204:207], v[16:19]
	v_mfma_f32_16x16x32_bf16 v[4:7], v[168:171], v[212:215], v[4:7]
	v_mfma_f32_16x16x32_bf16 v[0:3], v[176:179], v[212:215], v[0:3]
	v_mfma_f32_16x16x32_bf16 v[52:55], v[172:175], v[188:191], v[52:55]
	v_mfma_f32_16x16x32_bf16 v[48:51], v[180:183], v[188:191], v[48:51]
	v_mfma_f32_16x16x32_bf16 v[36:39], v[172:175], v[200:203], v[36:39]
	v_mfma_f32_16x16x32_bf16 v[32:35], v[180:183], v[200:203], v[32:35]
	v_mfma_f32_16x16x32_bf16 v[20:23], v[172:175], v[208:211], v[20:23]
	v_mfma_f32_16x16x32_bf16 v[16:19], v[180:183], v[208:211], v[16:19]
	v_mfma_f32_16x16x32_bf16 v[4:7], v[172:175], v[216:219], v[4:7]
	v_mfma_f32_16x16x32_bf16 v[0:3], v[180:183], v[216:219], v[0:3]
	s_barrier
	s_add_i32 s58, s58, 2
	s_add_u32 s24, s24, 0x100
	s_addc_u32 s25, s25, 0
	s_add_u32 s56, s56, 0x100
	s_addc_u32 s57, s57, 0
	s_cmp_gt_u32 s58, 13
	s_cbranch_scc0 .LBB0_849
	v_lshl_add_u32 v144, s22, 8, v152
	v_mov_b32_e32 v145, 0
	v_lshl_add_u64 v[150:151], v[144:145], 3, s[8:9]
	global_load_dwordx2 v[176:177], v[150:151], off
	global_load_dwordx2 v[178:179], v[150:151], off offset:128
	global_load_dwordx2 v[180:181], v[150:151], off offset:256
	global_load_dwordx2 v[182:183], v[150:151], off offset:384
	global_load_dwordx2 v[184:185], v[150:151], off offset:1024
	global_load_dwordx2 v[186:187], v[150:151], off offset:1152
	global_load_dwordx2 v[188:189], v[150:151], off offset:1280
	global_load_dwordx2 v[190:191], v[150:151], off offset:1408
	v_lshl_or_b32 v148, s53, 7, v153
	v_mul_u32_u24_e32 v146, s52, v144
	v_lshl_add_u32 v146, v148, 1, v146
	v_mov_b32_e32 v147, 0
	v_lshl_add_u64 v[146:147], v[146:147], 0, s[6:7]
	v_mov_b32_e32 v164, 1.0
	v_mov_b32_e32 v165, 1.0
	s_mov_b32 s101, 0
	s_and_b64 vcc, exec, s[12:13]
	s_cbranch_vccz .LBB0_852
	s_barrier

; #define PG8_STAGE(bufoff, gbase, voff) do { _Pragma("unroll") for (int _i = 0; _i < 2; ++_i) \
;         __builtin_amdgcn_global_load_lds((const unsigned*)((const char*)(gbase) + (voff)[_i]), (PG8_LAS unsigned*)(lds + (bufoff) + ldsw + _i * 8192), 16, 0, 0); } while (0)
; #define PG8_LDA(dst, b, h) do { _Pragma("unroll") for (int m = 0; m < 4; ++m) _Pragma("unroll") for (int k = 0; k < 2; ++k) dst[m][k] = *(const PG8_LAS bf16x8*)(lds + PG8_SA(b, h) + aoff + m * 2048 + k * 1024); } while (0)
; #define PG8_LDB(dst, b, h) do { _Pragma("unroll") for (int n = 0; n < 2; ++n) _Pragma("unroll") for (int k = 0; k < 2; ++k) dst[n][k] = *(const PG8_LAS bf16x8*)(lds + PG8_SB(b, h) + boff + n * 2048 + k * 1024); } while (0)
; #define PG8_MMA(ai, bj, At, Bt) do { __builtin_amdgcn_s_setprio(1); _Pragma("unroll") for (int m = 0; m < 4; ++m) _Pragma("unroll") for (int n = 0; n < 2; ++n) _Pragma("unroll") for (int k = 0; k < 2; ++k) \
;         acc[ai][bj][m][n] = __builtin_amdgcn_mfma_f32_16x16x32_bf16(Bt[n][k], At[m][k], acc[ai][bj][m][n], 0, 0, 0); __builtin_amdgcn_s_setprio(0); } while (0)
; #define PG8_WAIT_V(n) asm volatile("s_waitcnt vmcnt(" #n ")" ::: "memory")
; #define PG8_WAIT_L(n) asm volatile("s_waitcnt lgkmcnt(" #n ")" ::: "memory")
; template <class Epi, class Sched, bool ALIGN_EPI = false, bool SP2 = false>
; __device__ __forceinline__ void gemm_phase(PG8_LAS unsigned char* lds, const Gemm g, const Sched& S, const Epi& E, const int tid) {
;     ...
;             const bool last = (t == nt - 2);
;             const char* a1 = cA + (size_t)(t + 1) * kstep;
;             const char* a2 = last ? nA : cA + (size_t)(t + 2) * kstep; const char* b2 = last ? nB : cB + (size_t)(t + 2) * kstep;
;             const char* a3 = a2 + kstep; const char* b3 = b2 + kstep;
;             if (last && has_next) S.a_ready(nxt);
;             if constexpr (SP2) {
;             PG8_LDB(B0, 0, 0); PG8_LDB(B1, 0, 1); PG8_SCHED; PG8_LDA(At, 0, 0); PG8_STAGE(PG8_SA(1, 1), a1 + hstepA, voffA);
;             PG8_WAIT_V(8); PG8_WAIT_L(0); PG8_BAR; PG8_MMA(0, 0, At, B0); PG8_MMA(0, 1, At, B1); PG8_BAR; PG8_SCHED;
;             PG8_LDA(At, 0, 1); PG8_STAGE(PG8_SB(0, 0), b2, voffB); PG8_STAGE(PG8_SB(0, 1), b2 + hstep, voffB); PG8_STAGE(PG8_SA(0, 0), a2, voffA);
;             PG8_WAIT_V(8); PG8_WAIT_L(0); PG8_BAR; PG8_MMA(1, 0, At, B0); PG8_MMA(1, 1, At, B1); PG8_BAR; PG8_SCHED;
.LBB0_923:
	ds_read_b128 v[144:147], v166
	ds_read_b128 v[148:151], v166 offset:1024
	ds_read_b128 v[152:155], v166 offset:2048
	ds_read_b128 v[156:159], v166 offset:3072
	ds_read_b128 v[160:163], v167
	ds_read_b128 v[172:175], v167 offset:1024
	ds_read_b128 v[176:179], v167 offset:2048
	ds_read_b128 v[180:183], v167 offset:3072
	s_add_u32 s28, s26, 0x100
	s_addc_u32 s29, s27, 0
	s_cmp_eq_u32 s63, 40
	s_cselect_b32 s35, s7, s29
	s_cselect_b32 s34, s6, s28
	s_cselect_b32 s31, s25, s62
	s_cselect_b32 s30, s24, s61
	v_lshl_add_u64 v[196:197], s[26:27], 0, v[136:137]
	s_add_i32 m0, s42, 0xc000
	ds_read_b128 v[184:187], v168
	ds_read_b128 v[188:191], v168 offset:1024
	ds_read_b128 v[192:195], v168 offset:2048
	ds_read_b128 v[200:203], v168 offset:3072
	ds_read_b128 v[204:207], v168 offset:4096
	ds_read_b128 v[208:211], v168 offset:5120
	ds_read_b128 v[212:215], v168 offset:6144
	ds_read_b128 v[216:219], v168 offset:7168
	global_load_lds_dwordx4 v[196:197], off
	v_lshl_add_u64 v[196:197], s[26:27], 0, v[138:139]
	s_add_i32 m0, s42, 0xe000
	s_nop 0
	global_load_lds_dwordx4 v[196:197], off
	s_waitcnt vmcnt(8)
	s_waitcnt lgkmcnt(0)
	s_barrier
	s_waitcnt lgkmcnt(0)
	v_mfma_f32_16x16x32_bf16 v[124:127], v[144:147], v[184:187], v[124:127]
	v_mfma_f32_16x16x32_bf16 v[120:123], v[152:155], v[184:187], v[120:123]
	v_mfma_f32_16x16x32_bf16 v[108:111], v[144:147], v[192:195], v[108:111]
	v_mfma_f32_16x16x32_bf16 v[104:107], v[152:155], v[192:195], v[104:107]
	v_mfma_f32_16x16x32_bf16 v[92:95], v[144:147], v[204:207], v[92:95]
	v_mfma_f32_16x16x32_bf16 v[88:91], v[152:155], v[204:207], v[88:91]
	v_mfma_f32_16x16x32_bf16 v[76:79], v[144:147], v[212:215], v[76:79]
	v_mfma_f32_16x16x32_bf16 v[72:75], v[152:155], v[212:215], v[72:75]
	v_mfma_f32_16x16x32_bf16 v[124:127], v[148:151], v[188:191], v[124:127]
	v_mfma_f32_16x16x32_bf16 v[120:123], v[156:159], v[188:191], v[120:123]
	v_mfma_f32_16x16x32_bf16 v[108:111], v[148:151], v[200:203], v[108:111]
	v_mfma_f32_16x16x32_bf16 v[104:107], v[156:159], v[200:203], v[104:107]
	v_mfma_f32_16x16x32_bf16 v[92:95], v[148:151], v[208:211], v[92:95]
	v_mfma_f32_16x16x32_bf16 v[88:91], v[156:159], v[208:211], v[88:91]
	v_mfma_f32_16x16x32_bf16 v[76:79], v[148:151], v[216:219], v[76:79]
	v_mfma_f32_16x16x32_bf16 v[72:75], v[156:159], v[216:219], v[72:75]
	v_mfma_f32_16x16x32_bf16 v[116:119], v[160:163], v[184:187], v[116:119]
	v_mfma_f32_16x16x32_bf16 v[112:115], v[176:179], v[184:187], v[112:115]
	v_mfma_f32_16x16x32_bf16 v[100:103], v[160:163], v[192:195], v[100:103]
	v_mfma_f32_16x16x32_bf16 v[96:99], v[176:179], v[192:195], v[96:99]
	v_mfma_f32_16x16x32_bf16 v[84:87], v[160:163], v[204:207], v[84:87]
	v_mfma_f32_16x16x32_bf16 v[80:83], v[176:179], v[204:207], v[80:83]
	v_mfma_f32_16x16x32_bf16 v[68:71], v[160:163], v[212:215], v[68:71]
	v_mfma_f32_16x16x32_bf16 v[64:67], v[176:179], v[212:215], v[64:67]
	v_mfma_f32_16x16x32_bf16 v[116:119], v[172:175], v[188:191], v[116:119]
	v_mfma_f32_16x16x32_bf16 v[112:115], v[180:183], v[188:191], v[112:115]
	v_mfma_f32_16x16x32_bf16 v[100:103], v[172:175], v[200:203], v[100:103]
	v_mfma_f32_16x16x32_bf16 v[96:99], v[180:183], v[200:203], v[96:99]
	v_mfma_f32_16x16x32_bf16 v[84:87], v[172:175], v[208:211], v[84:87]
	v_mfma_f32_16x16x32_bf16 v[80:83], v[180:183], v[208:211], v[80:83]
	v_mfma_f32_16x16x32_bf16 v[68:71], v[172:175], v[216:219], v[68:71]
	v_mfma_f32_16x16x32_bf16 v[64:67], v[180:183], v[216:219], v[64:67]
	s_barrier
	s_mov_b32 m0, s38
	v_lshl_add_u64 v[196:197], s[30:31], 0, v[130:131]
	s_add_u32 s26, s30, 0xb0000
	ds_read_b128 v[184:187], v168 offset:16384
	ds_read_b128 v[188:191], v168 offset:17408
	ds_read_b128 v[192:195], v168 offset:18432
	ds_read_b128 v[200:203], v168 offset:19456
	ds_read_b128 v[204:207], v168 offset:20480
	ds_read_b128 v[208:211], v168 offset:21504
	ds_read_b128 v[212:215], v168 offset:22528
	ds_read_b128 v[216:219], v168 offset:23552
	global_load_lds_dwordx4 v[196:197], off
	v_lshl_add_u64 v[220:221], s[30:31], 0, v[134:135]
	s_mov_b32 m0, s39
	s_addc_u32 s27, s31, 0
	global_load_lds_dwordx4 v[220:221], off
	v_lshl_add_u64 v[222:223], s[26:27], 0, v[130:131]
	s_mov_b32 m0, s40
	v_lshl_add_u64 v[224:225], s[34:35], 0, v[132:133]
	global_load_lds_dwordx4 v[222:223], off
	v_lshl_add_u64 v[222:223], s[26:27], 0, v[134:135]
	s_mov_b32 m0, s41
	s_nop 0
	global_load_lds_dwordx4 v[222:223], off
	v_lshl_add_u64 v[222:223], s[34:35], 0, v[128:129]
	s_mov_b32 m0, s42
	s_nop 0
	global_load_lds_dwordx4 v[222:223], off
	s_mov_b32 m0, s43
	s_nop 0
	global_load_lds_dwordx4 v[224:225], off
	s_waitcnt vmcnt(8)
	s_waitcnt lgkmcnt(0)
	s_barrier
; #define PG8_STAGE(bufoff, gbase, voff) do { _Pragma("unroll") for (int _i = 0; _i < 2; ++_i) \
;         __builtin_amdgcn_global_load_lds((const unsigned*)((const char*)(gbase) + (voff)[_i]), (PG8_LAS unsigned*)(lds + (bufoff) + ldsw + _i * 8192), 16, 0, 0); } while (0)
; #define PG8_LDA(dst, b, h) do { _Pragma("unroll") for (int m = 0; m < 4; ++m) _Pragma("unroll") for (int k = 0; k < 2; ++k) dst[m][k] = *(const PG8_LAS bf16x8*)(lds + PG8_SA(b, h) + aoff + m * 2048 + k * 1024); } while (0)
; #define PG8_LDB(dst, b, h) do { _Pragma("unroll") for (int n = 0; n < 2; ++n) _Pragma("unroll") for (int k = 0; k < 2; ++k) dst[n][k] = *(const PG8_LAS bf16x8*)(lds + PG8_SB(b, h) + boff + n * 2048 + k * 1024); } while (0)
; #define PG8_MMA(ai, bj, At, Bt) do { __builtin_amdgcn_s_setprio(1); _Pragma("unroll") for (int m = 0; m < 4; ++m) _Pragma("unroll") for (int n = 0; n < 2; ++n) _Pragma("unroll") for (int k = 0; k < 2; ++k) \
;         acc[ai][bj][m][n] = __builtin_amdgcn_mfma_f32_16x16x32_bf16(Bt[n][k], At[m][k], acc[ai][bj][m][n], 0, 0, 0); __builtin_amdgcn_s_setprio(0); } while (0)
; #define PG8_WAIT_V(n) asm volatile("s_waitcnt vmcnt(" #n ")" ::: "memory")
; #define PG8_WAIT_L(n) asm volatile("s_waitcnt lgkmcnt(" #n ")" ::: "memory")
; #define PG8_BAR __builtin_amdgcn_s_barrier()
; #define PG8_SCHED __builtin_amdgcn_sched_barrier(0)
; template <class Epi, class Sched, bool ALIGN_EPI = false, bool SP2 = false>
; __device__ __forceinline__ void gemm_phase(PG8_LAS unsigned char* lds, const Gemm g, const Sched& S, const Epi& E, const int tid) {
;     ...
;             PG8_WAIT_V(8); PG8_WAIT_L(0); PG8_BAR; PG8_MMA(1, 0, At, B0); PG8_MMA(1, 1, At, B1); PG8_BAR; PG8_SCHED;
;             PG8_LDB(B0, 1, 0); PG8_LDB(B1, 1, 1); PG8_SCHED; PG8_LDA(At, 1, 0); PG8_STAGE(PG8_SA(0, 1), a2 + hstepA, voffA);
;             PG8_WAIT_V(8); PG8_WAIT_L(0); PG8_BAR; PG8_MMA(0, 0, At, B0); PG8_MMA(0, 1, At, B1); PG8_BAR; PG8_SCHED;
	s_waitcnt lgkmcnt(0)
	v_mfma_f32_16x16x32_bf16 v[60:63], v[144:147], v[184:187], v[60:63]
	v_mfma_f32_16x16x32_bf16 v[56:59], v[152:155], v[184:187], v[56:59]
	v_mfma_f32_16x16x32_bf16 v[44:47], v[144:147], v[192:195], v[44:47]
	v_mfma_f32_16x16x32_bf16 v[40:43], v[152:155], v[192:195], v[40:43]
	v_mfma_f32_16x16x32_bf16 v[28:31], v[144:147], v[204:207], v[28:31]
	v_mfma_f32_16x16x32_bf16 v[24:27], v[152:155], v[204:207], v[24:27]
	v_mfma_f32_16x16x32_bf16 v[12:15], v[144:147], v[212:215], v[12:15]
	v_mfma_f32_16x16x32_bf16 v[8:11], v[152:155], v[212:215], v[8:11]
	v_mfma_f32_16x16x32_bf16 v[60:63], v[148:151], v[188:191], v[60:63]
	v_mfma_f32_16x16x32_bf16 v[56:59], v[156:159], v[188:191], v[56:59]
	v_mfma_f32_16x16x32_bf16 v[44:47], v[148:151], v[200:203], v[44:47]
	v_mfma_f32_16x16x32_bf16 v[40:43], v[156:159], v[200:203], v[40:43]
	v_mfma_f32_16x16x32_bf16 v[28:31], v[148:151], v[208:211], v[28:31]
	v_mfma_f32_16x16x32_bf16 v[24:27], v[156:159], v[208:211], v[24:27]
	v_mfma_f32_16x16x32_bf16 v[12:15], v[148:151], v[216:219], v[12:15]
	v_mfma_f32_16x16x32_bf16 v[8:11], v[156:159], v[216:219], v[8:11]
	v_mfma_f32_16x16x32_bf16 v[52:55], v[160:163], v[184:187], v[52:55]
	v_mfma_f32_16x16x32_bf16 v[48:51], v[176:179], v[184:187], v[48:51]
	v_mfma_f32_16x16x32_bf16 v[36:39], v[160:163], v[192:195], v[36:39]
	v_mfma_f32_16x16x32_bf16 v[32:35], v[176:179], v[192:195], v[32:35]
	v_mfma_f32_16x16x32_bf16 v[20:23], v[160:163], v[204:207], v[20:23]
	v_mfma_f32_16x16x32_bf16 v[16:19], v[176:179], v[204:207], v[16:19]
	v_mfma_f32_16x16x32_bf16 v[4:7], v[160:163], v[212:215], v[4:7]
	v_mfma_f32_16x16x32_bf16 v[0:3], v[176:179], v[212:215], v[0:3]
	v_mfma_f32_16x16x32_bf16 v[52:55], v[172:175], v[188:191], v[52:55]
	v_mfma_f32_16x16x32_bf16 v[48:51], v[180:183], v[188:191], v[48:51]
	v_mfma_f32_16x16x32_bf16 v[36:39], v[172:175], v[200:203], v[36:39]
	v_mfma_f32_16x16x32_bf16 v[32:35], v[180:183], v[200:203], v[32:35]
	v_mfma_f32_16x16x32_bf16 v[20:23], v[172:175], v[208:211], v[20:23]
	v_mfma_f32_16x16x32_bf16 v[16:19], v[180:183], v[208:211], v[16:19]
	v_mfma_f32_16x16x32_bf16 v[4:7], v[172:175], v[216:219], v[4:7]
	v_mfma_f32_16x16x32_bf16 v[0:3], v[180:183], v[216:219], v[0:3]
	s_barrier
	ds_read_b128 v[144:147], v169
	ds_read_b128 v[148:151], v169 offset:1024
	ds_read_b128 v[152:155], v169 offset:2048
	ds_read_b128 v[156:159], v169 offset:3072
	ds_read_b128 v[160:163], v170
	ds_read_b128 v[172:175], v170 offset:1024
	ds_read_b128 v[176:179], v170 offset:2048
	ds_read_b128 v[180:183], v170 offset:3072
	s_add_u32 s26, s34, 0xb0000
	s_addc_u32 s27, s35, 0
	s_mov_b32 m0, s44
	v_lshl_add_u64 v[226:227], s[26:27], 0, v[128:129]
	ds_read_b128 v[184:187], v168 offset:32768
	ds_read_b128 v[188:191], v168 offset:33792
	ds_read_b128 v[192:195], v168 offset:34816
	ds_read_b128 v[200:203], v168 offset:35840
	ds_read_b128 v[204:207], v168 offset:36864
	ds_read_b128 v[208:211], v168 offset:37888
	ds_read_b128 v[212:215], v168 offset:38912
	ds_read_b128 v[216:219], v168 offset:39936
	global_load_lds_dwordx4 v[226:227], off
	v_lshl_add_u64 v[226:227], s[26:27], 0, v[132:133]
	s_mov_b32 m0, s45
	s_nop 0
	global_load_lds_dwordx4 v[226:227], off
	s_waitcnt vmcnt(8)
	s_waitcnt lgkmcnt(0)
	s_barrier
	s_waitcnt lgkmcnt(0)
	v_mfma_f32_16x16x32_bf16 v[124:127], v[144:147], v[184:187], v[124:127]
	v_mfma_f32_16x16x32_bf16 v[120:123], v[152:155], v[184:187], v[120:123]
	v_mfma_f32_16x16x32_bf16 v[108:111], v[144:147], v[192:195], v[108:111]
	v_mfma_f32_16x16x32_bf16 v[104:107], v[152:155], v[192:195], v[104:107]
	v_mfma_f32_16x16x32_bf16 v[92:95], v[144:147], v[204:207], v[92:95]
	v_mfma_f32_16x16x32_bf16 v[88:91], v[152:155], v[204:207], v[88:91]
	v_mfma_f32_16x16x32_bf16 v[76:79], v[144:147], v[212:215], v[76:79]
	v_mfma_f32_16x16x32_bf16 v[72:75], v[152:155], v[212:215], v[72:75]
	v_mfma_f32_16x16x32_bf16 v[124:127], v[148:151], v[188:191], v[124:127]
	v_mfma_f32_16x16x32_bf16 v[120:123], v[156:159], v[188:191], v[120:123]
	v_mfma_f32_16x16x32_bf16 v[108:111], v[148:151], v[200:203], v[108:111]
	v_mfma_f32_16x16x32_bf16 v[104:107], v[156:159], v[200:203], v[104:107]
	v_mfma_f32_16x16x32_bf16 v[92:95], v[148:151], v[208:211], v[92:95]
	v_mfma_f32_16x16x32_bf16 v[88:91], v[156:159], v[208:211], v[88:91]
	v_mfma_f32_16x16x32_bf16 v[76:79], v[148:151], v[216:219], v[76:79]
	v_mfma_f32_16x16x32_bf16 v[72:75], v[156:159], v[216:219], v[72:75]
	v_mfma_f32_16x16x32_bf16 v[116:119], v[160:163], v[184:187], v[116:119]
	v_mfma_f32_16x16x32_bf16 v[112:115], v[176:179], v[184:187], v[112:115]
	v_mfma_f32_16x16x32_bf16 v[100:103], v[160:163], v[192:195], v[100:103]
	v_mfma_f32_16x16x32_bf16 v[96:99], v[176:179], v[192:195], v[96:99]
	v_mfma_f32_16x16x32_bf16 v[84:87], v[160:163], v[204:207], v[84:87]
	v_mfma_f32_16x16x32_bf16 v[80:83], v[176:179], v[204:207], v[80:83]
	v_mfma_f32_16x16x32_bf16 v[68:71], v[160:163], v[212:215], v[68:71]
	v_mfma_f32_16x16x32_bf16 v[64:67], v[176:179], v[212:215], v[64:67]
	v_mfma_f32_16x16x32_bf16 v[116:119], v[172:175], v[188:191], v[116:119]
	v_mfma_f32_16x16x32_bf16 v[112:115], v[180:183], v[188:191], v[112:115]
	v_mfma_f32_16x16x32_bf16 v[100:103], v[172:175], v[200:203], v[100:103]
	v_mfma_f32_16x16x32_bf16 v[96:99], v[180:183], v[200:203], v[96:99]
	v_mfma_f32_16x16x32_bf16 v[84:87], v[172:175], v[208:211], v[84:87]
	v_mfma_f32_16x16x32_bf16 v[80:83], v[180:183], v[208:211], v[80:83]
	v_mfma_f32_16x16x32_bf16 v[68:71], v[172:175], v[216:219], v[68:71]
	v_mfma_f32_16x16x32_bf16 v[64:67], v[180:183], v[216:219], v[64:67]
	s_barrier
; #define PG8_STAGE(bufoff, gbase, voff) do { _Pragma("unroll") for (int _i = 0; _i < 2; ++_i) \
;         __builtin_amdgcn_global_load_lds((const unsigned*)((const char*)(gbase) + (voff)[_i]), (PG8_LAS unsigned*)(lds + (bufoff) + ldsw + _i * 8192), 16, 0, 0); } while (0)
; #define PG8_LDA(dst, b, h) do { _Pragma("unroll") for (int m = 0; m < 4; ++m) _Pragma("unroll") for (int k = 0; k < 2; ++k) dst[m][k] = *(const PG8_LAS bf16x8*)(lds + PG8_SA(b, h) + aoff + m * 2048 + k * 1024); } while (0)
; #define PG8_MMA(ai, bj, At, Bt) do { __builtin_amdgcn_s_setprio(1); _Pragma("unroll") for (int m = 0; m < 4; ++m) _Pragma("unroll") for (int n = 0; n < 2; ++n) _Pragma("unroll") for (int k = 0; k < 2; ++k) \
;         acc[ai][bj][m][n] = __builtin_amdgcn_mfma_f32_16x16x32_bf16(Bt[n][k], At[m][k], acc[ai][bj][m][n], 0, 0, 0); __builtin_amdgcn_s_setprio(0); } while (0)
; #define PG8_WAIT_V(n) asm volatile("s_waitcnt vmcnt(" #n ")" ::: "memory")
; #define PG8_WAIT_L(n) asm volatile("s_waitcnt lgkmcnt(" #n ")" ::: "memory")
; #define PG8_BAR __builtin_amdgcn_s_barrier()
; #define PG8_SCHED __builtin_amdgcn_sched_barrier(0)
; template <class Epi, class Sched, bool ALIGN_EPI = false, bool SP2 = false>
; __device__ __forceinline__ void gemm_phase(PG8_LAS unsigned char* lds, const Gemm g, const Sched& S, const Epi& E, const int tid) {
;     ...
;             PG8_LDA(At, 1, 1); PG8_STAGE(PG8_SB(1, 0), b3, voffB); PG8_STAGE(PG8_SB(1, 1), b3 + hstep, voffB); PG8_STAGE(PG8_SA(1, 0), a3, voffA);
;             PG8_WAIT_V(8); PG8_WAIT_L(0); PG8_BAR; PG8_MMA(1, 0, At, B0); PG8_MMA(1, 1, At, B1); PG8_BAR; PG8_SCHED;
	s_mov_b32 m0, s48
	v_lshl_add_u64 v[196:197], v[196:197], 0, s[18:19]
	s_add_u32 s26, s30, 0xb0080
	ds_read_b128 v[184:187], v168 offset:49152
	ds_read_b128 v[188:191], v168 offset:50176
	ds_read_b128 v[192:195], v168 offset:51200
	ds_read_b128 v[200:203], v168 offset:52224
	ds_read_b128 v[204:207], v168 offset:53248
	ds_read_b128 v[208:211], v168 offset:54272
	ds_read_b128 v[212:215], v168 offset:55296
	ds_read_b128 v[216:219], v168 offset:56320
	global_load_lds_dwordx4 v[196:197], off
	v_lshl_add_u64 v[196:197], v[220:221], 0, s[18:19]
	s_mov_b32 m0, s49
	s_addc_u32 s27, s31, 0
	global_load_lds_dwordx4 v[196:197], off
	v_lshl_add_u64 v[196:197], s[26:27], 0, v[130:131]
	s_mov_b32 m0, s52
	s_nop 0
	global_load_lds_dwordx4 v[196:197], off
	v_lshl_add_u64 v[196:197], s[26:27], 0, v[134:135]
	s_mov_b32 m0, s53
	s_nop 0
	global_load_lds_dwordx4 v[196:197], off
	v_lshl_add_u64 v[196:197], v[222:223], 0, s[18:19]
	s_mov_b32 m0, s50
	s_nop 0
	global_load_lds_dwordx4 v[196:197], off
	v_lshl_add_u64 v[196:197], v[224:225], 0, s[18:19]
	s_mov_b32 m0, s51
	s_nop 0
	global_load_lds_dwordx4 v[196:197], off
	s_waitcnt vmcnt(8)
	s_waitcnt lgkmcnt(0)
	s_barrier
	s_waitcnt lgkmcnt(0)
	v_mfma_f32_16x16x32_bf16 v[60:63], v[144:147], v[184:187], v[60:63]
	v_mfma_f32_16x16x32_bf16 v[56:59], v[152:155], v[184:187], v[56:59]
	v_mfma_f32_16x16x32_bf16 v[44:47], v[144:147], v[192:195], v[44:47]
	v_mfma_f32_16x16x32_bf16 v[40:43], v[152:155], v[192:195], v[40:43]
	v_mfma_f32_16x16x32_bf16 v[28:31], v[144:147], v[204:207], v[28:31]
	v_mfma_f32_16x16x32_bf16 v[24:27], v[152:155], v[204:207], v[24:27]
	v_mfma_f32_16x16x32_bf16 v[12:15], v[144:147], v[212:215], v[12:15]
	v_mfma_f32_16x16x32_bf16 v[8:11], v[152:155], v[212:215], v[8:11]
	v_mfma_f32_16x16x32_bf16 v[60:63], v[148:151], v[188:191], v[60:63]
	v_mfma_f32_16x16x32_bf16 v[56:59], v[156:159], v[188:191], v[56:59]
	v_mfma_f32_16x16x32_bf16 v[44:47], v[148:151], v[200:203], v[44:47]
	v_mfma_f32_16x16x32_bf16 v[40:43], v[156:159], v[200:203], v[40:43]
	v_mfma_f32_16x16x32_bf16 v[28:31], v[148:151], v[208:211], v[28:31]
	v_mfma_f32_16x16x32_bf16 v[24:27], v[156:159], v[208:211], v[24:27]
	v_mfma_f32_16x16x32_bf16 v[12:15], v[148:151], v[216:219], v[12:15]
	v_mfma_f32_16x16x32_bf16 v[8:11], v[156:159], v[216:219], v[8:11]
	v_mfma_f32_16x16x32_bf16 v[52:55], v[160:163], v[184:187], v[52:55]
	v_mfma_f32_16x16x32_bf16 v[48:51], v[176:179], v[184:187], v[48:51]
	v_mfma_f32_16x16x32_bf16 v[36:39], v[160:163], v[192:195], v[36:39]
	v_mfma_f32_16x16x32_bf16 v[32:35], v[176:179], v[192:195], v[32:35]
	v_mfma_f32_16x16x32_bf16 v[20:23], v[160:163], v[204:207], v[20:23]
	v_mfma_f32_16x16x32_bf16 v[16:19], v[176:179], v[204:207], v[16:19]
	v_mfma_f32_16x16x32_bf16 v[4:7], v[160:163], v[212:215], v[4:7]
	v_mfma_f32_16x16x32_bf16 v[0:3], v[176:179], v[212:215], v[0:3]
	v_mfma_f32_16x16x32_bf16 v[52:55], v[172:175], v[188:191], v[52:55]
	v_mfma_f32_16x16x32_bf16 v[48:51], v[180:183], v[188:191], v[48:51]
	v_mfma_f32_16x16x32_bf16 v[36:39], v[172:175], v[200:203], v[36:39]
	v_mfma_f32_16x16x32_bf16 v[32:35], v[180:183], v[200:203], v[32:35]
	v_mfma_f32_16x16x32_bf16 v[20:23], v[172:175], v[208:211], v[20:23]
	v_mfma_f32_16x16x32_bf16 v[16:19], v[180:183], v[208:211], v[16:19]
	v_mfma_f32_16x16x32_bf16 v[4:7], v[172:175], v[216:219], v[4:7]
	v_mfma_f32_16x16x32_bf16 v[0:3], v[180:183], v[216:219], v[0:3]
	s_barrier
	s_add_i32 s63, s63, 2
	s_add_u32 s61, s61, 0x100
	s_addc_u32 s62, s62, 0
	s_cmp_gt_u32 s63, 41
	s_mov_b64 s[26:27], s[28:29]
	s_cbranch_scc0 .LBB0_923
	s_and_b64 vcc, exec, s[20:21]
	s_cbranch_vccnz .LBB0_927
	s_andn2_b64 vcc, exec, s[22:23]
	s_cbranch_vccz .LBB0_928

; #define PG8_STAGE(bufoff, gbase, voff) do { _Pragma("unroll") for (int _i = 0; _i < 2; ++_i) \
;         __builtin_amdgcn_global_load_lds((const unsigned*)((const char*)(gbase) + (voff)[_i]), (PG8_LAS unsigned*)(lds + (bufoff) + ldsw + _i * 8192), 16, 0, 0); } while (0)
; #define PG8_LDA(dst, b, h) do { _Pragma("unroll") for (int m = 0; m < 4; ++m) _Pragma("unroll") for (int k = 0; k < 2; ++k) dst[m][k] = *(const PG8_LAS bf16x8*)(lds + PG8_SA(b, h) + aoff + m * 2048 + k * 1024); } while (0)
; #define PG8_LDB(dst, b, h) do { _Pragma("unroll") for (int n = 0; n < 2; ++n) _Pragma("unroll") for (int k = 0; k < 2; ++k) dst[n][k] = *(const PG8_LAS bf16x8*)(lds + PG8_SB(b, h) + boff + n * 2048 + k * 1024); } while (0)
; #define PG8_MMA(ai, bj, At, Bt) do { __builtin_amdgcn_s_setprio(1); _Pragma("unroll") for (int m = 0; m < 4; ++m) _Pragma("unroll") for (int n = 0; n < 2; ++n) _Pragma("unroll") for (int k = 0; k < 2; ++k) \
;         acc[ai][bj][m][n] = __builtin_amdgcn_mfma_f32_16x16x32_bf16(Bt[n][k], At[m][k], acc[ai][bj][m][n], 0, 0, 0); __builtin_amdgcn_s_setprio(0); } while (0)
; #define PG8_WAIT_V(n) asm volatile("s_waitcnt vmcnt(" #n ")" ::: "memory")
; #define PG8_WAIT_L(n) asm volatile("s_waitcnt lgkmcnt(" #n ")" ::: "memory")
; template <class Epi, class Sched, bool ALIGN_EPI = false, bool SP2 = false>
; __device__ __forceinline__ void gemm_phase(PG8_LAS unsigned char* lds, const Gemm g, const Sched& S, const Epi& E, const int tid) {
;     ...
;             const bool last = (t == nt - 2);
;             const char* a1 = cA + (size_t)(t + 1) * kstep;
;             const char* a2 = last ? nA : cA + (size_t)(t + 2) * kstep; const char* b2 = last ? nB : cB + (size_t)(t + 2) * kstep;
;             const char* a3 = a2 + kstep; const char* b3 = b2 + kstep;
;             if (last && has_next) S.a_ready(nxt);
;             if constexpr (SP2) {
;             PG8_LDB(B0, 0, 0); PG8_LDB(B1, 0, 1); PG8_SCHED; PG8_LDA(At, 0, 0); PG8_STAGE(PG8_SA(1, 1), a1 + hstepA, voffA);
;             PG8_WAIT_V(8); PG8_WAIT_L(0); PG8_BAR; PG8_MMA(0, 0, At, B0); PG8_MMA(0, 1, At, B1); PG8_BAR; PG8_SCHED;
;             PG8_LDA(At, 0, 1); PG8_STAGE(PG8_SB(0, 0), b2, voffB); PG8_STAGE(PG8_SB(0, 1), b2 + hstep, voffB); PG8_STAGE(PG8_SA(0, 0), a2, voffA);
;             PG8_WAIT_V(8); PG8_WAIT_L(0); PG8_BAR; PG8_MMA(1, 0, At, B0); PG8_MMA(1, 1, At, B1); PG8_BAR; PG8_SCHED;
.LBB0_1007:
	ds_read_b128 v[144:147], v156
	ds_read_b128 v[148:151], v156 offset:1024
	ds_read_b128 v[162:165], v156 offset:2048
	ds_read_b128 v[166:169], v156 offset:3072
	ds_read_b128 v[170:173], v157
	ds_read_b128 v[174:177], v157 offset:1024
	ds_read_b128 v[178:181], v157 offset:2048
	ds_read_b128 v[182:185], v157 offset:3072
	s_add_u32 s28, s26, 0xfffc0080
	s_addc_u32 s29, s27, -1
	s_cmp_eq_u32 s60, 12
	s_cselect_b32 s31, s19, s29
	s_cselect_b32 s30, s56, s28
	s_cselect_b32 s29, s17, s59
	s_cselect_b32 s28, s57, s58
	v_lshl_add_u64 v[152:153], s[26:27], 0, v[136:137]
	s_add_i32 m0, s41, 0xc000
	ds_read_b128 v[186:189], v158
	ds_read_b128 v[190:193], v158 offset:1024
	ds_read_b128 v[194:197], v158 offset:2048
	ds_read_b128 v[200:203], v158 offset:3072
	ds_read_b128 v[204:207], v158 offset:4096
	ds_read_b128 v[208:211], v158 offset:5120
	ds_read_b128 v[212:215], v158 offset:6144
	ds_read_b128 v[216:219], v158 offset:7168
	global_load_lds_dwordx4 v[152:153], off
	v_lshl_add_u64 v[152:153], s[26:27], 0, v[138:139]
	s_add_i32 m0, s41, 0xe000
	s_nop 0
	global_load_lds_dwordx4 v[152:153], off
	s_waitcnt vmcnt(8)
	s_waitcnt lgkmcnt(0)
	s_barrier
	s_waitcnt lgkmcnt(0)
	v_mfma_f32_16x16x32_bf16 v[124:127], v[144:147], v[186:189], v[124:127]
	v_mfma_f32_16x16x32_bf16 v[120:123], v[162:165], v[186:189], v[120:123]
	v_mfma_f32_16x16x32_bf16 v[108:111], v[144:147], v[194:197], v[108:111]
	v_mfma_f32_16x16x32_bf16 v[104:107], v[162:165], v[194:197], v[104:107]
	v_mfma_f32_16x16x32_bf16 v[92:95], v[144:147], v[204:207], v[92:95]
	v_mfma_f32_16x16x32_bf16 v[88:91], v[162:165], v[204:207], v[88:91]
	v_mfma_f32_16x16x32_bf16 v[76:79], v[144:147], v[212:215], v[76:79]
	v_mfma_f32_16x16x32_bf16 v[72:75], v[162:165], v[212:215], v[72:75]
	v_mfma_f32_16x16x32_bf16 v[124:127], v[148:151], v[190:193], v[124:127]
	v_mfma_f32_16x16x32_bf16 v[120:123], v[166:169], v[190:193], v[120:123]
	v_mfma_f32_16x16x32_bf16 v[108:111], v[148:151], v[200:203], v[108:111]
	v_mfma_f32_16x16x32_bf16 v[104:107], v[166:169], v[200:203], v[104:107]
	v_mfma_f32_16x16x32_bf16 v[92:95], v[148:151], v[208:211], v[92:95]
	v_mfma_f32_16x16x32_bf16 v[88:91], v[166:169], v[208:211], v[88:91]
	v_mfma_f32_16x16x32_bf16 v[76:79], v[148:151], v[216:219], v[76:79]
	v_mfma_f32_16x16x32_bf16 v[72:75], v[166:169], v[216:219], v[72:75]
	v_mfma_f32_16x16x32_bf16 v[116:119], v[170:173], v[186:189], v[116:119]
	v_mfma_f32_16x16x32_bf16 v[112:115], v[178:181], v[186:189], v[112:115]
	v_mfma_f32_16x16x32_bf16 v[100:103], v[170:173], v[194:197], v[100:103]
	v_mfma_f32_16x16x32_bf16 v[96:99], v[178:181], v[194:197], v[96:99]
	v_mfma_f32_16x16x32_bf16 v[84:87], v[170:173], v[204:207], v[84:87]
	v_mfma_f32_16x16x32_bf16 v[80:83], v[178:181], v[204:207], v[80:83]
	v_mfma_f32_16x16x32_bf16 v[68:71], v[170:173], v[212:215], v[68:71]
	v_mfma_f32_16x16x32_bf16 v[64:67], v[178:181], v[212:215], v[64:67]
	v_mfma_f32_16x16x32_bf16 v[116:119], v[174:177], v[190:193], v[116:119]
	v_mfma_f32_16x16x32_bf16 v[112:115], v[182:185], v[190:193], v[112:115]
	v_mfma_f32_16x16x32_bf16 v[100:103], v[174:177], v[200:203], v[100:103]
	v_mfma_f32_16x16x32_bf16 v[96:99], v[182:185], v[200:203], v[96:99]
	v_mfma_f32_16x16x32_bf16 v[84:87], v[174:177], v[208:211], v[84:87]
	v_mfma_f32_16x16x32_bf16 v[80:83], v[182:185], v[208:211], v[80:83]
	v_mfma_f32_16x16x32_bf16 v[68:71], v[174:177], v[216:219], v[68:71]
	v_mfma_f32_16x16x32_bf16 v[64:67], v[182:185], v[216:219], v[64:67]
	s_barrier
	s_mov_b32 m0, s25
	v_lshl_add_u64 v[152:153], s[28:29], 0, v[132:133]
	s_add_u32 s62, s28, 0x40000
	ds_read_b128 v[186:189], v158 offset:16384
	ds_read_b128 v[190:193], v158 offset:17408
	ds_read_b128 v[194:197], v158 offset:18432
	ds_read_b128 v[200:203], v158 offset:19456
	ds_read_b128 v[204:207], v158 offset:20480
	ds_read_b128 v[208:211], v158 offset:21504
	ds_read_b128 v[212:215], v158 offset:22528
	ds_read_b128 v[216:219], v158 offset:23552
	global_load_lds_dwordx4 v[152:153], off
	v_lshl_add_u64 v[220:221], s[28:29], 0, v[128:129]
	s_mov_b32 m0, s38
	s_addc_u32 s63, s29, 0
	global_load_lds_dwordx4 v[220:221], off
	v_lshl_add_u64 v[222:223], s[62:63], 0, v[132:133]
	s_mov_b32 m0, s39
	v_lshl_add_u64 v[224:225], s[30:31], 0, v[130:131]
	global_load_lds_dwordx4 v[222:223], off
	v_lshl_add_u64 v[222:223], s[62:63], 0, v[128:129]
	s_mov_b32 m0, s40
	s_nop 0
	global_load_lds_dwordx4 v[222:223], off
	v_lshl_add_u64 v[222:223], s[30:31], 0, v[134:135]
	s_mov_b32 m0, s41
	s_nop 0
	global_load_lds_dwordx4 v[222:223], off
	s_mov_b32 m0, s42
	s_nop 0
	global_load_lds_dwordx4 v[224:225], off
	s_waitcnt vmcnt(8)
	s_waitcnt lgkmcnt(0)
	s_barrier
; #define PG8_STAGE(bufoff, gbase, voff) do { _Pragma("unroll") for (int _i = 0; _i < 2; ++_i) \
;         __builtin_amdgcn_global_load_lds((const unsigned*)((const char*)(gbase) + (voff)[_i]), (PG8_LAS unsigned*)(lds + (bufoff) + ldsw + _i * 8192), 16, 0, 0); } while (0)
; #define PG8_LDA(dst, b, h) do { _Pragma("unroll") for (int m = 0; m < 4; ++m) _Pragma("unroll") for (int k = 0; k < 2; ++k) dst[m][k] = *(const PG8_LAS bf16x8*)(lds + PG8_SA(b, h) + aoff + m * 2048 + k * 1024); } while (0)
; #define PG8_LDB(dst, b, h) do { _Pragma("unroll") for (int n = 0; n < 2; ++n) _Pragma("unroll") for (int k = 0; k < 2; ++k) dst[n][k] = *(const PG8_LAS bf16x8*)(lds + PG8_SB(b, h) + boff + n * 2048 + k * 1024); } while (0)
; #define PG8_MMA(ai, bj, At, Bt) do { __builtin_amdgcn_s_setprio(1); _Pragma("unroll") for (int m = 0; m < 4; ++m) _Pragma("unroll") for (int n = 0; n < 2; ++n) _Pragma("unroll") for (int k = 0; k < 2; ++k) \
;         acc[ai][bj][m][n] = __builtin_amdgcn_mfma_f32_16x16x32_bf16(Bt[n][k], At[m][k], acc[ai][bj][m][n], 0, 0, 0); __builtin_amdgcn_s_setprio(0); } while (0)
; #define PG8_WAIT_V(n) asm volatile("s_waitcnt vmcnt(" #n ")" ::: "memory")
; #define PG8_WAIT_L(n) asm volatile("s_waitcnt lgkmcnt(" #n ")" ::: "memory")
; #define PG8_BAR __builtin_amdgcn_s_barrier()
; #define PG8_SCHED __builtin_amdgcn_sched_barrier(0)
; template <class Epi, class Sched, bool ALIGN_EPI = false, bool SP2 = false>
; __device__ __forceinline__ void gemm_phase(PG8_LAS unsigned char* lds, const Gemm g, const Sched& S, const Epi& E, const int tid) {
;     ...
;             PG8_WAIT_V(8); PG8_WAIT_L(0); PG8_BAR; PG8_MMA(1, 0, At, B0); PG8_MMA(1, 1, At, B1); PG8_BAR; PG8_SCHED;
;             PG8_LDB(B0, 1, 0); PG8_LDB(B1, 1, 1); PG8_SCHED; PG8_LDA(At, 1, 0); PG8_STAGE(PG8_SA(0, 1), a2 + hstepA, voffA);
;             PG8_WAIT_V(8); PG8_WAIT_L(0); PG8_BAR; PG8_MMA(0, 0, At, B0); PG8_MMA(0, 1, At, B1); PG8_BAR; PG8_SCHED;
	s_waitcnt lgkmcnt(0)
	v_mfma_f32_16x16x32_bf16 v[60:63], v[144:147], v[186:189], v[60:63]
	v_mfma_f32_16x16x32_bf16 v[56:59], v[162:165], v[186:189], v[56:59]
	v_mfma_f32_16x16x32_bf16 v[44:47], v[144:147], v[194:197], v[44:47]
	v_mfma_f32_16x16x32_bf16 v[40:43], v[162:165], v[194:197], v[40:43]
	v_mfma_f32_16x16x32_bf16 v[28:31], v[144:147], v[204:207], v[28:31]
	v_mfma_f32_16x16x32_bf16 v[24:27], v[162:165], v[204:207], v[24:27]
	v_mfma_f32_16x16x32_bf16 v[12:15], v[144:147], v[212:215], v[12:15]
	v_mfma_f32_16x16x32_bf16 v[8:11], v[162:165], v[212:215], v[8:11]
	v_mfma_f32_16x16x32_bf16 v[60:63], v[148:151], v[190:193], v[60:63]
	v_mfma_f32_16x16x32_bf16 v[56:59], v[166:169], v[190:193], v[56:59]
	v_mfma_f32_16x16x32_bf16 v[44:47], v[148:151], v[200:203], v[44:47]
	v_mfma_f32_16x16x32_bf16 v[40:43], v[166:169], v[200:203], v[40:43]
	v_mfma_f32_16x16x32_bf16 v[28:31], v[148:151], v[208:211], v[28:31]
	v_mfma_f32_16x16x32_bf16 v[24:27], v[166:169], v[208:211], v[24:27]
	v_mfma_f32_16x16x32_bf16 v[12:15], v[148:151], v[216:219], v[12:15]
	v_mfma_f32_16x16x32_bf16 v[8:11], v[166:169], v[216:219], v[8:11]
	v_mfma_f32_16x16x32_bf16 v[52:55], v[170:173], v[186:189], v[52:55]
	v_mfma_f32_16x16x32_bf16 v[48:51], v[178:181], v[186:189], v[48:51]
	v_mfma_f32_16x16x32_bf16 v[36:39], v[170:173], v[194:197], v[36:39]
	v_mfma_f32_16x16x32_bf16 v[32:35], v[178:181], v[194:197], v[32:35]
	v_mfma_f32_16x16x32_bf16 v[20:23], v[170:173], v[204:207], v[20:23]
	v_mfma_f32_16x16x32_bf16 v[16:19], v[178:181], v[204:207], v[16:19]
	v_mfma_f32_16x16x32_bf16 v[4:7], v[170:173], v[212:215], v[4:7]
	v_mfma_f32_16x16x32_bf16 v[0:3], v[178:181], v[212:215], v[0:3]
	v_mfma_f32_16x16x32_bf16 v[52:55], v[174:177], v[190:193], v[52:55]
	v_mfma_f32_16x16x32_bf16 v[48:51], v[182:185], v[190:193], v[48:51]
	v_mfma_f32_16x16x32_bf16 v[36:39], v[174:177], v[200:203], v[36:39]
	v_mfma_f32_16x16x32_bf16 v[32:35], v[182:185], v[200:203], v[32:35]
	v_mfma_f32_16x16x32_bf16 v[20:23], v[174:177], v[208:211], v[20:23]
	v_mfma_f32_16x16x32_bf16 v[16:19], v[182:185], v[208:211], v[16:19]
	v_mfma_f32_16x16x32_bf16 v[4:7], v[174:177], v[216:219], v[4:7]
	v_mfma_f32_16x16x32_bf16 v[0:3], v[182:185], v[216:219], v[0:3]
	s_barrier
	ds_read_b128 v[144:147], v159
	ds_read_b128 v[148:151], v159 offset:1024
	ds_read_b128 v[162:165], v159 offset:2048
	ds_read_b128 v[166:169], v159 offset:3072
	ds_read_b128 v[170:173], v160
	ds_read_b128 v[174:177], v160 offset:1024
	ds_read_b128 v[178:181], v160 offset:2048
	ds_read_b128 v[182:185], v160 offset:3072
	s_add_u32 s30, s30, 0x40000
	s_addc_u32 s31, s31, 0
	s_mov_b32 m0, s43
	v_lshl_add_u64 v[226:227], s[30:31], 0, v[134:135]
	ds_read_b128 v[186:189], v158 offset:32768
	ds_read_b128 v[190:193], v158 offset:33792
	ds_read_b128 v[194:197], v158 offset:34816
	ds_read_b128 v[200:203], v158 offset:35840
	ds_read_b128 v[204:207], v158 offset:36864
	ds_read_b128 v[208:211], v158 offset:37888
	ds_read_b128 v[212:215], v158 offset:38912
	ds_read_b128 v[216:219], v158 offset:39936
	global_load_lds_dwordx4 v[226:227], off
	v_lshl_add_u64 v[226:227], s[30:31], 0, v[130:131]
	s_mov_b32 m0, s44
	s_nop 0
	global_load_lds_dwordx4 v[226:227], off
	s_waitcnt vmcnt(8)
	s_waitcnt lgkmcnt(0)
	s_barrier
	s_waitcnt lgkmcnt(0)
	v_mfma_f32_16x16x32_bf16 v[124:127], v[144:147], v[186:189], v[124:127]
	v_mfma_f32_16x16x32_bf16 v[120:123], v[162:165], v[186:189], v[120:123]
	v_mfma_f32_16x16x32_bf16 v[108:111], v[144:147], v[194:197], v[108:111]
	v_mfma_f32_16x16x32_bf16 v[104:107], v[162:165], v[194:197], v[104:107]
	v_mfma_f32_16x16x32_bf16 v[92:95], v[144:147], v[204:207], v[92:95]
	v_mfma_f32_16x16x32_bf16 v[88:91], v[162:165], v[204:207], v[88:91]
	v_mfma_f32_16x16x32_bf16 v[76:79], v[144:147], v[212:215], v[76:79]
	v_mfma_f32_16x16x32_bf16 v[72:75], v[162:165], v[212:215], v[72:75]
	v_mfma_f32_16x16x32_bf16 v[124:127], v[148:151], v[190:193], v[124:127]
	v_mfma_f32_16x16x32_bf16 v[120:123], v[166:169], v[190:193], v[120:123]
	v_mfma_f32_16x16x32_bf16 v[108:111], v[148:151], v[200:203], v[108:111]
	v_mfma_f32_16x16x32_bf16 v[104:107], v[166:169], v[200:203], v[104:107]
	v_mfma_f32_16x16x32_bf16 v[92:95], v[148:151], v[208:211], v[92:95]
	v_mfma_f32_16x16x32_bf16 v[88:91], v[166:169], v[208:211], v[88:91]
	v_mfma_f32_16x16x32_bf16 v[76:79], v[148:151], v[216:219], v[76:79]
	v_mfma_f32_16x16x32_bf16 v[72:75], v[166:169], v[216:219], v[72:75]
	v_mfma_f32_16x16x32_bf16 v[116:119], v[170:173], v[186:189], v[116:119]
	v_mfma_f32_16x16x32_bf16 v[112:115], v[178:181], v[186:189], v[112:115]
	v_mfma_f32_16x16x32_bf16 v[100:103], v[170:173], v[194:197], v[100:103]
	v_mfma_f32_16x16x32_bf16 v[96:99], v[178:181], v[194:197], v[96:99]
	v_mfma_f32_16x16x32_bf16 v[84:87], v[170:173], v[204:207], v[84:87]
	v_mfma_f32_16x16x32_bf16 v[80:83], v[178:181], v[204:207], v[80:83]
	v_mfma_f32_16x16x32_bf16 v[68:71], v[170:173], v[212:215], v[68:71]
	v_mfma_f32_16x16x32_bf16 v[64:67], v[178:181], v[212:215], v[64:67]
	v_mfma_f32_16x16x32_bf16 v[116:119], v[174:177], v[190:193], v[116:119]
	v_mfma_f32_16x16x32_bf16 v[112:115], v[182:185], v[190:193], v[112:115]
	v_mfma_f32_16x16x32_bf16 v[100:103], v[174:177], v[200:203], v[100:103]
	v_mfma_f32_16x16x32_bf16 v[96:99], v[182:185], v[200:203], v[96:99]
	v_mfma_f32_16x16x32_bf16 v[84:87], v[174:177], v[208:211], v[84:87]
	v_mfma_f32_16x16x32_bf16 v[80:83], v[182:185], v[208:211], v[80:83]
	v_mfma_f32_16x16x32_bf16 v[68:71], v[174:177], v[216:219], v[68:71]
	v_mfma_f32_16x16x32_bf16 v[64:67], v[182:185], v[216:219], v[64:67]
	s_barrier
; #define PG8_STAGE(bufoff, gbase, voff) do { _Pragma("unroll") for (int _i = 0; _i < 2; ++_i) \
;         __builtin_amdgcn_global_load_lds((const unsigned*)((const char*)(gbase) + (voff)[_i]), (PG8_LAS unsigned*)(lds + (bufoff) + ldsw + _i * 8192), 16, 0, 0); } while (0)
; #define PG8_LDA(dst, b, h) do { _Pragma("unroll") for (int m = 0; m < 4; ++m) _Pragma("unroll") for (int k = 0; k < 2; ++k) dst[m][k] = *(const PG8_LAS bf16x8*)(lds + PG8_SA(b, h) + aoff + m * 2048 + k * 1024); } while (0)
; #define PG8_MMA(ai, bj, At, Bt) do { __builtin_amdgcn_s_setprio(1); _Pragma("unroll") for (int m = 0; m < 4; ++m) _Pragma("unroll") for (int n = 0; n < 2; ++n) _Pragma("unroll") for (int k = 0; k < 2; ++k) \
;         acc[ai][bj][m][n] = __builtin_amdgcn_mfma_f32_16x16x32_bf16(Bt[n][k], At[m][k], acc[ai][bj][m][n], 0, 0, 0); __builtin_amdgcn_s_setprio(0); } while (0)
; #define PG8_WAIT_V(n) asm volatile("s_waitcnt vmcnt(" #n ")" ::: "memory")
; #define PG8_WAIT_L(n) asm volatile("s_waitcnt lgkmcnt(" #n ")" ::: "memory")
; #define PG8_BAR __builtin_amdgcn_s_barrier()
; #define PG8_SCHED __builtin_amdgcn_sched_barrier(0)
; __device__ __forceinline__ float ss_scale(const u64* ss, int row) { return __builtin_amdgcn_rsqf((float)ss[row] * (1.f / 4294967296.f / 1024.f) + EPS); }
; template <class Epi, class Sched, bool ALIGN_EPI = false, bool SP2 = false>
; __device__ __forceinline__ void gemm_phase(PG8_LAS unsigned char* lds, const Gemm g, const Sched& S, const Epi& E, const int tid) {
;     ...
;             PG8_LDA(At, 1, 1); PG8_STAGE(PG8_SB(1, 0), b3, voffB); PG8_STAGE(PG8_SB(1, 1), b3 + hstep, voffB); PG8_STAGE(PG8_SA(1, 0), a3, voffA);
;             PG8_WAIT_V(8); PG8_WAIT_L(0); PG8_BAR; PG8_MMA(1, 0, At, B0); PG8_MMA(1, 1, At, B1); PG8_BAR; PG8_SCHED;
;     __device__ __forceinline__ void operator()(const f32x4 (&acc)[2][2][4][2], const pg8::Unit& u, int wr, int wc, int fr, int fq) const {
;         const int row0 = u.pm * 256 + wr * 64 + fr, col0 = u.pn * 128 + wc * 32 + 8 * fq;
; #pragma unroll
;         for (int ai = 0; ai < 2; ++ai)
; #pragma unroll
;             for (int m = 0; m < 4; ++m) {
;                 const int row = row0 + ai * 128 + m * 16;
;                 float s = ss_scale(ss, row);
;                 if constexpr (NN) s *= __builtin_amdgcn_rsqf(s * s * (float)ssw[row] * (1.f / 4294967296.f / 1024.f) + EPS);
	s_mov_b32 m0, s47
	v_lshl_add_u64 v[152:153], v[152:153], 0, s[12:13]
	s_add_u32 s28, s28, 0x40080
	ds_read_b128 v[186:189], v158 offset:49152
	ds_read_b128 v[190:193], v158 offset:50176
	ds_read_b128 v[194:197], v158 offset:51200
	ds_read_b128 v[200:203], v158 offset:52224
	ds_read_b128 v[204:207], v158 offset:53248
	ds_read_b128 v[208:211], v158 offset:54272
	ds_read_b128 v[212:215], v158 offset:55296
	ds_read_b128 v[216:219], v158 offset:56320
	global_load_lds_dwordx4 v[152:153], off
	v_lshl_add_u64 v[152:153], v[220:221], 0, s[12:13]
	s_mov_b32 m0, s48
	s_addc_u32 s29, s29, 0
	global_load_lds_dwordx4 v[152:153], off
	v_lshl_add_u64 v[152:153], s[28:29], 0, v[132:133]
	s_mov_b32 m0, s51
	s_nop 0
	global_load_lds_dwordx4 v[152:153], off
	v_lshl_add_u64 v[152:153], s[28:29], 0, v[128:129]
	s_mov_b32 m0, s52
	s_nop 0
	global_load_lds_dwordx4 v[152:153], off
	v_lshl_add_u64 v[152:153], v[222:223], 0, s[12:13]
	s_mov_b32 m0, s49
	s_nop 0
	global_load_lds_dwordx4 v[152:153], off
	v_lshl_add_u64 v[152:153], v[224:225], 0, s[12:13]
	s_mov_b32 m0, s50
	s_nop 0
	global_load_lds_dwordx4 v[152:153], off
	s_waitcnt vmcnt(8)
	s_waitcnt lgkmcnt(0)
	s_barrier
	s_waitcnt lgkmcnt(0)
	v_mfma_f32_16x16x32_bf16 v[60:63], v[144:147], v[186:189], v[60:63]
	v_mfma_f32_16x16x32_bf16 v[56:59], v[162:165], v[186:189], v[56:59]
	v_mfma_f32_16x16x32_bf16 v[44:47], v[144:147], v[194:197], v[44:47]
	v_mfma_f32_16x16x32_bf16 v[40:43], v[162:165], v[194:197], v[40:43]
	v_mfma_f32_16x16x32_bf16 v[28:31], v[144:147], v[204:207], v[28:31]
	v_mfma_f32_16x16x32_bf16 v[24:27], v[162:165], v[204:207], v[24:27]
	v_mfma_f32_16x16x32_bf16 v[12:15], v[144:147], v[212:215], v[12:15]
	v_mfma_f32_16x16x32_bf16 v[8:11], v[162:165], v[212:215], v[8:11]
	v_mfma_f32_16x16x32_bf16 v[60:63], v[148:151], v[190:193], v[60:63]
	v_mfma_f32_16x16x32_bf16 v[56:59], v[166:169], v[190:193], v[56:59]
	v_mfma_f32_16x16x32_bf16 v[44:47], v[148:151], v[200:203], v[44:47]
	v_mfma_f32_16x16x32_bf16 v[40:43], v[166:169], v[200:203], v[40:43]
	v_mfma_f32_16x16x32_bf16 v[28:31], v[148:151], v[208:211], v[28:31]
	v_mfma_f32_16x16x32_bf16 v[24:27], v[166:169], v[208:211], v[24:27]
	v_mfma_f32_16x16x32_bf16 v[12:15], v[148:151], v[216:219], v[12:15]
	v_mfma_f32_16x16x32_bf16 v[8:11], v[166:169], v[216:219], v[8:11]
	v_mfma_f32_16x16x32_bf16 v[52:55], v[170:173], v[186:189], v[52:55]
	v_mfma_f32_16x16x32_bf16 v[48:51], v[178:181], v[186:189], v[48:51]
	v_mfma_f32_16x16x32_bf16 v[36:39], v[170:173], v[194:197], v[36:39]
	v_mfma_f32_16x16x32_bf16 v[32:35], v[178:181], v[194:197], v[32:35]
	v_mfma_f32_16x16x32_bf16 v[20:23], v[170:173], v[204:207], v[20:23]
	v_mfma_f32_16x16x32_bf16 v[16:19], v[178:181], v[204:207], v[16:19]
	v_mfma_f32_16x16x32_bf16 v[4:7], v[170:173], v[212:215], v[4:7]
	v_mfma_f32_16x16x32_bf16 v[0:3], v[178:181], v[212:215], v[0:3]
	v_mfma_f32_16x16x32_bf16 v[52:55], v[174:177], v[190:193], v[52:55]
	v_mfma_f32_16x16x32_bf16 v[48:51], v[182:185], v[190:193], v[48:51]
	v_mfma_f32_16x16x32_bf16 v[36:39], v[174:177], v[200:203], v[36:39]
	v_mfma_f32_16x16x32_bf16 v[32:35], v[182:185], v[200:203], v[32:35]
	v_mfma_f32_16x16x32_bf16 v[20:23], v[174:177], v[208:211], v[20:23]
	v_mfma_f32_16x16x32_bf16 v[16:19], v[182:185], v[208:211], v[16:19]
	v_mfma_f32_16x16x32_bf16 v[4:7], v[174:177], v[216:219], v[4:7]
	v_mfma_f32_16x16x32_bf16 v[0:3], v[182:185], v[216:219], v[0:3]
	s_barrier
	s_add_i32 s60, s60, 2
	s_add_u32 s26, s26, 0x100
	s_addc_u32 s27, s27, 0
	s_add_u32 s58, s58, 0x100
	s_addc_u32 s59, s59, 0
	s_cmp_gt_u32 s60, 13
	s_cbranch_scc0 .LBB0_1007
	v_lshl_add_u32 v144, s24, 8, v154
	v_mov_b32_e32 v145, 0
	v_lshl_add_u64 v[150:151], v[144:145], 3, s[8:9]
	global_load_dwordx2 v[176:177], v[150:151], off
	global_load_dwordx2 v[178:179], v[150:151], off offset:128
	global_load_dwordx2 v[180:181], v[150:151], off offset:256
	global_load_dwordx2 v[182:183], v[150:151], off offset:384
	global_load_dwordx2 v[184:185], v[150:151], off offset:1024
	global_load_dwordx2 v[186:187], v[150:151], off offset:1152
	global_load_dwordx2 v[188:189], v[150:151], off offset:1280
	global_load_dwordx2 v[190:191], v[150:151], off offset:1408
	v_lshl_add_u64 v[210:211], v[144:145], 3, s[10:11]
	global_load_dwordx2 v[192:193], v[210:211], off
	global_load_dwordx2 v[194:195], v[210:211], off offset:128
	global_load_dwordx2 v[196:197], v[210:211], off offset:256
	global_load_dwordx2 v[200:201], v[210:211], off offset:384
	global_load_dwordx2 v[202:203], v[210:211], off offset:1024
	global_load_dwordx2 v[204:205], v[210:211], off offset:1152
	global_load_dwordx2 v[206:207], v[210:211], off offset:1280
	global_load_dwordx2 v[208:209], v[210:211], off offset:1408
	v_lshl_or_b32 v148, s55, 7, v155
	v_mul_u32_u24_e32 v146, s54, v144
	v_lshl_add_u32 v146, v148, 1, v146
	v_mov_b32_e32 v147, 0
	v_lshl_add_u64 v[146:147], v[146:147], 0, s[6:7]
	v_mov_b32_e32 v164, 1.0
	v_mov_b32_e32 v165, 1.0
	s_mov_b32 s101, 0
	s_and_b64 vcc, exec, s[14:15]
	s_cbranch_vccz .LBB0_1010
	s_barrier

; #define PG8_STAGE(bufoff, gbase, voff) do { _Pragma("unroll") for (int _i = 0; _i < 2; ++_i) \
;         __builtin_amdgcn_global_load_lds((const unsigned*)((const char*)(gbase) + (voff)[_i]), (PG8_LAS unsigned*)(lds + (bufoff) + ldsw + _i * 8192), 16, 0, 0); } while (0)
; #define PG8_LDA(dst, b, h) do { _Pragma("unroll") for (int m = 0; m < 4; ++m) _Pragma("unroll") for (int k = 0; k < 2; ++k) dst[m][k] = *(const PG8_LAS bf16x8*)(lds + PG8_SA(b, h) + aoff + m * 2048 + k * 1024); } while (0)
; #define PG8_LDB(dst, b, h) do { _Pragma("unroll") for (int n = 0; n < 2; ++n) _Pragma("unroll") for (int k = 0; k < 2; ++k) dst[n][k] = *(const PG8_LAS bf16x8*)(lds + PG8_SB(b, h) + boff + n * 2048 + k * 1024); } while (0)
; #define PG8_MMA(ai, bj, At, Bt) do { __builtin_amdgcn_s_setprio(1); _Pragma("unroll") for (int m = 0; m < 4; ++m) _Pragma("unroll") for (int n = 0; n < 2; ++n) _Pragma("unroll") for (int k = 0; k < 2; ++k) \
;         acc[ai][bj][m][n] = __builtin_amdgcn_mfma_f32_16x16x32_bf16(Bt[n][k], At[m][k], acc[ai][bj][m][n], 0, 0, 0); __builtin_amdgcn_s_setprio(0); } while (0)
; #define PG8_WAIT_V(n) asm volatile("s_waitcnt vmcnt(" #n ")" ::: "memory")
; #define PG8_WAIT_L(n) asm volatile("s_waitcnt lgkmcnt(" #n ")" ::: "memory")
; template <class Epi, class Sched, bool ALIGN_EPI = false, bool SP2 = false>
; __device__ __forceinline__ void gemm_phase(PG8_LAS unsigned char* lds, const Gemm g, const Sched& S, const Epi& E, const int tid) {
;     ...
;             const bool last = (t == nt - 2);
;             const char* a1 = cA + (size_t)(t + 1) * kstep;
;             const char* a2 = last ? nA : cA + (size_t)(t + 2) * kstep; const char* b2 = last ? nB : cB + (size_t)(t + 2) * kstep;
;             const char* a3 = a2 + kstep; const char* b3 = b2 + kstep;
;             if (last && has_next) S.a_ready(nxt);
;             if constexpr (SP2) {
;             PG8_LDB(B0, 0, 0); PG8_LDB(B1, 0, 1); PG8_SCHED; PG8_LDA(At, 0, 0); PG8_STAGE(PG8_SA(1, 1), a1 + hstepA, voffA);
;             PG8_WAIT_V(8); PG8_WAIT_L(0); PG8_BAR; PG8_MMA(0, 0, At, B0); PG8_MMA(0, 1, At, B1); PG8_BAR; PG8_SCHED;
;             PG8_LDA(At, 0, 1); PG8_STAGE(PG8_SB(0, 0), b2, voffB); PG8_STAGE(PG8_SB(0, 1), b2 + hstep, voffB); PG8_STAGE(PG8_SA(0, 0), a2, voffA);
;             PG8_WAIT_V(8); PG8_WAIT_L(0); PG8_BAR; PG8_MMA(1, 0, At, B0); PG8_MMA(1, 1, At, B1); PG8_BAR; PG8_SCHED;
.LBB0_1081:
	ds_read_b128 v[80:83], v168
	ds_read_b128 v[84:87], v168 offset:1024
	ds_read_b128 v[88:91], v168 offset:2048
	ds_read_b128 v[92:95], v168 offset:3072
	ds_read_b128 v[160:163], v169
	ds_read_b128 v[176:179], v169 offset:1024
	ds_read_b128 v[180:183], v169 offset:2048
	ds_read_b128 v[184:187], v169 offset:3072
	s_add_u32 s28, s26, 0x100
	s_addc_u32 s29, s27, 0
	s_cmp_eq_u32 s63, 40
	s_cselect_b32 s35, s7, s29
	s_cselect_b32 s34, s6, s28
	s_cselect_b32 s31, s25, s62
	s_cselect_b32 s30, s24, s61
	v_lshl_add_u64 v[164:165], s[26:27], 0, v[152:153]
	s_add_i32 m0, s42, 0xc000
	ds_read_b128 v[188:191], v170
	ds_read_b128 v[192:195], v170 offset:1024
	ds_read_b128 v[200:203], v170 offset:2048
	ds_read_b128 v[204:207], v170 offset:3072
	ds_read_b128 v[208:211], v170 offset:4096
	ds_read_b128 v[212:215], v170 offset:5120
	ds_read_b128 v[216:219], v170 offset:6144
	ds_read_b128 v[220:223], v170 offset:7168
	global_load_lds_dwordx4 v[164:165], off
	v_lshl_add_u64 v[164:165], s[26:27], 0, v[154:155]
	s_add_i32 m0, s42, 0xe000
	s_nop 0
	global_load_lds_dwordx4 v[164:165], off
	s_waitcnt vmcnt(8)
	s_waitcnt lgkmcnt(0)
	s_barrier
	s_waitcnt lgkmcnt(0)
	v_mfma_f32_16x16x32_bf16 v[140:143], v[80:83], v[188:191], v[140:143]
	v_mfma_f32_16x16x32_bf16 v[136:139], v[88:91], v[188:191], v[136:139]
	v_mfma_f32_16x16x32_bf16 v[124:127], v[80:83], v[200:203], v[124:127]
	v_mfma_f32_16x16x32_bf16 v[120:123], v[88:91], v[200:203], v[120:123]
	v_mfma_f32_16x16x32_bf16 v[108:111], v[80:83], v[208:211], v[108:111]
	v_mfma_f32_16x16x32_bf16 v[104:107], v[88:91], v[208:211], v[104:107]
	v_mfma_f32_16x16x32_bf16 v[76:79], v[80:83], v[216:219], v[76:79]
	v_mfma_f32_16x16x32_bf16 v[72:75], v[88:91], v[216:219], v[72:75]
	v_mfma_f32_16x16x32_bf16 v[140:143], v[84:87], v[192:195], v[140:143]
	v_mfma_f32_16x16x32_bf16 v[136:139], v[92:95], v[192:195], v[136:139]
	v_mfma_f32_16x16x32_bf16 v[124:127], v[84:87], v[204:207], v[124:127]
	v_mfma_f32_16x16x32_bf16 v[120:123], v[92:95], v[204:207], v[120:123]
	v_mfma_f32_16x16x32_bf16 v[108:111], v[84:87], v[212:215], v[108:111]
	v_mfma_f32_16x16x32_bf16 v[104:107], v[92:95], v[212:215], v[104:107]
	v_mfma_f32_16x16x32_bf16 v[76:79], v[84:87], v[220:223], v[76:79]
	v_mfma_f32_16x16x32_bf16 v[72:75], v[92:95], v[220:223], v[72:75]
	v_mfma_f32_16x16x32_bf16 v[132:135], v[160:163], v[188:191], v[132:135]
	v_mfma_f32_16x16x32_bf16 v[128:131], v[180:183], v[188:191], v[128:131]
	v_mfma_f32_16x16x32_bf16 v[116:119], v[160:163], v[200:203], v[116:119]
	v_mfma_f32_16x16x32_bf16 v[112:115], v[180:183], v[200:203], v[112:115]
	v_mfma_f32_16x16x32_bf16 v[100:103], v[160:163], v[208:211], v[100:103]
	v_mfma_f32_16x16x32_bf16 v[96:99], v[180:183], v[208:211], v[96:99]
	v_mfma_f32_16x16x32_bf16 v[68:71], v[160:163], v[216:219], v[68:71]
	v_mfma_f32_16x16x32_bf16 v[64:67], v[180:183], v[216:219], v[64:67]
	v_mfma_f32_16x16x32_bf16 v[132:135], v[176:179], v[192:195], v[132:135]
	v_mfma_f32_16x16x32_bf16 v[128:131], v[184:187], v[192:195], v[128:131]
	v_mfma_f32_16x16x32_bf16 v[116:119], v[176:179], v[204:207], v[116:119]
	v_mfma_f32_16x16x32_bf16 v[112:115], v[184:187], v[204:207], v[112:115]
	v_mfma_f32_16x16x32_bf16 v[100:103], v[176:179], v[212:215], v[100:103]
	v_mfma_f32_16x16x32_bf16 v[96:99], v[184:187], v[212:215], v[96:99]
	v_mfma_f32_16x16x32_bf16 v[68:71], v[176:179], v[220:223], v[68:71]
	v_mfma_f32_16x16x32_bf16 v[64:67], v[184:187], v[220:223], v[64:67]
	s_barrier
	s_mov_b32 m0, s38
	v_lshl_add_u64 v[164:165], s[30:31], 0, v[146:147]
	s_add_u32 s26, s30, 0xb0000
	ds_read_b128 v[188:191], v170 offset:16384
	ds_read_b128 v[192:195], v170 offset:17408
	ds_read_b128 v[200:203], v170 offset:18432
	ds_read_b128 v[204:207], v170 offset:19456
	ds_read_b128 v[208:211], v170 offset:20480
	ds_read_b128 v[212:215], v170 offset:21504
	ds_read_b128 v[216:219], v170 offset:22528
	ds_read_b128 v[220:223], v170 offset:23552
	global_load_lds_dwordx4 v[164:165], off
	v_lshl_add_u64 v[196:197], s[30:31], 0, v[150:151]
	s_mov_b32 m0, s39
	s_addc_u32 s27, s31, 0
	global_load_lds_dwordx4 v[196:197], off
	v_lshl_add_u64 v[224:225], s[26:27], 0, v[146:147]
	s_mov_b32 m0, s40
	v_lshl_add_u64 v[226:227], s[34:35], 0, v[148:149]
	global_load_lds_dwordx4 v[224:225], off
	v_lshl_add_u64 v[224:225], s[26:27], 0, v[150:151]
	s_mov_b32 m0, s41
	s_nop 0
	global_load_lds_dwordx4 v[224:225], off
	v_lshl_add_u64 v[224:225], s[34:35], 0, v[144:145]
	s_mov_b32 m0, s42
	s_nop 0
	global_load_lds_dwordx4 v[224:225], off
	s_mov_b32 m0, s43
	s_nop 0
	global_load_lds_dwordx4 v[226:227], off
	s_waitcnt vmcnt(8)
	s_waitcnt lgkmcnt(0)
	s_barrier
; #define PG8_STAGE(bufoff, gbase, voff) do { _Pragma("unroll") for (int _i = 0; _i < 2; ++_i) \
;         __builtin_amdgcn_global_load_lds((const unsigned*)((const char*)(gbase) + (voff)[_i]), (PG8_LAS unsigned*)(lds + (bufoff) + ldsw + _i * 8192), 16, 0, 0); } while (0)
; #define PG8_LDA(dst, b, h) do { _Pragma("unroll") for (int m = 0; m < 4; ++m) _Pragma("unroll") for (int k = 0; k < 2; ++k) dst[m][k] = *(const PG8_LAS bf16x8*)(lds + PG8_SA(b, h) + aoff + m * 2048 + k * 1024); } while (0)
; #define PG8_LDB(dst, b, h) do { _Pragma("unroll") for (int n = 0; n < 2; ++n) _Pragma("unroll") for (int k = 0; k < 2; ++k) dst[n][k] = *(const PG8_LAS bf16x8*)(lds + PG8_SB(b, h) + boff + n * 2048 + k * 1024); } while (0)
; #define PG8_MMA(ai, bj, At, Bt) do { __builtin_amdgcn_s_setprio(1); _Pragma("unroll") for (int m = 0; m < 4; ++m) _Pragma("unroll") for (int n = 0; n < 2; ++n) _Pragma("unroll") for (int k = 0; k < 2; ++k) \
;         acc[ai][bj][m][n] = __builtin_amdgcn_mfma_f32_16x16x32_bf16(Bt[n][k], At[m][k], acc[ai][bj][m][n], 0, 0, 0); __builtin_amdgcn_s_setprio(0); } while (0)
; #define PG8_WAIT_V(n) asm volatile("s_waitcnt vmcnt(" #n ")" ::: "memory")
; #define PG8_WAIT_L(n) asm volatile("s_waitcnt lgkmcnt(" #n ")" ::: "memory")
; #define PG8_BAR __builtin_amdgcn_s_barrier()
; #define PG8_SCHED __builtin_amdgcn_sched_barrier(0)
; template <class Epi, class Sched, bool ALIGN_EPI = false, bool SP2 = false>
; __device__ __forceinline__ void gemm_phase(PG8_LAS unsigned char* lds, const Gemm g, const Sched& S, const Epi& E, const int tid) {
;     ...
;             PG8_WAIT_V(8); PG8_WAIT_L(0); PG8_BAR; PG8_MMA(1, 0, At, B0); PG8_MMA(1, 1, At, B1); PG8_BAR; PG8_SCHED;
;             PG8_LDB(B0, 1, 0); PG8_LDB(B1, 1, 1); PG8_SCHED; PG8_LDA(At, 1, 0); PG8_STAGE(PG8_SA(0, 1), a2 + hstepA, voffA);
;             PG8_WAIT_V(8); PG8_WAIT_L(0); PG8_BAR; PG8_MMA(0, 0, At, B0); PG8_MMA(0, 1, At, B1); PG8_BAR; PG8_SCHED;
	s_waitcnt lgkmcnt(0)
	v_mfma_f32_16x16x32_bf16 v[60:63], v[80:83], v[188:191], v[60:63]
	v_mfma_f32_16x16x32_bf16 v[56:59], v[88:91], v[188:191], v[56:59]
	v_mfma_f32_16x16x32_bf16 v[44:47], v[80:83], v[200:203], v[44:47]
	v_mfma_f32_16x16x32_bf16 v[40:43], v[88:91], v[200:203], v[40:43]
	v_mfma_f32_16x16x32_bf16 v[28:31], v[80:83], v[208:211], v[28:31]
	v_mfma_f32_16x16x32_bf16 v[24:27], v[88:91], v[208:211], v[24:27]
	v_mfma_f32_16x16x32_bf16 v[12:15], v[80:83], v[216:219], v[12:15]
	v_mfma_f32_16x16x32_bf16 v[8:11], v[88:91], v[216:219], v[8:11]
	v_mfma_f32_16x16x32_bf16 v[60:63], v[84:87], v[192:195], v[60:63]
	v_mfma_f32_16x16x32_bf16 v[56:59], v[92:95], v[192:195], v[56:59]
	v_mfma_f32_16x16x32_bf16 v[44:47], v[84:87], v[204:207], v[44:47]
	v_mfma_f32_16x16x32_bf16 v[40:43], v[92:95], v[204:207], v[40:43]
	v_mfma_f32_16x16x32_bf16 v[28:31], v[84:87], v[212:215], v[28:31]
	v_mfma_f32_16x16x32_bf16 v[24:27], v[92:95], v[212:215], v[24:27]
	v_mfma_f32_16x16x32_bf16 v[12:15], v[84:87], v[220:223], v[12:15]
	v_mfma_f32_16x16x32_bf16 v[8:11], v[92:95], v[220:223], v[8:11]
	v_mfma_f32_16x16x32_bf16 v[52:55], v[160:163], v[188:191], v[52:55]
	v_mfma_f32_16x16x32_bf16 v[48:51], v[180:183], v[188:191], v[48:51]
	v_mfma_f32_16x16x32_bf16 v[36:39], v[160:163], v[200:203], v[36:39]
	v_mfma_f32_16x16x32_bf16 v[32:35], v[180:183], v[200:203], v[32:35]
	v_mfma_f32_16x16x32_bf16 v[20:23], v[160:163], v[208:211], v[20:23]
	v_mfma_f32_16x16x32_bf16 v[16:19], v[180:183], v[208:211], v[16:19]
	v_mfma_f32_16x16x32_bf16 v[4:7], v[160:163], v[216:219], v[4:7]
	v_mfma_f32_16x16x32_bf16 v[0:3], v[180:183], v[216:219], v[0:3]
	v_mfma_f32_16x16x32_bf16 v[52:55], v[176:179], v[192:195], v[52:55]
	v_mfma_f32_16x16x32_bf16 v[48:51], v[184:187], v[192:195], v[48:51]
	v_mfma_f32_16x16x32_bf16 v[36:39], v[176:179], v[204:207], v[36:39]
	v_mfma_f32_16x16x32_bf16 v[32:35], v[184:187], v[204:207], v[32:35]
	v_mfma_f32_16x16x32_bf16 v[20:23], v[176:179], v[212:215], v[20:23]
	v_mfma_f32_16x16x32_bf16 v[16:19], v[184:187], v[212:215], v[16:19]
	v_mfma_f32_16x16x32_bf16 v[4:7], v[176:179], v[220:223], v[4:7]
	v_mfma_f32_16x16x32_bf16 v[0:3], v[184:187], v[220:223], v[0:3]
	s_barrier
	ds_read_b128 v[80:83], v171
	ds_read_b128 v[84:87], v171 offset:1024
	ds_read_b128 v[88:91], v171 offset:2048
	ds_read_b128 v[92:95], v171 offset:3072
	ds_read_b128 v[160:163], v172
	ds_read_b128 v[176:179], v172 offset:1024
	ds_read_b128 v[180:183], v172 offset:2048
	ds_read_b128 v[184:187], v172 offset:3072
	s_add_u32 s26, s34, 0xb0000
	s_addc_u32 s27, s35, 0
	s_mov_b32 m0, s44
	v_lshl_add_u64 v[228:229], s[26:27], 0, v[144:145]
	ds_read_b128 v[188:191], v170 offset:32768
	ds_read_b128 v[192:195], v170 offset:33792
	ds_read_b128 v[200:203], v170 offset:34816
	ds_read_b128 v[204:207], v170 offset:35840
	ds_read_b128 v[208:211], v170 offset:36864
	ds_read_b128 v[212:215], v170 offset:37888
	ds_read_b128 v[216:219], v170 offset:38912
	ds_read_b128 v[220:223], v170 offset:39936
	global_load_lds_dwordx4 v[228:229], off
	v_lshl_add_u64 v[228:229], s[26:27], 0, v[148:149]
	s_mov_b32 m0, s45
	s_nop 0
	global_load_lds_dwordx4 v[228:229], off
	s_waitcnt vmcnt(8)
	s_waitcnt lgkmcnt(0)
	s_barrier
	s_waitcnt lgkmcnt(0)
	v_mfma_f32_16x16x32_bf16 v[140:143], v[80:83], v[188:191], v[140:143]
	v_mfma_f32_16x16x32_bf16 v[136:139], v[88:91], v[188:191], v[136:139]
	v_mfma_f32_16x16x32_bf16 v[124:127], v[80:83], v[200:203], v[124:127]
	v_mfma_f32_16x16x32_bf16 v[120:123], v[88:91], v[200:203], v[120:123]
	v_mfma_f32_16x16x32_bf16 v[108:111], v[80:83], v[208:211], v[108:111]
	v_mfma_f32_16x16x32_bf16 v[104:107], v[88:91], v[208:211], v[104:107]
	v_mfma_f32_16x16x32_bf16 v[76:79], v[80:83], v[216:219], v[76:79]
	v_mfma_f32_16x16x32_bf16 v[72:75], v[88:91], v[216:219], v[72:75]
	v_mfma_f32_16x16x32_bf16 v[140:143], v[84:87], v[192:195], v[140:143]
	v_mfma_f32_16x16x32_bf16 v[136:139], v[92:95], v[192:195], v[136:139]
	v_mfma_f32_16x16x32_bf16 v[124:127], v[84:87], v[204:207], v[124:127]
	v_mfma_f32_16x16x32_bf16 v[120:123], v[92:95], v[204:207], v[120:123]
	v_mfma_f32_16x16x32_bf16 v[108:111], v[84:87], v[212:215], v[108:111]
	v_mfma_f32_16x16x32_bf16 v[104:107], v[92:95], v[212:215], v[104:107]
	v_mfma_f32_16x16x32_bf16 v[76:79], v[84:87], v[220:223], v[76:79]
	v_mfma_f32_16x16x32_bf16 v[72:75], v[92:95], v[220:223], v[72:75]
	v_mfma_f32_16x16x32_bf16 v[132:135], v[160:163], v[188:191], v[132:135]
	v_mfma_f32_16x16x32_bf16 v[128:131], v[180:183], v[188:191], v[128:131]
	v_mfma_f32_16x16x32_bf16 v[116:119], v[160:163], v[200:203], v[116:119]
	v_mfma_f32_16x16x32_bf16 v[112:115], v[180:183], v[200:203], v[112:115]
	v_mfma_f32_16x16x32_bf16 v[100:103], v[160:163], v[208:211], v[100:103]
	v_mfma_f32_16x16x32_bf16 v[96:99], v[180:183], v[208:211], v[96:99]
	v_mfma_f32_16x16x32_bf16 v[68:71], v[160:163], v[216:219], v[68:71]
	v_mfma_f32_16x16x32_bf16 v[64:67], v[180:183], v[216:219], v[64:67]
	v_mfma_f32_16x16x32_bf16 v[132:135], v[176:179], v[192:195], v[132:135]
	v_mfma_f32_16x16x32_bf16 v[128:131], v[184:187], v[192:195], v[128:131]
	v_mfma_f32_16x16x32_bf16 v[116:119], v[176:179], v[204:207], v[116:119]
	v_mfma_f32_16x16x32_bf16 v[112:115], v[184:187], v[204:207], v[112:115]
	v_mfma_f32_16x16x32_bf16 v[100:103], v[176:179], v[212:215], v[100:103]
	v_mfma_f32_16x16x32_bf16 v[96:99], v[184:187], v[212:215], v[96:99]
	v_mfma_f32_16x16x32_bf16 v[68:71], v[176:179], v[220:223], v[68:71]
	v_mfma_f32_16x16x32_bf16 v[64:67], v[184:187], v[220:223], v[64:67]
	s_barrier
; #define PG8_STAGE(bufoff, gbase, voff) do { _Pragma("unroll") for (int _i = 0; _i < 2; ++_i) \
;         __builtin_amdgcn_global_load_lds((const unsigned*)((const char*)(gbase) + (voff)[_i]), (PG8_LAS unsigned*)(lds + (bufoff) + ldsw + _i * 8192), 16, 0, 0); } while (0)
; #define PG8_LDA(dst, b, h) do { _Pragma("unroll") for (int m = 0; m < 4; ++m) _Pragma("unroll") for (int k = 0; k < 2; ++k) dst[m][k] = *(const PG8_LAS bf16x8*)(lds + PG8_SA(b, h) + aoff + m * 2048 + k * 1024); } while (0)
; #define PG8_MMA(ai, bj, At, Bt) do { __builtin_amdgcn_s_setprio(1); _Pragma("unroll") for (int m = 0; m < 4; ++m) _Pragma("unroll") for (int n = 0; n < 2; ++n) _Pragma("unroll") for (int k = 0; k < 2; ++k) \
;         acc[ai][bj][m][n] = __builtin_amdgcn_mfma_f32_16x16x32_bf16(Bt[n][k], At[m][k], acc[ai][bj][m][n], 0, 0, 0); __builtin_amdgcn_s_setprio(0); } while (0)
; #define PG8_WAIT_V(n) asm volatile("s_waitcnt vmcnt(" #n ")" ::: "memory")
; #define PG8_WAIT_L(n) asm volatile("s_waitcnt lgkmcnt(" #n ")" ::: "memory")
; #define PG8_BAR __builtin_amdgcn_s_barrier()
; #define PG8_SCHED __builtin_amdgcn_sched_barrier(0)
; template <class Epi, class Sched, bool ALIGN_EPI = false, bool SP2 = false>
; __device__ __forceinline__ void gemm_phase(PG8_LAS unsigned char* lds, const Gemm g, const Sched& S, const Epi& E, const int tid) {
;     ...
;             PG8_LDA(At, 1, 1); PG8_STAGE(PG8_SB(1, 0), b3, voffB); PG8_STAGE(PG8_SB(1, 1), b3 + hstep, voffB); PG8_STAGE(PG8_SA(1, 0), a3, voffA);
;             PG8_WAIT_V(8); PG8_WAIT_L(0); PG8_BAR; PG8_MMA(1, 0, At, B0); PG8_MMA(1, 1, At, B1); PG8_BAR; PG8_SCHED;
	s_mov_b32 m0, s48
	v_lshl_add_u64 v[164:165], v[164:165], 0, s[18:19]
	s_add_u32 s26, s30, 0xb0080
	ds_read_b128 v[188:191], v170 offset:49152
	ds_read_b128 v[192:195], v170 offset:50176
	ds_read_b128 v[200:203], v170 offset:51200
	ds_read_b128 v[204:207], v170 offset:52224
	ds_read_b128 v[208:211], v170 offset:53248
	ds_read_b128 v[212:215], v170 offset:54272
	ds_read_b128 v[216:219], v170 offset:55296
	ds_read_b128 v[220:223], v170 offset:56320
	global_load_lds_dwordx4 v[164:165], off
	v_lshl_add_u64 v[164:165], v[196:197], 0, s[18:19]
	s_mov_b32 m0, s49
	s_addc_u32 s27, s31, 0
	global_load_lds_dwordx4 v[164:165], off
	v_lshl_add_u64 v[164:165], s[26:27], 0, v[146:147]
	s_mov_b32 m0, s52
	s_nop 0
	global_load_lds_dwordx4 v[164:165], off
	v_lshl_add_u64 v[164:165], s[26:27], 0, v[150:151]
	s_mov_b32 m0, s53
	s_nop 0
	global_load_lds_dwordx4 v[164:165], off
	v_lshl_add_u64 v[164:165], v[224:225], 0, s[18:19]
	s_mov_b32 m0, s50
	s_nop 0
	global_load_lds_dwordx4 v[164:165], off
	v_lshl_add_u64 v[164:165], v[226:227], 0, s[18:19]
	s_mov_b32 m0, s51
	s_nop 0
	global_load_lds_dwordx4 v[164:165], off
	s_waitcnt vmcnt(8)
	s_waitcnt lgkmcnt(0)
	s_barrier
	s_waitcnt lgkmcnt(0)
	v_mfma_f32_16x16x32_bf16 v[60:63], v[80:83], v[188:191], v[60:63]
	v_mfma_f32_16x16x32_bf16 v[56:59], v[88:91], v[188:191], v[56:59]
	v_mfma_f32_16x16x32_bf16 v[44:47], v[80:83], v[200:203], v[44:47]
	v_mfma_f32_16x16x32_bf16 v[40:43], v[88:91], v[200:203], v[40:43]
	v_mfma_f32_16x16x32_bf16 v[28:31], v[80:83], v[208:211], v[28:31]
	v_mfma_f32_16x16x32_bf16 v[24:27], v[88:91], v[208:211], v[24:27]
	v_mfma_f32_16x16x32_bf16 v[12:15], v[80:83], v[216:219], v[12:15]
	v_mfma_f32_16x16x32_bf16 v[8:11], v[88:91], v[216:219], v[8:11]
	v_mfma_f32_16x16x32_bf16 v[60:63], v[84:87], v[192:195], v[60:63]
	v_mfma_f32_16x16x32_bf16 v[56:59], v[92:95], v[192:195], v[56:59]
	v_mfma_f32_16x16x32_bf16 v[44:47], v[84:87], v[204:207], v[44:47]
	v_mfma_f32_16x16x32_bf16 v[40:43], v[92:95], v[204:207], v[40:43]
	v_mfma_f32_16x16x32_bf16 v[28:31], v[84:87], v[212:215], v[28:31]
	v_mfma_f32_16x16x32_bf16 v[24:27], v[92:95], v[212:215], v[24:27]
	v_mfma_f32_16x16x32_bf16 v[12:15], v[84:87], v[220:223], v[12:15]
	v_mfma_f32_16x16x32_bf16 v[8:11], v[92:95], v[220:223], v[8:11]
	v_mfma_f32_16x16x32_bf16 v[52:55], v[160:163], v[188:191], v[52:55]
	v_mfma_f32_16x16x32_bf16 v[48:51], v[180:183], v[188:191], v[48:51]
	v_mfma_f32_16x16x32_bf16 v[36:39], v[160:163], v[200:203], v[36:39]
	v_mfma_f32_16x16x32_bf16 v[32:35], v[180:183], v[200:203], v[32:35]
	v_mfma_f32_16x16x32_bf16 v[20:23], v[160:163], v[208:211], v[20:23]
	v_mfma_f32_16x16x32_bf16 v[16:19], v[180:183], v[208:211], v[16:19]
	v_mfma_f32_16x16x32_bf16 v[4:7], v[160:163], v[216:219], v[4:7]
	v_mfma_f32_16x16x32_bf16 v[0:3], v[180:183], v[216:219], v[0:3]
	v_mfma_f32_16x16x32_bf16 v[52:55], v[176:179], v[192:195], v[52:55]
	v_mfma_f32_16x16x32_bf16 v[48:51], v[184:187], v[192:195], v[48:51]
	v_mfma_f32_16x16x32_bf16 v[36:39], v[176:179], v[204:207], v[36:39]
	v_mfma_f32_16x16x32_bf16 v[32:35], v[184:187], v[204:207], v[32:35]
	v_mfma_f32_16x16x32_bf16 v[20:23], v[176:179], v[212:215], v[20:23]
	v_mfma_f32_16x16x32_bf16 v[16:19], v[184:187], v[212:215], v[16:19]
	v_mfma_f32_16x16x32_bf16 v[4:7], v[176:179], v[220:223], v[4:7]
	v_mfma_f32_16x16x32_bf16 v[0:3], v[184:187], v[220:223], v[0:3]
	s_barrier
	s_add_i32 s63, s63, 2
	s_add_u32 s61, s61, 0x100
	s_addc_u32 s62, s62, 0
	s_cmp_gt_u32 s63, 41
	s_mov_b64 s[26:27], s[28:29]
	s_cbranch_scc0 .LBB0_1081
	s_and_b64 vcc, exec, s[20:21]
	s_cbranch_vccnz .LBB0_1085
	s_andn2_b64 vcc, exec, s[22:23]
	s_cbranch_vccz .LBB0_1086
